# GEMM k-step: MFMA order snakes through the 8x4 fragment grid so consecutive MFMAs always share one operand
# speedup vs baseline: 1.0242x; 1.0031x over previous
.Lgy_nn_a:
	s_waitcnt lgkmcnt(0)
	v_add_u32_e32 v240, s61, v238
	v_add_u32_e32 v241, s61, v239
	s_setprio 1
	v_mfma_f32_16x16x32_bf16 v[2:5], v[162:165], v[130:133], 0
	v_mfma_f32_16x16x32_bf16 v[6:9], v[166:169], v[130:133], 0
	v_mfma_f32_16x16x32_bf16 v[10:13], v[170:173], v[130:133], 0
	v_mfma_f32_16x16x32_bf16 v[14:17], v[174:177], v[130:133], 0
	s_waitcnt vmcnt(6)
	s_barrier
	v_mfma_f32_16x16x32_bf16 v[30:33], v[174:177], v[134:137], 0
	s_add_i32 m0, s60, s62
	v_mfma_f32_16x16x32_bf16 v[26:29], v[170:173], v[134:137], 0
	global_load_lds_dwordx4 v226, s[54:55]
	v_mfma_f32_16x16x32_bf16 v[22:25], v[166:169], v[134:137], 0
	v_mfma_f32_16x16x32_bf16 v[18:21], v[162:165], v[134:137], 0
	v_mfma_f32_16x16x32_bf16 v[34:37], v[162:165], v[138:141], 0
	ds_read_b128 v[210:213], v241 offset:0
	v_mfma_f32_16x16x32_bf16 v[38:41], v[166:169], v[138:141], 0
	ds_read_b128 v[214:217], v241 offset:256
	v_mfma_f32_16x16x32_bf16 v[42:45], v[170:173], v[138:141], 0
	ds_read_b128 v[218:221], v241 offset:512
	global_load_lds_dwordx4 v226, s[54:55] offset:1024
	v_mfma_f32_16x16x32_bf16 v[46:49], v[174:177], v[138:141], 0
	ds_read_b128 v[222:225], v241 offset:768
	v_mfma_f32_16x16x32_bf16 v[62:65], v[174:177], v[142:145], 0
	ds_read_b128 v[178:181], v240 offset:0
	v_mfma_f32_16x16x32_bf16 v[58:61], v[170:173], v[142:145], 0
	ds_read_b128 v[182:185], v240 offset:1024
	v_mfma_f32_16x16x32_bf16 v[54:57], v[166:169], v[142:145], 0
	ds_read_b128 v[186:189], v240 offset:2048
	v_mfma_f32_16x16x32_bf16 v[50:53], v[162:165], v[142:145], 0
	ds_read_b128 v[190:193], v240 offset:3072
	global_load_lds_dwordx4 v226, s[54:55] offset:2048
	v_mfma_f32_16x16x32_bf16 v[66:69], v[162:165], v[146:149], 0
	ds_read_b128 v[194:197], v240 offset:4096
	v_mfma_f32_16x16x32_bf16 v[70:73], v[166:169], v[146:149], 0
	ds_read_b128 v[198:201], v240 offset:5120
	v_mfma_f32_16x16x32_bf16 v[74:77], v[170:173], v[146:149], 0
	ds_read_b128 v[202:205], v240 offset:6144
	v_mfma_f32_16x16x32_bf16 v[78:81], v[174:177], v[146:149], 0
	ds_read_b128 v[206:209], v240 offset:7168
	v_mfma_f32_16x16x32_bf16 v[94:97], v[174:177], v[150:153], 0
	global_load_lds_dwordx4 v226, s[54:55] offset:3072
	v_mfma_f32_16x16x32_bf16 v[90:93], v[170:173], v[150:153], 0
	v_mfma_f32_16x16x32_bf16 v[86:89], v[166:169], v[150:153], 0
	v_mfma_f32_16x16x32_bf16 v[82:85], v[162:165], v[150:153], 0
	v_mfma_f32_16x16x32_bf16 v[98:101], v[162:165], v[154:157], 0
	s_add_i32 m0, s60, s63
	v_mfma_f32_16x16x32_bf16 v[102:105], v[166:169], v[154:157], 0
	global_load_lds_dwordx4 v230, s[56:57]
	v_mfma_f32_16x16x32_bf16 v[106:109], v[170:173], v[154:157], 0
	v_mfma_f32_16x16x32_bf16 v[110:113], v[174:177], v[154:157], 0
	v_mfma_f32_16x16x32_bf16 v[126:129], v[174:177], v[158:161], 0
	v_mfma_f32_16x16x32_bf16 v[122:125], v[170:173], v[158:161], 0
	v_mfma_f32_16x16x32_bf16 v[118:121], v[166:169], v[158:161], 0
	global_load_lds_dwordx4 v231, s[56:57] offset:1024
	v_mfma_f32_16x16x32_bf16 v[114:117], v[162:165], v[158:161], 0
	s_setprio 0
	s_add_i32 s60, s60, 0x6000
	s_cmp_eq_u32 s60, 0x12000
	s_cselect_b32 s60, 0, s60
	s_add_u32 s54, s54, s72
	s_addc_u32 s55, s55, 0
	s_add_u32 s56, s56, s73
	s_addc_u32 s57, s57, 0
	s_add_i32 s61, s61, 0x6000
	s_cmp_eq_u32 s61, 0x12000
	s_cselect_b32 s61, 0, s61
	s_waitcnt lgkmcnt(0)
	v_add_u32_e32 v240, s61, v238
	v_add_u32_e32 v241, s61, v239
	s_setprio 1
	v_mfma_f32_16x16x32_bf16 v[2:5], v[210:213], v[178:181], v[2:5]
	v_mfma_f32_16x16x32_bf16 v[6:9], v[214:217], v[178:181], v[6:9]
	v_mfma_f32_16x16x32_bf16 v[10:13], v[218:221], v[178:181], v[10:13]
	v_mfma_f32_16x16x32_bf16 v[14:17], v[222:225], v[178:181], v[14:17]
	s_waitcnt vmcnt(6)
	s_barrier
	v_mfma_f32_16x16x32_bf16 v[30:33], v[222:225], v[182:185], v[30:33]
	s_add_i32 m0, s60, s62
	v_mfma_f32_16x16x32_bf16 v[26:29], v[218:221], v[182:185], v[26:29]
	global_load_lds_dwordx4 v226, s[54:55]
	v_mfma_f32_16x16x32_bf16 v[22:25], v[214:217], v[182:185], v[22:25]
	v_mfma_f32_16x16x32_bf16 v[18:21], v[210:213], v[182:185], v[18:21]
	v_mfma_f32_16x16x32_bf16 v[34:37], v[210:213], v[186:189], v[34:37]
	ds_read_b128 v[162:165], v241 offset:0
	v_mfma_f32_16x16x32_bf16 v[38:41], v[214:217], v[186:189], v[38:41]
	ds_read_b128 v[166:169], v241 offset:256
	v_mfma_f32_16x16x32_bf16 v[42:45], v[218:221], v[186:189], v[42:45]
	ds_read_b128 v[170:173], v241 offset:512
	global_load_lds_dwordx4 v226, s[54:55] offset:1024
	v_mfma_f32_16x16x32_bf16 v[46:49], v[222:225], v[186:189], v[46:49]
	ds_read_b128 v[174:177], v241 offset:768
	v_mfma_f32_16x16x32_bf16 v[62:65], v[222:225], v[190:193], v[62:65]
	ds_read_b128 v[130:133], v240 offset:0
	v_mfma_f32_16x16x32_bf16 v[58:61], v[218:221], v[190:193], v[58:61]
	ds_read_b128 v[134:137], v240 offset:1024
	v_mfma_f32_16x16x32_bf16 v[54:57], v[214:217], v[190:193], v[54:57]
	ds_read_b128 v[138:141], v240 offset:2048
	v_mfma_f32_16x16x32_bf16 v[50:53], v[210:213], v[190:193], v[50:53]
	ds_read_b128 v[142:145], v240 offset:3072
	global_load_lds_dwordx4 v226, s[54:55] offset:2048
	v_mfma_f32_16x16x32_bf16 v[66:69], v[210:213], v[194:197], v[66:69]
	ds_read_b128 v[146:149], v240 offset:4096
	v_mfma_f32_16x16x32_bf16 v[70:73], v[214:217], v[194:197], v[70:73]
	ds_read_b128 v[150:153], v240 offset:5120
	v_mfma_f32_16x16x32_bf16 v[74:77], v[218:221], v[194:197], v[74:77]
	ds_read_b128 v[154:157], v240 offset:6144
	v_mfma_f32_16x16x32_bf16 v[78:81], v[222:225], v[194:197], v[78:81]
	ds_read_b128 v[158:161], v240 offset:7168
	v_mfma_f32_16x16x32_bf16 v[94:97], v[222:225], v[198:201], v[94:97]
	global_load_lds_dwordx4 v226, s[54:55] offset:3072
	v_mfma_f32_16x16x32_bf16 v[90:93], v[218:221], v[198:201], v[90:93]
	v_mfma_f32_16x16x32_bf16 v[86:89], v[214:217], v[198:201], v[86:89]
	v_mfma_f32_16x16x32_bf16 v[82:85], v[210:213], v[198:201], v[82:85]
	v_mfma_f32_16x16x32_bf16 v[98:101], v[210:213], v[202:205], v[98:101]
	s_add_i32 m0, s60, s63
	v_mfma_f32_16x16x32_bf16 v[102:105], v[214:217], v[202:205], v[102:105]
	global_load_lds_dwordx4 v230, s[56:57]
	v_mfma_f32_16x16x32_bf16 v[106:109], v[218:221], v[202:205], v[106:109]
	v_mfma_f32_16x16x32_bf16 v[110:113], v[222:225], v[202:205], v[110:113]
	v_mfma_f32_16x16x32_bf16 v[126:129], v[222:225], v[206:209], v[126:129]
	v_mfma_f32_16x16x32_bf16 v[122:125], v[218:221], v[206:209], v[122:125]
	v_mfma_f32_16x16x32_bf16 v[118:121], v[214:217], v[206:209], v[118:121]
	global_load_lds_dwordx4 v231, s[56:57] offset:1024
	v_mfma_f32_16x16x32_bf16 v[114:117], v[210:213], v[206:209], v[114:117]
	s_setprio 0
	s_add_i32 s60, s60, 0x6000
	s_cmp_eq_u32 s60, 0x12000
	s_cselect_b32 s60, 0, s60
	s_add_u32 s54, s54, s72
	s_addc_u32 s55, s55, 0
	s_add_u32 s56, s56, s73
	s_addc_u32 s57, s57, 0
	s_add_i32 s61, s61, 0x6000
	s_cmp_eq_u32 s61, 0x12000
	s_cselect_b32 s61, 0, s61
	s_branch .Lgy_main

.Lgy_nn_b:
	s_waitcnt lgkmcnt(0)
	v_add_u32_e32 v240, s61, v238
	v_add_u32_e32 v241, s61, v239
	s_setprio 1
	v_mfma_f32_16x16x32_bf16 v[2:5], v[162:165], v[130:133], 0
	v_mfma_f32_16x16x32_bf16 v[6:9], v[166:169], v[130:133], 0
	v_mfma_f32_16x16x32_bf16 v[10:13], v[170:173], v[130:133], 0
	v_mfma_f32_16x16x32_bf16 v[14:17], v[174:177], v[130:133], 0
	s_waitcnt vmcnt(22)
	s_barrier
	v_mfma_f32_16x16x32_bf16 v[30:33], v[174:177], v[134:137], 0
	s_add_i32 m0, s60, s62
	v_mfma_f32_16x16x32_bf16 v[26:29], v[170:173], v[134:137], 0
	global_load_lds_dwordx4 v226, s[54:55]
	v_mfma_f32_16x16x32_bf16 v[22:25], v[166:169], v[134:137], 0
	v_mfma_f32_16x16x32_bf16 v[18:21], v[162:165], v[134:137], 0
	v_mfma_f32_16x16x32_bf16 v[34:37], v[162:165], v[138:141], 0
	ds_read_b128 v[210:213], v241 offset:0
	v_mfma_f32_16x16x32_bf16 v[38:41], v[166:169], v[138:141], 0
	ds_read_b128 v[214:217], v241 offset:256
	v_mfma_f32_16x16x32_bf16 v[42:45], v[170:173], v[138:141], 0
	ds_read_b128 v[218:221], v241 offset:512
	global_load_lds_dwordx4 v226, s[54:55] offset:1024
	v_mfma_f32_16x16x32_bf16 v[46:49], v[174:177], v[138:141], 0
	ds_read_b128 v[222:225], v241 offset:768
	v_mfma_f32_16x16x32_bf16 v[62:65], v[174:177], v[142:145], 0
	ds_read_b128 v[178:181], v240 offset:0
	v_mfma_f32_16x16x32_bf16 v[58:61], v[170:173], v[142:145], 0
	ds_read_b128 v[182:185], v240 offset:1024
	v_mfma_f32_16x16x32_bf16 v[54:57], v[166:169], v[142:145], 0
	ds_read_b128 v[186:189], v240 offset:2048
	v_mfma_f32_16x16x32_bf16 v[50:53], v[162:165], v[142:145], 0
	ds_read_b128 v[190:193], v240 offset:3072
	global_load_lds_dwordx4 v226, s[54:55] offset:2048
	v_mfma_f32_16x16x32_bf16 v[66:69], v[162:165], v[146:149], 0
	ds_read_b128 v[194:197], v240 offset:4096
	v_mfma_f32_16x16x32_bf16 v[70:73], v[166:169], v[146:149], 0
	ds_read_b128 v[198:201], v240 offset:5120
	v_mfma_f32_16x16x32_bf16 v[74:77], v[170:173], v[146:149], 0
	ds_read_b128 v[202:205], v240 offset:6144
	v_mfma_f32_16x16x32_bf16 v[78:81], v[174:177], v[146:149], 0
	ds_read_b128 v[206:209], v240 offset:7168
	v_mfma_f32_16x16x32_bf16 v[94:97], v[174:177], v[150:153], 0
	global_load_lds_dwordx4 v226, s[54:55] offset:3072
	v_mfma_f32_16x16x32_bf16 v[90:93], v[170:173], v[150:153], 0
	v_mfma_f32_16x16x32_bf16 v[86:89], v[166:169], v[150:153], 0
	v_mfma_f32_16x16x32_bf16 v[82:85], v[162:165], v[150:153], 0
	v_mfma_f32_16x16x32_bf16 v[98:101], v[162:165], v[154:157], 0
	s_add_i32 m0, s60, s63
	v_mfma_f32_16x16x32_bf16 v[102:105], v[166:169], v[154:157], 0
	global_load_lds_dwordx4 v230, s[56:57]
	v_mfma_f32_16x16x32_bf16 v[106:109], v[170:173], v[154:157], 0
	v_mfma_f32_16x16x32_bf16 v[110:113], v[174:177], v[154:157], 0
	v_mfma_f32_16x16x32_bf16 v[126:129], v[174:177], v[158:161], 0
	v_mfma_f32_16x16x32_bf16 v[122:125], v[170:173], v[158:161], 0
	v_mfma_f32_16x16x32_bf16 v[118:121], v[166:169], v[158:161], 0
	global_load_lds_dwordx4 v231, s[56:57] offset:1024
	v_mfma_f32_16x16x32_bf16 v[114:117], v[162:165], v[158:161], 0
	s_setprio 0
	s_add_i32 s60, s60, 0x6000
	s_cmp_eq_u32 s60, 0x12000
	s_cselect_b32 s60, 0, s60
	s_add_u32 s54, s54, s72
	s_addc_u32 s55, s55, 0
	s_add_u32 s56, s56, s73
	s_addc_u32 s57, s57, 0
	s_add_i32 s61, s61, 0x6000
	s_cmp_eq_u32 s61, 0x12000
	s_cselect_b32 s61, 0, s61
	s_waitcnt lgkmcnt(0)
	v_add_u32_e32 v240, s61, v238
	v_add_u32_e32 v241, s61, v239
	s_setprio 1
	v_mfma_f32_16x16x32_bf16 v[2:5], v[210:213], v[178:181], v[2:5]
	v_mfma_f32_16x16x32_bf16 v[6:9], v[214:217], v[178:181], v[6:9]
	v_mfma_f32_16x16x32_bf16 v[10:13], v[218:221], v[178:181], v[10:13]
	v_mfma_f32_16x16x32_bf16 v[14:17], v[222:225], v[178:181], v[14:17]
	s_waitcnt vmcnt(22)
	s_barrier
	v_mfma_f32_16x16x32_bf16 v[30:33], v[222:225], v[182:185], v[30:33]
	s_add_i32 m0, s60, s62
	v_mfma_f32_16x16x32_bf16 v[26:29], v[218:221], v[182:185], v[26:29]
	global_load_lds_dwordx4 v226, s[54:55]
	v_mfma_f32_16x16x32_bf16 v[22:25], v[214:217], v[182:185], v[22:25]
	v_mfma_f32_16x16x32_bf16 v[18:21], v[210:213], v[182:185], v[18:21]
	v_mfma_f32_16x16x32_bf16 v[34:37], v[210:213], v[186:189], v[34:37]
	ds_read_b128 v[162:165], v241 offset:0
	v_mfma_f32_16x16x32_bf16 v[38:41], v[214:217], v[186:189], v[38:41]
	ds_read_b128 v[166:169], v241 offset:256
	v_mfma_f32_16x16x32_bf16 v[42:45], v[218:221], v[186:189], v[42:45]
	ds_read_b128 v[170:173], v241 offset:512
	global_load_lds_dwordx4 v226, s[54:55] offset:1024
	v_mfma_f32_16x16x32_bf16 v[46:49], v[222:225], v[186:189], v[46:49]
	ds_read_b128 v[174:177], v241 offset:768
	v_mfma_f32_16x16x32_bf16 v[62:65], v[222:225], v[190:193], v[62:65]
	ds_read_b128 v[130:133], v240 offset:0
	v_mfma_f32_16x16x32_bf16 v[58:61], v[218:221], v[190:193], v[58:61]
	ds_read_b128 v[134:137], v240 offset:1024
	v_mfma_f32_16x16x32_bf16 v[54:57], v[214:217], v[190:193], v[54:57]
	ds_read_b128 v[138:141], v240 offset:2048
	v_mfma_f32_16x16x32_bf16 v[50:53], v[210:213], v[190:193], v[50:53]
	ds_read_b128 v[142:145], v240 offset:3072
	global_load_lds_dwordx4 v226, s[54:55] offset:2048
	v_mfma_f32_16x16x32_bf16 v[66:69], v[210:213], v[194:197], v[66:69]
	ds_read_b128 v[146:149], v240 offset:4096
	v_mfma_f32_16x16x32_bf16 v[70:73], v[214:217], v[194:197], v[70:73]
	ds_read_b128 v[150:153], v240 offset:5120
	v_mfma_f32_16x16x32_bf16 v[74:77], v[218:221], v[194:197], v[74:77]
	ds_read_b128 v[154:157], v240 offset:6144
	v_mfma_f32_16x16x32_bf16 v[78:81], v[222:225], v[194:197], v[78:81]
	ds_read_b128 v[158:161], v240 offset:7168
	v_mfma_f32_16x16x32_bf16 v[94:97], v[222:225], v[198:201], v[94:97]
	global_load_lds_dwordx4 v226, s[54:55] offset:3072
	v_mfma_f32_16x16x32_bf16 v[90:93], v[218:221], v[198:201], v[90:93]
	v_mfma_f32_16x16x32_bf16 v[86:89], v[214:217], v[198:201], v[86:89]
	v_mfma_f32_16x16x32_bf16 v[82:85], v[210:213], v[198:201], v[82:85]
	v_mfma_f32_16x16x32_bf16 v[98:101], v[210:213], v[202:205], v[98:101]
	s_add_i32 m0, s60, s63
	v_mfma_f32_16x16x32_bf16 v[102:105], v[214:217], v[202:205], v[102:105]
	global_load_lds_dwordx4 v230, s[56:57]
	v_mfma_f32_16x16x32_bf16 v[106:109], v[218:221], v[202:205], v[106:109]
	v_mfma_f32_16x16x32_bf16 v[110:113], v[222:225], v[202:205], v[110:113]
	v_mfma_f32_16x16x32_bf16 v[126:129], v[222:225], v[206:209], v[126:129]
	v_mfma_f32_16x16x32_bf16 v[122:125], v[218:221], v[206:209], v[122:125]
	v_mfma_f32_16x16x32_bf16 v[118:121], v[214:217], v[206:209], v[118:121]
	global_load_lds_dwordx4 v231, s[56:57] offset:1024
	v_mfma_f32_16x16x32_bf16 v[114:117], v[210:213], v[206:209], v[114:117]
	s_setprio 0
	s_add_i32 s60, s60, 0x6000
	s_cmp_eq_u32 s60, 0x12000
	s_cselect_b32 s60, 0, s60
	s_add_u32 s54, s54, s72
	s_addc_u32 s55, s55, 0
	s_add_u32 s56, s56, s73
	s_addc_u32 s57, s57, 0
	s_add_i32 s61, s61, 0x6000
	s_cmp_eq_u32 s61, 0x12000
	s_cselect_b32 s61, 0, s61

.Lgy_kloop:
	s_waitcnt lgkmcnt(0)
	v_add_u32_e32 v240, s61, v238
	v_add_u32_e32 v241, s61, v239
	s_setprio 1
	v_mfma_f32_16x16x32_bf16 v[2:5], v[162:165], v[130:133], v[2:5]
	v_mfma_f32_16x16x32_bf16 v[6:9], v[166:169], v[130:133], v[6:9]
	v_mfma_f32_16x16x32_bf16 v[10:13], v[170:173], v[130:133], v[10:13]
	v_mfma_f32_16x16x32_bf16 v[14:17], v[174:177], v[130:133], v[14:17]
	s_waitcnt vmcnt(6)
	s_barrier
	v_mfma_f32_16x16x32_bf16 v[30:33], v[174:177], v[134:137], v[30:33]
	s_add_i32 m0, s60, s62
	v_mfma_f32_16x16x32_bf16 v[26:29], v[170:173], v[134:137], v[26:29]
	global_load_lds_dwordx4 v226, s[54:55]
	v_mfma_f32_16x16x32_bf16 v[22:25], v[166:169], v[134:137], v[22:25]
	v_mfma_f32_16x16x32_bf16 v[18:21], v[162:165], v[134:137], v[18:21]
	v_mfma_f32_16x16x32_bf16 v[34:37], v[162:165], v[138:141], v[34:37]
	ds_read_b128 v[210:213], v241 offset:0
	v_mfma_f32_16x16x32_bf16 v[38:41], v[166:169], v[138:141], v[38:41]
	ds_read_b128 v[214:217], v241 offset:256
	v_mfma_f32_16x16x32_bf16 v[42:45], v[170:173], v[138:141], v[42:45]
	ds_read_b128 v[218:221], v241 offset:512
	global_load_lds_dwordx4 v226, s[54:55] offset:1024
	v_mfma_f32_16x16x32_bf16 v[46:49], v[174:177], v[138:141], v[46:49]
	ds_read_b128 v[222:225], v241 offset:768
	v_mfma_f32_16x16x32_bf16 v[62:65], v[174:177], v[142:145], v[62:65]
	ds_read_b128 v[178:181], v240 offset:0
	v_mfma_f32_16x16x32_bf16 v[58:61], v[170:173], v[142:145], v[58:61]
	ds_read_b128 v[182:185], v240 offset:1024
	v_mfma_f32_16x16x32_bf16 v[54:57], v[166:169], v[142:145], v[54:57]
	ds_read_b128 v[186:189], v240 offset:2048
	v_mfma_f32_16x16x32_bf16 v[50:53], v[162:165], v[142:145], v[50:53]
	ds_read_b128 v[190:193], v240 offset:3072
	global_load_lds_dwordx4 v226, s[54:55] offset:2048
	v_mfma_f32_16x16x32_bf16 v[66:69], v[162:165], v[146:149], v[66:69]
	ds_read_b128 v[194:197], v240 offset:4096
	v_mfma_f32_16x16x32_bf16 v[70:73], v[166:169], v[146:149], v[70:73]
	ds_read_b128 v[198:201], v240 offset:5120
	v_mfma_f32_16x16x32_bf16 v[74:77], v[170:173], v[146:149], v[74:77]
	ds_read_b128 v[202:205], v240 offset:6144
	v_mfma_f32_16x16x32_bf16 v[78:81], v[174:177], v[146:149], v[78:81]
	ds_read_b128 v[206:209], v240 offset:7168
	v_mfma_f32_16x16x32_bf16 v[94:97], v[174:177], v[150:153], v[94:97]
	global_load_lds_dwordx4 v226, s[54:55] offset:3072
	v_mfma_f32_16x16x32_bf16 v[90:93], v[170:173], v[150:153], v[90:93]
	v_mfma_f32_16x16x32_bf16 v[86:89], v[166:169], v[150:153], v[86:89]
	v_mfma_f32_16x16x32_bf16 v[82:85], v[162:165], v[150:153], v[82:85]
	v_mfma_f32_16x16x32_bf16 v[98:101], v[162:165], v[154:157], v[98:101]
	s_add_i32 m0, s60, s63
	v_mfma_f32_16x16x32_bf16 v[102:105], v[166:169], v[154:157], v[102:105]
	global_load_lds_dwordx4 v230, s[56:57]
	v_mfma_f32_16x16x32_bf16 v[106:109], v[170:173], v[154:157], v[106:109]
	v_mfma_f32_16x16x32_bf16 v[110:113], v[174:177], v[154:157], v[110:113]
	v_mfma_f32_16x16x32_bf16 v[126:129], v[174:177], v[158:161], v[126:129]
	v_mfma_f32_16x16x32_bf16 v[122:125], v[170:173], v[158:161], v[122:125]
	v_mfma_f32_16x16x32_bf16 v[118:121], v[166:169], v[158:161], v[118:121]
	global_load_lds_dwordx4 v231, s[56:57] offset:1024
	v_mfma_f32_16x16x32_bf16 v[114:117], v[162:165], v[158:161], v[114:117]
	s_setprio 0
	s_add_i32 s60, s60, 0x6000
	s_cmp_eq_u32 s60, 0x12000
	s_cselect_b32 s60, 0, s60
	s_add_u32 s54, s54, s72
	s_addc_u32 s55, s55, 0
	s_add_u32 s56, s56, s73
	s_addc_u32 s57, s57, 0
	s_add_i32 s61, s61, 0x6000
	s_cmp_eq_u32 s61, 0x12000
	s_cselect_b32 s61, 0, s61
	s_waitcnt lgkmcnt(0)
	v_add_u32_e32 v240, s61, v238
	v_add_u32_e32 v241, s61, v239
	s_setprio 1
	v_mfma_f32_16x16x32_bf16 v[2:5], v[210:213], v[178:181], v[2:5]
	v_mfma_f32_16x16x32_bf16 v[6:9], v[214:217], v[178:181], v[6:9]
	v_mfma_f32_16x16x32_bf16 v[10:13], v[218:221], v[178:181], v[10:13]
	v_mfma_f32_16x16x32_bf16 v[14:17], v[222:225], v[178:181], v[14:17]
	s_waitcnt vmcnt(6)
	s_barrier
	v_mfma_f32_16x16x32_bf16 v[30:33], v[222:225], v[182:185], v[30:33]
	s_add_i32 m0, s60, s62
	v_mfma_f32_16x16x32_bf16 v[26:29], v[218:221], v[182:185], v[26:29]
	global_load_lds_dwordx4 v226, s[54:55]
	v_mfma_f32_16x16x32_bf16 v[22:25], v[214:217], v[182:185], v[22:25]
	v_mfma_f32_16x16x32_bf16 v[18:21], v[210:213], v[182:185], v[18:21]
	v_mfma_f32_16x16x32_bf16 v[34:37], v[210:213], v[186:189], v[34:37]
	ds_read_b128 v[162:165], v241 offset:0
	v_mfma_f32_16x16x32_bf16 v[38:41], v[214:217], v[186:189], v[38:41]
	ds_read_b128 v[166:169], v241 offset:256
	v_mfma_f32_16x16x32_bf16 v[42:45], v[218:221], v[186:189], v[42:45]
	ds_read_b128 v[170:173], v241 offset:512
	global_load_lds_dwordx4 v226, s[54:55] offset:1024
	v_mfma_f32_16x16x32_bf16 v[46:49], v[222:225], v[186:189], v[46:49]
	ds_read_b128 v[174:177], v241 offset:768
	v_mfma_f32_16x16x32_bf16 v[62:65], v[222:225], v[190:193], v[62:65]
	ds_read_b128 v[130:133], v240 offset:0
	v_mfma_f32_16x16x32_bf16 v[58:61], v[218:221], v[190:193], v[58:61]
	ds_read_b128 v[134:137], v240 offset:1024
	v_mfma_f32_16x16x32_bf16 v[54:57], v[214:217], v[190:193], v[54:57]
	ds_read_b128 v[138:141], v240 offset:2048
	v_mfma_f32_16x16x32_bf16 v[50:53], v[210:213], v[190:193], v[50:53]
	ds_read_b128 v[142:145], v240 offset:3072
	global_load_lds_dwordx4 v226, s[54:55] offset:2048
	v_mfma_f32_16x16x32_bf16 v[66:69], v[210:213], v[194:197], v[66:69]
	ds_read_b128 v[146:149], v240 offset:4096
	v_mfma_f32_16x16x32_bf16 v[70:73], v[214:217], v[194:197], v[70:73]
	ds_read_b128 v[150:153], v240 offset:5120
	v_mfma_f32_16x16x32_bf16 v[74:77], v[218:221], v[194:197], v[74:77]
	ds_read_b128 v[154:157], v240 offset:6144
	v_mfma_f32_16x16x32_bf16 v[78:81], v[222:225], v[194:197], v[78:81]
	ds_read_b128 v[158:161], v240 offset:7168
	v_mfma_f32_16x16x32_bf16 v[94:97], v[222:225], v[198:201], v[94:97]
	global_load_lds_dwordx4 v226, s[54:55] offset:3072
	v_mfma_f32_16x16x32_bf16 v[90:93], v[218:221], v[198:201], v[90:93]
	v_mfma_f32_16x16x32_bf16 v[86:89], v[214:217], v[198:201], v[86:89]
	v_mfma_f32_16x16x32_bf16 v[82:85], v[210:213], v[198:201], v[82:85]
	v_mfma_f32_16x16x32_bf16 v[98:101], v[210:213], v[202:205], v[98:101]
	s_add_i32 m0, s60, s63
	v_mfma_f32_16x16x32_bf16 v[102:105], v[214:217], v[202:205], v[102:105]
	global_load_lds_dwordx4 v230, s[56:57]
	v_mfma_f32_16x16x32_bf16 v[106:109], v[218:221], v[202:205], v[106:109]
	v_mfma_f32_16x16x32_bf16 v[110:113], v[222:225], v[202:205], v[110:113]
	v_mfma_f32_16x16x32_bf16 v[126:129], v[222:225], v[206:209], v[126:129]
	v_mfma_f32_16x16x32_bf16 v[122:125], v[218:221], v[206:209], v[122:125]
	v_mfma_f32_16x16x32_bf16 v[118:121], v[214:217], v[206:209], v[118:121]
	global_load_lds_dwordx4 v231, s[56:57] offset:1024
	v_mfma_f32_16x16x32_bf16 v[114:117], v[210:213], v[206:209], v[114:117]
	s_setprio 0
	s_add_i32 s60, s60, 0x6000
	s_cmp_eq_u32 s60, 0x12000
	s_cselect_b32 s60, 0, s60
	s_add_u32 s54, s54, s72
	s_addc_u32 s55, s55, 0
	s_add_u32 s56, s56, s73
	s_addc_u32 s57, s57, 0
	s_add_i32 s61, s61, 0x6000
	s_cmp_eq_u32 s61, 0x12000
	s_cselect_b32 s61, 0, s61
	s_add_i32 s40, s40, -1
	s_cmp_lg_u32 s40, 0
	s_cbranch_scc1 .Lgy_kloop
.Lgy_kdone:
	s_cmp_eq_u32 s37, 0
	s_cbranch_scc1 .Lgy_tail_last
	s_waitcnt lgkmcnt(0)
	v_add_u32_e32 v240, s61, v238
	v_add_u32_e32 v241, s61, v239
	s_setprio 1
	v_mfma_f32_16x16x32_bf16 v[2:5], v[162:165], v[130:133], v[2:5]
	v_mfma_f32_16x16x32_bf16 v[6:9], v[166:169], v[130:133], v[6:9]
	v_mfma_f32_16x16x32_bf16 v[10:13], v[170:173], v[130:133], v[10:13]
	v_mfma_f32_16x16x32_bf16 v[14:17], v[174:177], v[130:133], v[14:17]
	s_waitcnt vmcnt(6)
	s_barrier
	v_mfma_f32_16x16x32_bf16 v[30:33], v[174:177], v[134:137], v[30:33]
	s_add_i32 m0, s60, s62
	v_mfma_f32_16x16x32_bf16 v[26:29], v[170:173], v[134:137], v[26:29]
	global_load_lds_dwordx4 v226, s[54:55]
	v_mfma_f32_16x16x32_bf16 v[22:25], v[166:169], v[134:137], v[22:25]
	v_mfma_f32_16x16x32_bf16 v[18:21], v[162:165], v[134:137], v[18:21]
	v_mfma_f32_16x16x32_bf16 v[34:37], v[162:165], v[138:141], v[34:37]
	ds_read_b128 v[210:213], v241 offset:0
	v_mfma_f32_16x16x32_bf16 v[38:41], v[166:169], v[138:141], v[38:41]
	ds_read_b128 v[214:217], v241 offset:256
	v_mfma_f32_16x16x32_bf16 v[42:45], v[170:173], v[138:141], v[42:45]
	ds_read_b128 v[218:221], v241 offset:512
	global_load_lds_dwordx4 v226, s[54:55] offset:1024
	v_mfma_f32_16x16x32_bf16 v[46:49], v[174:177], v[138:141], v[46:49]
	ds_read_b128 v[222:225], v241 offset:768
	v_mfma_f32_16x16x32_bf16 v[62:65], v[174:177], v[142:145], v[62:65]
	ds_read_b128 v[178:181], v240 offset:0
	v_mfma_f32_16x16x32_bf16 v[58:61], v[170:173], v[142:145], v[58:61]
	ds_read_b128 v[182:185], v240 offset:1024
	v_mfma_f32_16x16x32_bf16 v[54:57], v[166:169], v[142:145], v[54:57]
	ds_read_b128 v[186:189], v240 offset:2048
	v_mfma_f32_16x16x32_bf16 v[50:53], v[162:165], v[142:145], v[50:53]
	ds_read_b128 v[190:193], v240 offset:3072
	global_load_lds_dwordx4 v226, s[54:55] offset:2048
	v_mfma_f32_16x16x32_bf16 v[66:69], v[162:165], v[146:149], v[66:69]
	ds_read_b128 v[194:197], v240 offset:4096
	v_mfma_f32_16x16x32_bf16 v[70:73], v[166:169], v[146:149], v[70:73]
	ds_read_b128 v[198:201], v240 offset:5120
	v_mfma_f32_16x16x32_bf16 v[74:77], v[170:173], v[146:149], v[74:77]
	ds_read_b128 v[202:205], v240 offset:6144
	v_mfma_f32_16x16x32_bf16 v[78:81], v[174:177], v[146:149], v[78:81]
	ds_read_b128 v[206:209], v240 offset:7168
	v_mfma_f32_16x16x32_bf16 v[94:97], v[174:177], v[150:153], v[94:97]
	global_load_lds_dwordx4 v226, s[54:55] offset:3072
	v_mfma_f32_16x16x32_bf16 v[90:93], v[170:173], v[150:153], v[90:93]
	v_mfma_f32_16x16x32_bf16 v[86:89], v[166:169], v[150:153], v[86:89]
	v_mfma_f32_16x16x32_bf16 v[82:85], v[162:165], v[150:153], v[82:85]
	v_mfma_f32_16x16x32_bf16 v[98:101], v[162:165], v[154:157], v[98:101]
	s_add_i32 m0, s60, s63
	v_mfma_f32_16x16x32_bf16 v[102:105], v[166:169], v[154:157], v[102:105]
	global_load_lds_dwordx4 v230, s[56:57]
	v_mfma_f32_16x16x32_bf16 v[106:109], v[170:173], v[154:157], v[106:109]
	v_mfma_f32_16x16x32_bf16 v[110:113], v[174:177], v[154:157], v[110:113]
	v_mfma_f32_16x16x32_bf16 v[126:129], v[174:177], v[158:161], v[126:129]
	v_mfma_f32_16x16x32_bf16 v[122:125], v[170:173], v[158:161], v[122:125]
	v_mfma_f32_16x16x32_bf16 v[118:121], v[166:169], v[158:161], v[118:121]
	global_load_lds_dwordx4 v231, s[56:57] offset:1024
	v_mfma_f32_16x16x32_bf16 v[114:117], v[162:165], v[158:161], v[114:117]
	s_setprio 0
	s_add_i32 s60, s60, 0x6000
	s_cmp_eq_u32 s60, 0x12000
	s_cselect_b32 s60, 0, s60
	s_add_u32 s54, s54, s72
	s_addc_u32 s55, s55, 0
	s_add_u32 s56, s56, s73
	s_addc_u32 s57, s57, 0
	s_add_i32 s61, s61, 0x6000
	s_cmp_eq_u32 s61, 0x12000
	s_cselect_b32 s61, 0, s61
	v_mov_b32_e32 v226, v232
	v_mov_b32_e32 v230, v236
	v_mov_b32_e32 v231, v237
	s_mov_b64 s[54:55], s[48:49]
	s_mov_b64 s[56:57], s[50:51]
	s_waitcnt lgkmcnt(0)
	v_add_u32_e32 v240, s61, v238
	v_add_u32_e32 v241, s61, v239
	s_setprio 1
	v_mfma_f32_16x16x32_bf16 v[2:5], v[210:213], v[178:181], v[2:5]
	v_mfma_f32_16x16x32_bf16 v[6:9], v[214:217], v[178:181], v[6:9]
	v_mfma_f32_16x16x32_bf16 v[10:13], v[218:221], v[178:181], v[10:13]
	v_mfma_f32_16x16x32_bf16 v[14:17], v[222:225], v[178:181], v[14:17]
	s_waitcnt vmcnt(6)
	s_barrier
	v_mfma_f32_16x16x32_bf16 v[30:33], v[222:225], v[182:185], v[30:33]
	s_add_i32 m0, s60, s62
	v_mfma_f32_16x16x32_bf16 v[26:29], v[218:221], v[182:185], v[26:29]
	global_load_lds_dwordx4 v226, s[54:55]
	v_mfma_f32_16x16x32_bf16 v[22:25], v[214:217], v[182:185], v[22:25]
	v_mfma_f32_16x16x32_bf16 v[18:21], v[210:213], v[182:185], v[18:21]
	v_mfma_f32_16x16x32_bf16 v[34:37], v[210:213], v[186:189], v[34:37]
	ds_read_b128 v[162:165], v241 offset:0
	v_mfma_f32_16x16x32_bf16 v[38:41], v[214:217], v[186:189], v[38:41]
	ds_read_b128 v[166:169], v241 offset:256
	v_mfma_f32_16x16x32_bf16 v[42:45], v[218:221], v[186:189], v[42:45]
	ds_read_b128 v[170:173], v241 offset:512
	global_load_lds_dwordx4 v226, s[54:55] offset:1024
	v_mfma_f32_16x16x32_bf16 v[46:49], v[222:225], v[186:189], v[46:49]
	ds_read_b128 v[174:177], v241 offset:768
	v_mfma_f32_16x16x32_bf16 v[62:65], v[222:225], v[190:193], v[62:65]
	ds_read_b128 v[130:133], v240 offset:0
	v_mfma_f32_16x16x32_bf16 v[58:61], v[218:221], v[190:193], v[58:61]
	ds_read_b128 v[134:137], v240 offset:1024
	v_mfma_f32_16x16x32_bf16 v[54:57], v[214:217], v[190:193], v[54:57]
	ds_read_b128 v[138:141], v240 offset:2048
	v_mfma_f32_16x16x32_bf16 v[50:53], v[210:213], v[190:193], v[50:53]
	ds_read_b128 v[142:145], v240 offset:3072
	global_load_lds_dwordx4 v226, s[54:55] offset:2048
	v_mfma_f32_16x16x32_bf16 v[66:69], v[210:213], v[194:197], v[66:69]
	ds_read_b128 v[146:149], v240 offset:4096
	v_mfma_f32_16x16x32_bf16 v[70:73], v[214:217], v[194:197], v[70:73]
	ds_read_b128 v[150:153], v240 offset:5120
	v_mfma_f32_16x16x32_bf16 v[74:77], v[218:221], v[194:197], v[74:77]
	ds_read_b128 v[154:157], v240 offset:6144
	v_mfma_f32_16x16x32_bf16 v[78:81], v[222:225], v[194:197], v[78:81]
	ds_read_b128 v[158:161], v240 offset:7168
	v_mfma_f32_16x16x32_bf16 v[94:97], v[222:225], v[198:201], v[94:97]
	global_load_lds_dwordx4 v226, s[54:55] offset:3072
	v_mfma_f32_16x16x32_bf16 v[90:93], v[218:221], v[198:201], v[90:93]
	v_mfma_f32_16x16x32_bf16 v[86:89], v[214:217], v[198:201], v[86:89]
	v_mfma_f32_16x16x32_bf16 v[82:85], v[210:213], v[198:201], v[82:85]
	v_mfma_f32_16x16x32_bf16 v[98:101], v[210:213], v[202:205], v[98:101]
	s_add_i32 m0, s60, s63
	v_mfma_f32_16x16x32_bf16 v[102:105], v[214:217], v[202:205], v[102:105]
	global_load_lds_dwordx4 v230, s[56:57]
	v_mfma_f32_16x16x32_bf16 v[106:109], v[218:221], v[202:205], v[106:109]
	v_mfma_f32_16x16x32_bf16 v[110:113], v[222:225], v[202:205], v[110:113]
	v_mfma_f32_16x16x32_bf16 v[126:129], v[222:225], v[206:209], v[126:129]
	v_mfma_f32_16x16x32_bf16 v[122:125], v[218:221], v[206:209], v[122:125]
	v_mfma_f32_16x16x32_bf16 v[118:121], v[214:217], v[206:209], v[118:121]
	global_load_lds_dwordx4 v231, s[56:57] offset:1024
	v_mfma_f32_16x16x32_bf16 v[114:117], v[210:213], v[206:209], v[114:117]
	s_setprio 0
	s_add_i32 s60, s60, 0x6000
	s_cmp_eq_u32 s60, 0x12000
	s_cselect_b32 s60, 0, s60
	s_add_u32 s54, s54, s72
	s_addc_u32 s55, s55, 0
	s_add_u32 s56, s56, s73
	s_addc_u32 s57, s57, 0
	s_add_i32 s61, s61, 0x6000
	s_cmp_eq_u32 s61, 0x12000
	s_cselect_b32 s61, 0, s61
	s_waitcnt lgkmcnt(0)
	v_add_u32_e32 v240, s61, v238
	v_add_u32_e32 v241, s61, v239
	s_setprio 1
	v_mfma_f32_16x16x32_bf16 v[2:5], v[162:165], v[130:133], v[2:5]
	v_mfma_f32_16x16x32_bf16 v[6:9], v[166:169], v[130:133], v[6:9]
	v_mfma_f32_16x16x32_bf16 v[10:13], v[170:173], v[130:133], v[10:13]
	v_mfma_f32_16x16x32_bf16 v[14:17], v[174:177], v[130:133], v[14:17]
	s_waitcnt vmcnt(6)
	s_barrier
	v_mfma_f32_16x16x32_bf16 v[30:33], v[174:177], v[134:137], v[30:33]
	s_add_i32 m0, s60, s62
	v_mfma_f32_16x16x32_bf16 v[26:29], v[170:173], v[134:137], v[26:29]
	global_load_lds_dwordx4 v226, s[54:55]
	v_mfma_f32_16x16x32_bf16 v[22:25], v[166:169], v[134:137], v[22:25]
	v_mfma_f32_16x16x32_bf16 v[18:21], v[162:165], v[134:137], v[18:21]
	v_mfma_f32_16x16x32_bf16 v[34:37], v[162:165], v[138:141], v[34:37]
	ds_read_b128 v[210:213], v241 offset:0
	v_mfma_f32_16x16x32_bf16 v[38:41], v[166:169], v[138:141], v[38:41]
	ds_read_b128 v[214:217], v241 offset:256
	v_mfma_f32_16x16x32_bf16 v[42:45], v[170:173], v[138:141], v[42:45]
	ds_read_b128 v[218:221], v241 offset:512
	global_load_lds_dwordx4 v226, s[54:55] offset:1024
	v_mfma_f32_16x16x32_bf16 v[46:49], v[174:177], v[138:141], v[46:49]
	ds_read_b128 v[222:225], v241 offset:768
	v_mfma_f32_16x16x32_bf16 v[62:65], v[174:177], v[142:145], v[62:65]
	ds_read_b128 v[178:181], v240 offset:0
	v_mfma_f32_16x16x32_bf16 v[58:61], v[170:173], v[142:145], v[58:61]
	ds_read_b128 v[182:185], v240 offset:1024
	v_mfma_f32_16x16x32_bf16 v[54:57], v[166:169], v[142:145], v[54:57]
	ds_read_b128 v[186:189], v240 offset:2048
	v_mfma_f32_16x16x32_bf16 v[50:53], v[162:165], v[142:145], v[50:53]
	ds_read_b128 v[190:193], v240 offset:3072
	global_load_lds_dwordx4 v226, s[54:55] offset:2048
	v_mfma_f32_16x16x32_bf16 v[66:69], v[162:165], v[146:149], v[66:69]
	ds_read_b128 v[194:197], v240 offset:4096
	v_mfma_f32_16x16x32_bf16 v[70:73], v[166:169], v[146:149], v[70:73]
	ds_read_b128 v[198:201], v240 offset:5120
	v_mfma_f32_16x16x32_bf16 v[74:77], v[170:173], v[146:149], v[74:77]
	ds_read_b128 v[202:205], v240 offset:6144
	v_mfma_f32_16x16x32_bf16 v[78:81], v[174:177], v[146:149], v[78:81]
	ds_read_b128 v[206:209], v240 offset:7168
	v_mfma_f32_16x16x32_bf16 v[94:97], v[174:177], v[150:153], v[94:97]
	global_load_lds_dwordx4 v226, s[54:55] offset:3072
	v_mfma_f32_16x16x32_bf16 v[90:93], v[170:173], v[150:153], v[90:93]
	v_mfma_f32_16x16x32_bf16 v[86:89], v[166:169], v[150:153], v[86:89]
	v_mfma_f32_16x16x32_bf16 v[82:85], v[162:165], v[150:153], v[82:85]
	v_mfma_f32_16x16x32_bf16 v[98:101], v[162:165], v[154:157], v[98:101]
	s_add_i32 m0, s60, s63
	v_mfma_f32_16x16x32_bf16 v[102:105], v[166:169], v[154:157], v[102:105]
	global_load_lds_dwordx4 v230, s[56:57]
	v_mfma_f32_16x16x32_bf16 v[106:109], v[170:173], v[154:157], v[106:109]
	v_mfma_f32_16x16x32_bf16 v[110:113], v[174:177], v[154:157], v[110:113]
	v_mfma_f32_16x16x32_bf16 v[126:129], v[174:177], v[158:161], v[126:129]
	v_mfma_f32_16x16x32_bf16 v[122:125], v[170:173], v[158:161], v[122:125]
	v_mfma_f32_16x16x32_bf16 v[118:121], v[166:169], v[158:161], v[118:121]
	global_load_lds_dwordx4 v231, s[56:57] offset:1024
	v_mfma_f32_16x16x32_bf16 v[114:117], v[162:165], v[158:161], v[114:117]
	s_setprio 0
	s_add_i32 s60, s60, 0x6000
	s_cmp_eq_u32 s60, 0x12000
	s_cselect_b32 s60, 0, s60
	s_add_u32 s54, s54, s72
	s_addc_u32 s55, s55, 0
	s_add_u32 s56, s56, s73
	s_addc_u32 s57, s57, 0
	s_add_i32 s61, s61, 0x6000
	s_cmp_eq_u32 s61, 0x12000
	s_cselect_b32 s61, 0, s61
	s_waitcnt lgkmcnt(0)
	v_add_u32_e32 v240, s61, v238
	v_add_u32_e32 v241, s61, v239
	s_setprio 1
	v_mfma_f32_16x16x32_bf16 v[2:5], v[210:213], v[178:181], v[2:5]
	v_mfma_f32_16x16x32_bf16 v[6:9], v[214:217], v[178:181], v[6:9]
	v_mfma_f32_16x16x32_bf16 v[10:13], v[218:221], v[178:181], v[10:13]
	v_mfma_f32_16x16x32_bf16 v[14:17], v[222:225], v[178:181], v[14:17]
	s_waitcnt vmcnt(6)
	s_barrier
	v_mfma_f32_16x16x32_bf16 v[30:33], v[222:225], v[182:185], v[30:33]
	s_add_i32 m0, s60, s62
	v_mfma_f32_16x16x32_bf16 v[26:29], v[218:221], v[182:185], v[26:29]
	global_load_lds_dwordx4 v226, s[54:55]
	v_mfma_f32_16x16x32_bf16 v[22:25], v[214:217], v[182:185], v[22:25]
	v_mfma_f32_16x16x32_bf16 v[18:21], v[210:213], v[182:185], v[18:21]
	v_mfma_f32_16x16x32_bf16 v[34:37], v[210:213], v[186:189], v[34:37]
	ds_read_b128 v[162:165], v241 offset:0
	v_mfma_f32_16x16x32_bf16 v[38:41], v[214:217], v[186:189], v[38:41]
	ds_read_b128 v[166:169], v241 offset:256
	v_mfma_f32_16x16x32_bf16 v[42:45], v[218:221], v[186:189], v[42:45]
	ds_read_b128 v[170:173], v241 offset:512
	global_load_lds_dwordx4 v226, s[54:55] offset:1024
	v_mfma_f32_16x16x32_bf16 v[46:49], v[222:225], v[186:189], v[46:49]
	ds_read_b128 v[174:177], v241 offset:768
	v_mfma_f32_16x16x32_bf16 v[62:65], v[222:225], v[190:193], v[62:65]
	ds_read_b128 v[130:133], v240 offset:0
	v_mfma_f32_16x16x32_bf16 v[58:61], v[218:221], v[190:193], v[58:61]
	ds_read_b128 v[134:137], v240 offset:1024
	v_mfma_f32_16x16x32_bf16 v[54:57], v[214:217], v[190:193], v[54:57]
	ds_read_b128 v[138:141], v240 offset:2048
	v_mfma_f32_16x16x32_bf16 v[50:53], v[210:213], v[190:193], v[50:53]
	ds_read_b128 v[142:145], v240 offset:3072
	global_load_lds_dwordx4 v226, s[54:55] offset:2048
	v_mfma_f32_16x16x32_bf16 v[66:69], v[210:213], v[194:197], v[66:69]
	ds_read_b128 v[146:149], v240 offset:4096
	v_mfma_f32_16x16x32_bf16 v[70:73], v[214:217], v[194:197], v[70:73]
	ds_read_b128 v[150:153], v240 offset:5120
	v_mfma_f32_16x16x32_bf16 v[74:77], v[218:221], v[194:197], v[74:77]
	ds_read_b128 v[154:157], v240 offset:6144
	v_mfma_f32_16x16x32_bf16 v[78:81], v[222:225], v[194:197], v[78:81]
	ds_read_b128 v[158:161], v240 offset:7168
	v_mfma_f32_16x16x32_bf16 v[94:97], v[222:225], v[198:201], v[94:97]
	global_load_lds_dwordx4 v226, s[54:55] offset:3072
	v_mfma_f32_16x16x32_bf16 v[90:93], v[218:221], v[198:201], v[90:93]
	v_mfma_f32_16x16x32_bf16 v[86:89], v[214:217], v[198:201], v[86:89]
	v_mfma_f32_16x16x32_bf16 v[82:85], v[210:213], v[198:201], v[82:85]
	v_mfma_f32_16x16x32_bf16 v[98:101], v[210:213], v[202:205], v[98:101]
	s_add_i32 m0, s60, s63
	v_mfma_f32_16x16x32_bf16 v[102:105], v[214:217], v[202:205], v[102:105]
	global_load_lds_dwordx4 v230, s[56:57]
	v_mfma_f32_16x16x32_bf16 v[106:109], v[218:221], v[202:205], v[106:109]
	v_mfma_f32_16x16x32_bf16 v[110:113], v[222:225], v[202:205], v[110:113]
	v_mfma_f32_16x16x32_bf16 v[126:129], v[222:225], v[206:209], v[126:129]
	v_mfma_f32_16x16x32_bf16 v[122:125], v[218:221], v[206:209], v[122:125]
	v_mfma_f32_16x16x32_bf16 v[118:121], v[214:217], v[206:209], v[118:121]
	global_load_lds_dwordx4 v231, s[56:57] offset:1024
	v_mfma_f32_16x16x32_bf16 v[114:117], v[210:213], v[206:209], v[114:117]
	s_setprio 0
	s_add_i32 s60, s60, 0x6000
	s_cmp_eq_u32 s60, 0x12000
	s_cselect_b32 s60, 0, s60
	s_add_u32 s54, s54, s72
	s_addc_u32 s55, s55, 0
	s_add_u32 s56, s56, s73
	s_addc_u32 s57, s57, 0
	s_add_i32 s61, s61, 0x6000
	s_cmp_eq_u32 s61, 0x12000
	s_cselect_b32 s61, 0, s61
	s_nop 7
	s_nop 1
	s_lshl_b32 s26, s35, 11
	s_lshl_b32 s27, s36, 1
	s_add_i32 s26, s26, s27
	s_add_u32 s18, s52, s26
	s_addc_u32 s19, s53, 0
	v_cvt_pk_bf16_f32 v2, v2, v3
	v_cvt_pk_bf16_f32 v3, v4, v5
	v_cvt_pk_bf16_f32 v4, v6, v7
	v_cvt_pk_bf16_f32 v5, v8, v9
	v_cvt_pk_bf16_f32 v6, v10, v11
	v_cvt_pk_bf16_f32 v7, v12, v13
	v_cvt_pk_bf16_f32 v8, v14, v15
	v_cvt_pk_bf16_f32 v9, v16, v17
	global_store_dwordx4 v242, v[2:5], s[18:19]
	global_store_dwordx4 v242, v[6:9], s[18:19] offset:16
	s_add_u32 s18, s18, 0x8000
	s_addc_u32 s19, s19, 0
	v_cvt_pk_bf16_f32 v18, v18, v19
	v_cvt_pk_bf16_f32 v19, v20, v21
	v_cvt_pk_bf16_f32 v20, v22, v23
	v_cvt_pk_bf16_f32 v21, v24, v25
	v_cvt_pk_bf16_f32 v22, v26, v27
	v_cvt_pk_bf16_f32 v23, v28, v29
	v_cvt_pk_bf16_f32 v24, v30, v31
	v_cvt_pk_bf16_f32 v25, v32, v33
	global_store_dwordx4 v242, v[18:21], s[18:19]
	global_store_dwordx4 v242, v[22:25], s[18:19] offset:16
	s_add_u32 s18, s18, 0x8000
	s_addc_u32 s19, s19, 0
	v_cvt_pk_bf16_f32 v34, v34, v35
	v_cvt_pk_bf16_f32 v35, v36, v37
	v_cvt_pk_bf16_f32 v36, v38, v39
	v_cvt_pk_bf16_f32 v37, v40, v41
	v_cvt_pk_bf16_f32 v38, v42, v43
	v_cvt_pk_bf16_f32 v39, v44, v45
	v_cvt_pk_bf16_f32 v40, v46, v47
	v_cvt_pk_bf16_f32 v41, v48, v49
	global_store_dwordx4 v242, v[34:37], s[18:19]
	global_store_dwordx4 v242, v[38:41], s[18:19] offset:16
	s_add_u32 s18, s18, 0x8000
	s_addc_u32 s19, s19, 0
	v_cvt_pk_bf16_f32 v50, v50, v51
	v_cvt_pk_bf16_f32 v51, v52, v53
	v_cvt_pk_bf16_f32 v52, v54, v55
	v_cvt_pk_bf16_f32 v53, v56, v57
	v_cvt_pk_bf16_f32 v54, v58, v59
	v_cvt_pk_bf16_f32 v55, v60, v61
	v_cvt_pk_bf16_f32 v56, v62, v63
	v_cvt_pk_bf16_f32 v57, v64, v65
	global_store_dwordx4 v242, v[50:53], s[18:19]
	global_store_dwordx4 v242, v[54:57], s[18:19] offset:16
	s_add_u32 s18, s18, 0x8000
	s_addc_u32 s19, s19, 0
	v_cvt_pk_bf16_f32 v66, v66, v67
	v_cvt_pk_bf16_f32 v67, v68, v69
	v_cvt_pk_bf16_f32 v68, v70, v71
	v_cvt_pk_bf16_f32 v69, v72, v73
	v_cvt_pk_bf16_f32 v70, v74, v75
	v_cvt_pk_bf16_f32 v71, v76, v77
	v_cvt_pk_bf16_f32 v72, v78, v79
	v_cvt_pk_bf16_f32 v73, v80, v81
	global_store_dwordx4 v242, v[66:69], s[18:19]
	global_store_dwordx4 v242, v[70:73], s[18:19] offset:16
	s_add_u32 s18, s18, 0x8000
	s_addc_u32 s19, s19, 0
	v_cvt_pk_bf16_f32 v82, v82, v83
	v_cvt_pk_bf16_f32 v83, v84, v85
	v_cvt_pk_bf16_f32 v84, v86, v87
	v_cvt_pk_bf16_f32 v85, v88, v89
	v_cvt_pk_bf16_f32 v86, v90, v91
	v_cvt_pk_bf16_f32 v87, v92, v93
	v_cvt_pk_bf16_f32 v88, v94, v95
	v_cvt_pk_bf16_f32 v89, v96, v97
	global_store_dwordx4 v242, v[82:85], s[18:19]
	global_store_dwordx4 v242, v[86:89], s[18:19] offset:16
	s_add_u32 s18, s18, 0x8000
	s_addc_u32 s19, s19, 0
	v_cvt_pk_bf16_f32 v98, v98, v99
	v_cvt_pk_bf16_f32 v99, v100, v101
	v_cvt_pk_bf16_f32 v100, v102, v103
	v_cvt_pk_bf16_f32 v101, v104, v105
	v_cvt_pk_bf16_f32 v102, v106, v107
	v_cvt_pk_bf16_f32 v103, v108, v109
	v_cvt_pk_bf16_f32 v104, v110, v111
	v_cvt_pk_bf16_f32 v105, v112, v113
	global_store_dwordx4 v242, v[98:101], s[18:19]
	global_store_dwordx4 v242, v[102:105], s[18:19] offset:16
	s_add_u32 s18, s18, 0x8000
	s_addc_u32 s19, s19, 0
	v_cvt_pk_bf16_f32 v114, v114, v115
	v_cvt_pk_bf16_f32 v115, v116, v117
	v_cvt_pk_bf16_f32 v116, v118, v119
	v_cvt_pk_bf16_f32 v117, v120, v121
	v_cvt_pk_bf16_f32 v118, v122, v123
	v_cvt_pk_bf16_f32 v119, v124, v125
	v_cvt_pk_bf16_f32 v120, v126, v127
	v_cvt_pk_bf16_f32 v121, v128, v129
	global_store_dwordx4 v242, v[114:117], s[18:19]
	global_store_dwordx4 v242, v[118:121], s[18:19] offset:16
	s_mov_b32 s34, s38
	s_mov_b32 s35, s30
	s_mov_b32 s36, s31
	s_branch .Lgy_tile
.Lgy_tail_last:
	s_waitcnt lgkmcnt(0)
	v_add_u32_e32 v240, s61, v238
	v_add_u32_e32 v241, s61, v239
	s_setprio 1
	v_mfma_f32_16x16x32_bf16 v[2:5], v[162:165], v[130:133], v[2:5]
	v_mfma_f32_16x16x32_bf16 v[6:9], v[166:169], v[130:133], v[6:9]
	v_mfma_f32_16x16x32_bf16 v[10:13], v[170:173], v[130:133], v[10:13]
	v_mfma_f32_16x16x32_bf16 v[14:17], v[174:177], v[130:133], v[14:17]
	s_waitcnt vmcnt(6)
	s_barrier
	v_mfma_f32_16x16x32_bf16 v[30:33], v[174:177], v[134:137], v[30:33]
	s_add_i32 m0, s60, s62
	v_mfma_f32_16x16x32_bf16 v[26:29], v[170:173], v[134:137], v[26:29]
	global_load_lds_dwordx4 v226, s[54:55]
	v_mfma_f32_16x16x32_bf16 v[22:25], v[166:169], v[134:137], v[22:25]
	v_mfma_f32_16x16x32_bf16 v[18:21], v[162:165], v[134:137], v[18:21]
	v_mfma_f32_16x16x32_bf16 v[34:37], v[162:165], v[138:141], v[34:37]
	ds_read_b128 v[210:213], v241 offset:0
	v_mfma_f32_16x16x32_bf16 v[38:41], v[166:169], v[138:141], v[38:41]
	ds_read_b128 v[214:217], v241 offset:256
	v_mfma_f32_16x16x32_bf16 v[42:45], v[170:173], v[138:141], v[42:45]
	ds_read_b128 v[218:221], v241 offset:512
	global_load_lds_dwordx4 v226, s[54:55] offset:1024
	v_mfma_f32_16x16x32_bf16 v[46:49], v[174:177], v[138:141], v[46:49]
	ds_read_b128 v[222:225], v241 offset:768
	v_mfma_f32_16x16x32_bf16 v[62:65], v[174:177], v[142:145], v[62:65]
	ds_read_b128 v[178:181], v240 offset:0
	v_mfma_f32_16x16x32_bf16 v[58:61], v[170:173], v[142:145], v[58:61]
	ds_read_b128 v[182:185], v240 offset:1024
	v_mfma_f32_16x16x32_bf16 v[54:57], v[166:169], v[142:145], v[54:57]
	ds_read_b128 v[186:189], v240 offset:2048
	v_mfma_f32_16x16x32_bf16 v[50:53], v[162:165], v[142:145], v[50:53]
	ds_read_b128 v[190:193], v240 offset:3072
	global_load_lds_dwordx4 v226, s[54:55] offset:2048
	v_mfma_f32_16x16x32_bf16 v[66:69], v[162:165], v[146:149], v[66:69]
	ds_read_b128 v[194:197], v240 offset:4096
	v_mfma_f32_16x16x32_bf16 v[70:73], v[166:169], v[146:149], v[70:73]
	ds_read_b128 v[198:201], v240 offset:5120
	v_mfma_f32_16x16x32_bf16 v[74:77], v[170:173], v[146:149], v[74:77]
	ds_read_b128 v[202:205], v240 offset:6144
	v_mfma_f32_16x16x32_bf16 v[78:81], v[174:177], v[146:149], v[78:81]
	ds_read_b128 v[206:209], v240 offset:7168
	v_mfma_f32_16x16x32_bf16 v[94:97], v[174:177], v[150:153], v[94:97]
	global_load_lds_dwordx4 v226, s[54:55] offset:3072
	v_mfma_f32_16x16x32_bf16 v[90:93], v[170:173], v[150:153], v[90:93]
	v_mfma_f32_16x16x32_bf16 v[86:89], v[166:169], v[150:153], v[86:89]
	v_mfma_f32_16x16x32_bf16 v[82:85], v[162:165], v[150:153], v[82:85]
	v_mfma_f32_16x16x32_bf16 v[98:101], v[162:165], v[154:157], v[98:101]
	s_add_i32 m0, s60, s63
	v_mfma_f32_16x16x32_bf16 v[102:105], v[166:169], v[154:157], v[102:105]
	global_load_lds_dwordx4 v230, s[56:57]
	v_mfma_f32_16x16x32_bf16 v[106:109], v[170:173], v[154:157], v[106:109]
	v_mfma_f32_16x16x32_bf16 v[110:113], v[174:177], v[154:157], v[110:113]
	v_mfma_f32_16x16x32_bf16 v[126:129], v[174:177], v[158:161], v[126:129]
	v_mfma_f32_16x16x32_bf16 v[122:125], v[170:173], v[158:161], v[122:125]
	v_mfma_f32_16x16x32_bf16 v[118:121], v[166:169], v[158:161], v[118:121]
	global_load_lds_dwordx4 v231, s[56:57] offset:1024
	v_mfma_f32_16x16x32_bf16 v[114:117], v[162:165], v[158:161], v[114:117]
	s_setprio 0
	s_add_i32 s60, s60, 0x6000
	s_cmp_eq_u32 s60, 0x12000
	s_cselect_b32 s60, 0, s60
	s_add_u32 s54, s54, s72
	s_addc_u32 s55, s55, 0
	s_add_u32 s56, s56, s73
	s_addc_u32 s57, s57, 0
	s_add_i32 s61, s61, 0x6000
	s_cmp_eq_u32 s61, 0x12000
	s_cselect_b32 s61, 0, s61
	s_waitcnt lgkmcnt(0)
	v_add_u32_e32 v240, s61, v238
	v_add_u32_e32 v241, s61, v239
	s_setprio 1
	v_mfma_f32_16x16x32_bf16 v[2:5], v[210:213], v[178:181], v[2:5]
	v_mfma_f32_16x16x32_bf16 v[6:9], v[214:217], v[178:181], v[6:9]
	v_mfma_f32_16x16x32_bf16 v[10:13], v[218:221], v[178:181], v[10:13]
	v_mfma_f32_16x16x32_bf16 v[14:17], v[222:225], v[178:181], v[14:17]
	s_waitcnt vmcnt(6)
	s_barrier
	v_mfma_f32_16x16x32_bf16 v[30:33], v[222:225], v[182:185], v[30:33]
	v_mfma_f32_16x16x32_bf16 v[26:29], v[218:221], v[182:185], v[26:29]
	v_mfma_f32_16x16x32_bf16 v[22:25], v[214:217], v[182:185], v[22:25]
	v_mfma_f32_16x16x32_bf16 v[18:21], v[210:213], v[182:185], v[18:21]
	v_mfma_f32_16x16x32_bf16 v[34:37], v[210:213], v[186:189], v[34:37]
	ds_read_b128 v[162:165], v241 offset:0
	v_mfma_f32_16x16x32_bf16 v[38:41], v[214:217], v[186:189], v[38:41]
	ds_read_b128 v[166:169], v241 offset:256
	v_mfma_f32_16x16x32_bf16 v[42:45], v[218:221], v[186:189], v[42:45]
	ds_read_b128 v[170:173], v241 offset:512
	v_mfma_f32_16x16x32_bf16 v[46:49], v[222:225], v[186:189], v[46:49]
	ds_read_b128 v[174:177], v241 offset:768
	v_mfma_f32_16x16x32_bf16 v[62:65], v[222:225], v[190:193], v[62:65]
	ds_read_b128 v[130:133], v240 offset:0
	v_mfma_f32_16x16x32_bf16 v[58:61], v[218:221], v[190:193], v[58:61]
	ds_read_b128 v[134:137], v240 offset:1024
	v_mfma_f32_16x16x32_bf16 v[54:57], v[214:217], v[190:193], v[54:57]
	ds_read_b128 v[138:141], v240 offset:2048
	v_mfma_f32_16x16x32_bf16 v[50:53], v[210:213], v[190:193], v[50:53]
	ds_read_b128 v[142:145], v240 offset:3072
	v_mfma_f32_16x16x32_bf16 v[66:69], v[210:213], v[194:197], v[66:69]
	ds_read_b128 v[146:149], v240 offset:4096
	v_mfma_f32_16x16x32_bf16 v[70:73], v[214:217], v[194:197], v[70:73]
	ds_read_b128 v[150:153], v240 offset:5120
	v_mfma_f32_16x16x32_bf16 v[74:77], v[218:221], v[194:197], v[74:77]
	ds_read_b128 v[154:157], v240 offset:6144
	v_mfma_f32_16x16x32_bf16 v[78:81], v[222:225], v[194:197], v[78:81]
	ds_read_b128 v[158:161], v240 offset:7168
	v_mfma_f32_16x16x32_bf16 v[94:97], v[222:225], v[198:201], v[94:97]
	v_mfma_f32_16x16x32_bf16 v[90:93], v[218:221], v[198:201], v[90:93]
	v_mfma_f32_16x16x32_bf16 v[86:89], v[214:217], v[198:201], v[86:89]
	v_mfma_f32_16x16x32_bf16 v[82:85], v[210:213], v[198:201], v[82:85]
	v_mfma_f32_16x16x32_bf16 v[98:101], v[210:213], v[202:205], v[98:101]
	v_mfma_f32_16x16x32_bf16 v[102:105], v[214:217], v[202:205], v[102:105]
	v_mfma_f32_16x16x32_bf16 v[106:109], v[218:221], v[202:205], v[106:109]
	v_mfma_f32_16x16x32_bf16 v[110:113], v[222:225], v[202:205], v[110:113]
	v_mfma_f32_16x16x32_bf16 v[126:129], v[222:225], v[206:209], v[126:129]
	v_mfma_f32_16x16x32_bf16 v[122:125], v[218:221], v[206:209], v[122:125]
	v_mfma_f32_16x16x32_bf16 v[118:121], v[214:217], v[206:209], v[118:121]
	v_mfma_f32_16x16x32_bf16 v[114:117], v[210:213], v[206:209], v[114:117]
	s_setprio 0
	s_add_i32 s61, s61, 0x6000
	s_cmp_eq_u32 s61, 0x12000
	s_cselect_b32 s61, 0, s61
	s_waitcnt lgkmcnt(0)
	v_add_u32_e32 v240, s61, v238
	v_add_u32_e32 v241, s61, v239
	s_setprio 1
	v_mfma_f32_16x16x32_bf16 v[2:5], v[162:165], v[130:133], v[2:5]
	v_mfma_f32_16x16x32_bf16 v[6:9], v[166:169], v[130:133], v[6:9]
	v_mfma_f32_16x16x32_bf16 v[10:13], v[170:173], v[130:133], v[10:13]
	v_mfma_f32_16x16x32_bf16 v[14:17], v[174:177], v[130:133], v[14:17]
	s_waitcnt vmcnt(0)
	s_barrier
	v_mfma_f32_16x16x32_bf16 v[30:33], v[174:177], v[134:137], v[30:33]
	v_mfma_f32_16x16x32_bf16 v[26:29], v[170:173], v[134:137], v[26:29]
	v_mfma_f32_16x16x32_bf16 v[22:25], v[166:169], v[134:137], v[22:25]
	v_mfma_f32_16x16x32_bf16 v[18:21], v[162:165], v[134:137], v[18:21]
	v_mfma_f32_16x16x32_bf16 v[34:37], v[162:165], v[138:141], v[34:37]
	ds_read_b128 v[210:213], v241 offset:0
	v_mfma_f32_16x16x32_bf16 v[38:41], v[166:169], v[138:141], v[38:41]
	ds_read_b128 v[214:217], v241 offset:256
	v_mfma_f32_16x16x32_bf16 v[42:45], v[170:173], v[138:141], v[42:45]
	ds_read_b128 v[218:221], v241 offset:512
	v_mfma_f32_16x16x32_bf16 v[46:49], v[174:177], v[138:141], v[46:49]
	ds_read_b128 v[222:225], v241 offset:768
	v_mfma_f32_16x16x32_bf16 v[62:65], v[174:177], v[142:145], v[62:65]
	ds_read_b128 v[178:181], v240 offset:0
	v_mfma_f32_16x16x32_bf16 v[58:61], v[170:173], v[142:145], v[58:61]
	ds_read_b128 v[182:185], v240 offset:1024
	v_mfma_f32_16x16x32_bf16 v[54:57], v[166:169], v[142:145], v[54:57]
	ds_read_b128 v[186:189], v240 offset:2048
	v_mfma_f32_16x16x32_bf16 v[50:53], v[162:165], v[142:145], v[50:53]
	ds_read_b128 v[190:193], v240 offset:3072
	v_mfma_f32_16x16x32_bf16 v[66:69], v[162:165], v[146:149], v[66:69]
	ds_read_b128 v[194:197], v240 offset:4096
	v_mfma_f32_16x16x32_bf16 v[70:73], v[166:169], v[146:149], v[70:73]
	ds_read_b128 v[198:201], v240 offset:5120
	v_mfma_f32_16x16x32_bf16 v[74:77], v[170:173], v[146:149], v[74:77]
	ds_read_b128 v[202:205], v240 offset:6144
	v_mfma_f32_16x16x32_bf16 v[78:81], v[174:177], v[146:149], v[78:81]
	ds_read_b128 v[206:209], v240 offset:7168
	v_mfma_f32_16x16x32_bf16 v[94:97], v[174:177], v[150:153], v[94:97]
	v_mfma_f32_16x16x32_bf16 v[90:93], v[170:173], v[150:153], v[90:93]
	v_mfma_f32_16x16x32_bf16 v[86:89], v[166:169], v[150:153], v[86:89]
	v_mfma_f32_16x16x32_bf16 v[82:85], v[162:165], v[150:153], v[82:85]
	v_mfma_f32_16x16x32_bf16 v[98:101], v[162:165], v[154:157], v[98:101]
	v_mfma_f32_16x16x32_bf16 v[102:105], v[166:169], v[154:157], v[102:105]
	v_mfma_f32_16x16x32_bf16 v[106:109], v[170:173], v[154:157], v[106:109]
	v_mfma_f32_16x16x32_bf16 v[110:113], v[174:177], v[154:157], v[110:113]
	v_mfma_f32_16x16x32_bf16 v[126:129], v[174:177], v[158:161], v[126:129]
	v_mfma_f32_16x16x32_bf16 v[122:125], v[170:173], v[158:161], v[122:125]
	v_mfma_f32_16x16x32_bf16 v[118:121], v[166:169], v[158:161], v[118:121]
	v_mfma_f32_16x16x32_bf16 v[114:117], v[162:165], v[158:161], v[114:117]
	s_setprio 0
	s_add_i32 s61, s61, 0x6000
	s_cmp_eq_u32 s61, 0x12000
	s_cselect_b32 s61, 0, s61
	s_waitcnt lgkmcnt(0)
	s_setprio 1
	v_mfma_f32_16x16x32_bf16 v[2:5], v[210:213], v[178:181], v[2:5]
	v_mfma_f32_16x16x32_bf16 v[6:9], v[214:217], v[178:181], v[6:9]
	v_mfma_f32_16x16x32_bf16 v[10:13], v[218:221], v[178:181], v[10:13]
	v_mfma_f32_16x16x32_bf16 v[14:17], v[222:225], v[178:181], v[14:17]
	s_barrier
	v_mfma_f32_16x16x32_bf16 v[30:33], v[222:225], v[182:185], v[30:33]
	v_mfma_f32_16x16x32_bf16 v[26:29], v[218:221], v[182:185], v[26:29]
	v_mfma_f32_16x16x32_bf16 v[22:25], v[214:217], v[182:185], v[22:25]
	v_mfma_f32_16x16x32_bf16 v[18:21], v[210:213], v[182:185], v[18:21]
	v_mfma_f32_16x16x32_bf16 v[34:37], v[210:213], v[186:189], v[34:37]
	v_mfma_f32_16x16x32_bf16 v[38:41], v[214:217], v[186:189], v[38:41]
	v_mfma_f32_16x16x32_bf16 v[42:45], v[218:221], v[186:189], v[42:45]
	v_mfma_f32_16x16x32_bf16 v[46:49], v[222:225], v[186:189], v[46:49]
	v_mfma_f32_16x16x32_bf16 v[62:65], v[222:225], v[190:193], v[62:65]
	v_mfma_f32_16x16x32_bf16 v[58:61], v[218:221], v[190:193], v[58:61]
	v_mfma_f32_16x16x32_bf16 v[54:57], v[214:217], v[190:193], v[54:57]
	v_mfma_f32_16x16x32_bf16 v[50:53], v[210:213], v[190:193], v[50:53]
	v_mfma_f32_16x16x32_bf16 v[66:69], v[210:213], v[194:197], v[66:69]
	v_mfma_f32_16x16x32_bf16 v[70:73], v[214:217], v[194:197], v[70:73]
	v_mfma_f32_16x16x32_bf16 v[74:77], v[218:221], v[194:197], v[74:77]
	v_mfma_f32_16x16x32_bf16 v[78:81], v[222:225], v[194:197], v[78:81]
	v_mfma_f32_16x16x32_bf16 v[94:97], v[222:225], v[198:201], v[94:97]
	v_mfma_f32_16x16x32_bf16 v[90:93], v[218:221], v[198:201], v[90:93]
	v_mfma_f32_16x16x32_bf16 v[86:89], v[214:217], v[198:201], v[86:89]
	v_mfma_f32_16x16x32_bf16 v[82:85], v[210:213], v[198:201], v[82:85]
	v_mfma_f32_16x16x32_bf16 v[98:101], v[210:213], v[202:205], v[98:101]
	v_mfma_f32_16x16x32_bf16 v[102:105], v[214:217], v[202:205], v[102:105]
	v_mfma_f32_16x16x32_bf16 v[106:109], v[218:221], v[202:205], v[106:109]
	v_mfma_f32_16x16x32_bf16 v[110:113], v[222:225], v[202:205], v[110:113]
	v_mfma_f32_16x16x32_bf16 v[126:129], v[222:225], v[206:209], v[126:129]
	v_mfma_f32_16x16x32_bf16 v[122:125], v[218:221], v[206:209], v[122:125]
	v_mfma_f32_16x16x32_bf16 v[118:121], v[214:217], v[206:209], v[118:121]
	v_mfma_f32_16x16x32_bf16 v[114:117], v[210:213], v[206:209], v[114:117]
	s_setprio 0
	s_nop 7
	s_nop 1
	s_lshl_b32 s26, s35, 11
	s_lshl_b32 s27, s36, 1
	s_add_i32 s26, s26, s27
	s_add_u32 s18, s52, s26
	s_addc_u32 s19, s53, 0
	v_cvt_pk_bf16_f32 v2, v2, v3
	v_cvt_pk_bf16_f32 v3, v4, v5
	v_cvt_pk_bf16_f32 v4, v6, v7
	v_cvt_pk_bf16_f32 v5, v8, v9
	v_cvt_pk_bf16_f32 v6, v10, v11
	v_cvt_pk_bf16_f32 v7, v12, v13
	v_cvt_pk_bf16_f32 v8, v14, v15
	v_cvt_pk_bf16_f32 v9, v16, v17
	global_store_dwordx4 v242, v[2:5], s[18:19]
	global_store_dwordx4 v242, v[6:9], s[18:19] offset:16
	s_add_u32 s18, s18, 0x8000
	s_addc_u32 s19, s19, 0
	v_cvt_pk_bf16_f32 v18, v18, v19
	v_cvt_pk_bf16_f32 v19, v20, v21
	v_cvt_pk_bf16_f32 v20, v22, v23
	v_cvt_pk_bf16_f32 v21, v24, v25
	v_cvt_pk_bf16_f32 v22, v26, v27
	v_cvt_pk_bf16_f32 v23, v28, v29
	v_cvt_pk_bf16_f32 v24, v30, v31
	v_cvt_pk_bf16_f32 v25, v32, v33
	global_store_dwordx4 v242, v[18:21], s[18:19]
	global_store_dwordx4 v242, v[22:25], s[18:19] offset:16
	s_add_u32 s18, s18, 0x8000
	s_addc_u32 s19, s19, 0
	v_cvt_pk_bf16_f32 v34, v34, v35
	v_cvt_pk_bf16_f32 v35, v36, v37
	v_cvt_pk_bf16_f32 v36, v38, v39
	v_cvt_pk_bf16_f32 v37, v40, v41
	v_cvt_pk_bf16_f32 v38, v42, v43
	v_cvt_pk_bf16_f32 v39, v44, v45
	v_cvt_pk_bf16_f32 v40, v46, v47
	v_cvt_pk_bf16_f32 v41, v48, v49
	global_store_dwordx4 v242, v[34:37], s[18:19]
	global_store_dwordx4 v242, v[38:41], s[18:19] offset:16
	s_add_u32 s18, s18, 0x8000
	s_addc_u32 s19, s19, 0
	v_cvt_pk_bf16_f32 v50, v50, v51
	v_cvt_pk_bf16_f32 v51, v52, v53
	v_cvt_pk_bf16_f32 v52, v54, v55
	v_cvt_pk_bf16_f32 v53, v56, v57
	v_cvt_pk_bf16_f32 v54, v58, v59
	v_cvt_pk_bf16_f32 v55, v60, v61
	v_cvt_pk_bf16_f32 v56, v62, v63
	v_cvt_pk_bf16_f32 v57, v64, v65
	global_store_dwordx4 v242, v[50:53], s[18:19]
	global_store_dwordx4 v242, v[54:57], s[18:19] offset:16
	s_add_u32 s18, s18, 0x8000
	s_addc_u32 s19, s19, 0
	v_cvt_pk_bf16_f32 v66, v66, v67
	v_cvt_pk_bf16_f32 v67, v68, v69
	v_cvt_pk_bf16_f32 v68, v70, v71
	v_cvt_pk_bf16_f32 v69, v72, v73
	v_cvt_pk_bf16_f32 v70, v74, v75
	v_cvt_pk_bf16_f32 v71, v76, v77
	v_cvt_pk_bf16_f32 v72, v78, v79
	v_cvt_pk_bf16_f32 v73, v80, v81
	global_store_dwordx4 v242, v[66:69], s[18:19]
	global_store_dwordx4 v242, v[70:73], s[18:19] offset:16
	s_add_u32 s18, s18, 0x8000
	s_addc_u32 s19, s19, 0
	v_cvt_pk_bf16_f32 v82, v82, v83
	v_cvt_pk_bf16_f32 v83, v84, v85
	v_cvt_pk_bf16_f32 v84, v86, v87
	v_cvt_pk_bf16_f32 v85, v88, v89
	v_cvt_pk_bf16_f32 v86, v90, v91
	v_cvt_pk_bf16_f32 v87, v92, v93
	v_cvt_pk_bf16_f32 v88, v94, v95
	v_cvt_pk_bf16_f32 v89, v96, v97
	global_store_dwordx4 v242, v[82:85], s[18:19]
	global_store_dwordx4 v242, v[86:89], s[18:19] offset:16
	s_add_u32 s18, s18, 0x8000
	s_addc_u32 s19, s19, 0
	v_cvt_pk_bf16_f32 v98, v98, v99
	v_cvt_pk_bf16_f32 v99, v100, v101
	v_cvt_pk_bf16_f32 v100, v102, v103
	v_cvt_pk_bf16_f32 v101, v104, v105
	v_cvt_pk_bf16_f32 v102, v106, v107
	v_cvt_pk_bf16_f32 v103, v108, v109
	v_cvt_pk_bf16_f32 v104, v110, v111
	v_cvt_pk_bf16_f32 v105, v112, v113
	global_store_dwordx4 v242, v[98:101], s[18:19]
	global_store_dwordx4 v242, v[102:105], s[18:19] offset:16
	s_add_u32 s18, s18, 0x8000
	s_addc_u32 s19, s19, 0
	v_cvt_pk_bf16_f32 v114, v114, v115
	v_cvt_pk_bf16_f32 v115, v116, v117
	v_cvt_pk_bf16_f32 v116, v118, v119
	v_cvt_pk_bf16_f32 v117, v120, v121
	v_cvt_pk_bf16_f32 v118, v122, v123
	v_cvt_pk_bf16_f32 v119, v124, v125
	v_cvt_pk_bf16_f32 v120, v126, v127
	v_cvt_pk_bf16_f32 v121, v128, v129
	global_store_dwordx4 v242, v[114:117], s[18:19]
	global_store_dwordx4 v242, v[118:121], s[18:19] offset:16

.Lup_nn_a:
	s_waitcnt lgkmcnt(0)
	v_add_u32_e32 v240, s61, v238
	v_add_u32_e32 v241, s61, v239
	s_setprio 1
	v_mfma_f32_16x16x32_bf16 v[2:5], v[162:165], v[130:133], 0
	v_mfma_f32_16x16x32_bf16 v[6:9], v[166:169], v[130:133], 0
	v_mfma_f32_16x16x32_bf16 v[10:13], v[170:173], v[130:133], 0
	v_mfma_f32_16x16x32_bf16 v[14:17], v[174:177], v[130:133], 0
	s_waitcnt vmcnt(6)
	s_barrier
	v_mfma_f32_16x16x32_bf16 v[30:33], v[174:177], v[134:137], 0
	s_add_i32 m0, s60, s62
	v_mfma_f32_16x16x32_bf16 v[26:29], v[170:173], v[134:137], 0
	global_load_lds_dwordx4 v226, s[54:55]
	v_mfma_f32_16x16x32_bf16 v[22:25], v[166:169], v[134:137], 0
	v_mfma_f32_16x16x32_bf16 v[18:21], v[162:165], v[134:137], 0
	v_mfma_f32_16x16x32_bf16 v[34:37], v[162:165], v[138:141], 0
	ds_read_b128 v[210:213], v241 offset:0
	v_mfma_f32_16x16x32_bf16 v[38:41], v[166:169], v[138:141], 0
	ds_read_b128 v[214:217], v241 offset:256
	v_mfma_f32_16x16x32_bf16 v[42:45], v[170:173], v[138:141], 0
	ds_read_b128 v[218:221], v241 offset:2048
	global_load_lds_dwordx4 v226, s[54:55] offset:1024
	v_mfma_f32_16x16x32_bf16 v[46:49], v[174:177], v[138:141], 0
	ds_read_b128 v[222:225], v241 offset:2304
	v_mfma_f32_16x16x32_bf16 v[62:65], v[174:177], v[142:145], 0
	ds_read_b128 v[178:181], v240 offset:0
	v_mfma_f32_16x16x32_bf16 v[58:61], v[170:173], v[142:145], 0
	ds_read_b128 v[182:185], v240 offset:1024
	v_mfma_f32_16x16x32_bf16 v[54:57], v[166:169], v[142:145], 0
	ds_read_b128 v[186:189], v240 offset:2048
	v_mfma_f32_16x16x32_bf16 v[50:53], v[162:165], v[142:145], 0
	ds_read_b128 v[190:193], v240 offset:3072
	global_load_lds_dwordx4 v226, s[54:55] offset:2048
	v_mfma_f32_16x16x32_bf16 v[66:69], v[162:165], v[146:149], 0
	ds_read_b128 v[194:197], v240 offset:4096
	v_mfma_f32_16x16x32_bf16 v[70:73], v[166:169], v[146:149], 0
	ds_read_b128 v[198:201], v240 offset:5120
	v_mfma_f32_16x16x32_bf16 v[74:77], v[170:173], v[146:149], 0
	ds_read_b128 v[202:205], v240 offset:6144
	v_mfma_f32_16x16x32_bf16 v[78:81], v[174:177], v[146:149], 0
	ds_read_b128 v[206:209], v240 offset:7168
	v_mfma_f32_16x16x32_bf16 v[94:97], v[174:177], v[150:153], 0
	global_load_lds_dwordx4 v226, s[54:55] offset:3072
	v_mfma_f32_16x16x32_bf16 v[90:93], v[170:173], v[150:153], 0
	v_mfma_f32_16x16x32_bf16 v[86:89], v[166:169], v[150:153], 0
	v_mfma_f32_16x16x32_bf16 v[82:85], v[162:165], v[150:153], 0
	v_mfma_f32_16x16x32_bf16 v[98:101], v[162:165], v[154:157], 0
	s_add_i32 m0, s60, s63
	v_mfma_f32_16x16x32_bf16 v[102:105], v[166:169], v[154:157], 0
	global_load_lds_dwordx4 v230, s[56:57]
	v_mfma_f32_16x16x32_bf16 v[106:109], v[170:173], v[154:157], 0
	v_mfma_f32_16x16x32_bf16 v[110:113], v[174:177], v[154:157], 0
	v_mfma_f32_16x16x32_bf16 v[126:129], v[174:177], v[158:161], 0
	v_mfma_f32_16x16x32_bf16 v[122:125], v[170:173], v[158:161], 0
	v_mfma_f32_16x16x32_bf16 v[118:121], v[166:169], v[158:161], 0
	global_load_lds_dwordx4 v231, s[56:57] offset:1024
	v_mfma_f32_16x16x32_bf16 v[114:117], v[162:165], v[158:161], 0
	s_setprio 0
	s_add_i32 s60, s60, 0x6000
	s_cmp_eq_u32 s60, 0x12000
	s_cselect_b32 s60, 0, s60
	s_add_u32 s54, s54, s72
	s_addc_u32 s55, s55, 0
	s_add_u32 s56, s56, s73
	s_addc_u32 s57, s57, 0
	s_add_i32 s61, s61, 0x6000
	s_cmp_eq_u32 s61, 0x12000
	s_cselect_b32 s61, 0, s61
	v_mbcnt_lo_u32_b32 v0, -1, 0
	v_lshlrev_b32_e32 v0, 4, v0
	s_lshl_b32 s26, s36, 1
	v_add_u32_e32 v0, s26, v0
	s_lshl_b32 s26, s41, 8
	s_add_i32 m0, s26, 0x13010
	s_mov_b64 exec, 0xffff
	global_load_lds_dwordx4 v0, s[82:83]
	s_mov_b64 exec, -1
	s_waitcnt lgkmcnt(0)
	v_add_u32_e32 v240, s61, v238
	v_add_u32_e32 v241, s61, v239
	s_setprio 1
	v_mfma_f32_16x16x32_bf16 v[2:5], v[210:213], v[178:181], v[2:5]
	v_mfma_f32_16x16x32_bf16 v[6:9], v[214:217], v[178:181], v[6:9]
	v_mfma_f32_16x16x32_bf16 v[10:13], v[218:221], v[178:181], v[10:13]
	v_mfma_f32_16x16x32_bf16 v[14:17], v[222:225], v[178:181], v[14:17]
	s_waitcnt vmcnt(6)
	s_barrier
	v_mfma_f32_16x16x32_bf16 v[30:33], v[222:225], v[182:185], v[30:33]
	s_add_i32 m0, s60, s62
	v_mfma_f32_16x16x32_bf16 v[26:29], v[218:221], v[182:185], v[26:29]
	global_load_lds_dwordx4 v226, s[54:55]
	v_mfma_f32_16x16x32_bf16 v[22:25], v[214:217], v[182:185], v[22:25]
	v_mfma_f32_16x16x32_bf16 v[18:21], v[210:213], v[182:185], v[18:21]
	v_mfma_f32_16x16x32_bf16 v[34:37], v[210:213], v[186:189], v[34:37]
	ds_read_b128 v[162:165], v241 offset:0
	v_mfma_f32_16x16x32_bf16 v[38:41], v[214:217], v[186:189], v[38:41]
	ds_read_b128 v[166:169], v241 offset:256
	v_mfma_f32_16x16x32_bf16 v[42:45], v[218:221], v[186:189], v[42:45]
	ds_read_b128 v[170:173], v241 offset:2048
	global_load_lds_dwordx4 v226, s[54:55] offset:1024
	v_mfma_f32_16x16x32_bf16 v[46:49], v[222:225], v[186:189], v[46:49]
	ds_read_b128 v[174:177], v241 offset:2304
	v_mfma_f32_16x16x32_bf16 v[62:65], v[222:225], v[190:193], v[62:65]
	ds_read_b128 v[130:133], v240 offset:0
	v_mfma_f32_16x16x32_bf16 v[58:61], v[218:221], v[190:193], v[58:61]
	ds_read_b128 v[134:137], v240 offset:1024
	v_mfma_f32_16x16x32_bf16 v[54:57], v[214:217], v[190:193], v[54:57]
	ds_read_b128 v[138:141], v240 offset:2048
	v_mfma_f32_16x16x32_bf16 v[50:53], v[210:213], v[190:193], v[50:53]
	ds_read_b128 v[142:145], v240 offset:3072
	global_load_lds_dwordx4 v226, s[54:55] offset:2048
	v_mfma_f32_16x16x32_bf16 v[66:69], v[210:213], v[194:197], v[66:69]
	ds_read_b128 v[146:149], v240 offset:4096
	v_mfma_f32_16x16x32_bf16 v[70:73], v[214:217], v[194:197], v[70:73]
	ds_read_b128 v[150:153], v240 offset:5120
	v_mfma_f32_16x16x32_bf16 v[74:77], v[218:221], v[194:197], v[74:77]
	ds_read_b128 v[154:157], v240 offset:6144
	v_mfma_f32_16x16x32_bf16 v[78:81], v[222:225], v[194:197], v[78:81]
	ds_read_b128 v[158:161], v240 offset:7168
	v_mfma_f32_16x16x32_bf16 v[94:97], v[222:225], v[198:201], v[94:97]
	global_load_lds_dwordx4 v226, s[54:55] offset:3072
	v_mfma_f32_16x16x32_bf16 v[90:93], v[218:221], v[198:201], v[90:93]
	v_mfma_f32_16x16x32_bf16 v[86:89], v[214:217], v[198:201], v[86:89]
	v_mfma_f32_16x16x32_bf16 v[82:85], v[210:213], v[198:201], v[82:85]
	v_mfma_f32_16x16x32_bf16 v[98:101], v[210:213], v[202:205], v[98:101]
	s_add_i32 m0, s60, s63
	v_mfma_f32_16x16x32_bf16 v[102:105], v[214:217], v[202:205], v[102:105]
	global_load_lds_dwordx4 v230, s[56:57]
	v_mfma_f32_16x16x32_bf16 v[106:109], v[218:221], v[202:205], v[106:109]
	v_mfma_f32_16x16x32_bf16 v[110:113], v[222:225], v[202:205], v[110:113]
	v_mfma_f32_16x16x32_bf16 v[126:129], v[222:225], v[206:209], v[126:129]
	v_mfma_f32_16x16x32_bf16 v[122:125], v[218:221], v[206:209], v[122:125]
	v_mfma_f32_16x16x32_bf16 v[118:121], v[214:217], v[206:209], v[118:121]
	global_load_lds_dwordx4 v231, s[56:57] offset:1024
	v_mfma_f32_16x16x32_bf16 v[114:117], v[210:213], v[206:209], v[114:117]
	s_setprio 0
	s_add_i32 s60, s60, 0x6000
	s_cmp_eq_u32 s60, 0x12000
	s_cselect_b32 s60, 0, s60
	s_add_u32 s54, s54, s72
	s_addc_u32 s55, s55, 0
	s_add_u32 s56, s56, s73
	s_addc_u32 s57, s57, 0
	s_add_i32 s61, s61, 0x6000
	s_cmp_eq_u32 s61, 0x12000
	s_cselect_b32 s61, 0, s61
	s_branch .Lup_main

.Lup_nn_b:
	s_waitcnt lgkmcnt(0)
	v_add_u32_e32 v240, s61, v238
	v_add_u32_e32 v241, s61, v239
	s_setprio 1
	v_mfma_f32_16x16x32_bf16 v[2:5], v[162:165], v[130:133], 0
	v_mfma_f32_16x16x32_bf16 v[6:9], v[166:169], v[130:133], 0
	v_mfma_f32_16x16x32_bf16 v[10:13], v[170:173], v[130:133], 0
	v_mfma_f32_16x16x32_bf16 v[14:17], v[174:177], v[130:133], 0
	s_waitcnt vmcnt(14)
	s_barrier
	v_mfma_f32_16x16x32_bf16 v[30:33], v[174:177], v[134:137], 0
	s_add_i32 m0, s60, s62
	v_mfma_f32_16x16x32_bf16 v[26:29], v[170:173], v[134:137], 0
	global_load_lds_dwordx4 v226, s[54:55]
	v_mfma_f32_16x16x32_bf16 v[22:25], v[166:169], v[134:137], 0
	v_mfma_f32_16x16x32_bf16 v[18:21], v[162:165], v[134:137], 0
	v_mfma_f32_16x16x32_bf16 v[34:37], v[162:165], v[138:141], 0
	ds_read_b128 v[210:213], v241 offset:0
	v_mfma_f32_16x16x32_bf16 v[38:41], v[166:169], v[138:141], 0
	ds_read_b128 v[214:217], v241 offset:256
	v_mfma_f32_16x16x32_bf16 v[42:45], v[170:173], v[138:141], 0
	ds_read_b128 v[218:221], v241 offset:2048
	global_load_lds_dwordx4 v226, s[54:55] offset:1024
	v_mfma_f32_16x16x32_bf16 v[46:49], v[174:177], v[138:141], 0
	ds_read_b128 v[222:225], v241 offset:2304
	v_mfma_f32_16x16x32_bf16 v[62:65], v[174:177], v[142:145], 0
	ds_read_b128 v[178:181], v240 offset:0
	v_mfma_f32_16x16x32_bf16 v[58:61], v[170:173], v[142:145], 0
	ds_read_b128 v[182:185], v240 offset:1024
	v_mfma_f32_16x16x32_bf16 v[54:57], v[166:169], v[142:145], 0
	ds_read_b128 v[186:189], v240 offset:2048
	v_mfma_f32_16x16x32_bf16 v[50:53], v[162:165], v[142:145], 0
	ds_read_b128 v[190:193], v240 offset:3072
	global_load_lds_dwordx4 v226, s[54:55] offset:2048
	v_mfma_f32_16x16x32_bf16 v[66:69], v[162:165], v[146:149], 0
	ds_read_b128 v[194:197], v240 offset:4096
	v_mfma_f32_16x16x32_bf16 v[70:73], v[166:169], v[146:149], 0
	ds_read_b128 v[198:201], v240 offset:5120
	v_mfma_f32_16x16x32_bf16 v[74:77], v[170:173], v[146:149], 0
	ds_read_b128 v[202:205], v240 offset:6144
	v_mfma_f32_16x16x32_bf16 v[78:81], v[174:177], v[146:149], 0
	ds_read_b128 v[206:209], v240 offset:7168
	v_mfma_f32_16x16x32_bf16 v[94:97], v[174:177], v[150:153], 0
	global_load_lds_dwordx4 v226, s[54:55] offset:3072
	v_mfma_f32_16x16x32_bf16 v[90:93], v[170:173], v[150:153], 0
	v_mfma_f32_16x16x32_bf16 v[86:89], v[166:169], v[150:153], 0
	v_mfma_f32_16x16x32_bf16 v[82:85], v[162:165], v[150:153], 0
	v_mfma_f32_16x16x32_bf16 v[98:101], v[162:165], v[154:157], 0
	s_add_i32 m0, s60, s63
	v_mfma_f32_16x16x32_bf16 v[102:105], v[166:169], v[154:157], 0
	global_load_lds_dwordx4 v230, s[56:57]
	v_mfma_f32_16x16x32_bf16 v[106:109], v[170:173], v[154:157], 0
	v_mfma_f32_16x16x32_bf16 v[110:113], v[174:177], v[154:157], 0
	v_mfma_f32_16x16x32_bf16 v[126:129], v[174:177], v[158:161], 0
	v_mfma_f32_16x16x32_bf16 v[122:125], v[170:173], v[158:161], 0
	v_mfma_f32_16x16x32_bf16 v[118:121], v[166:169], v[158:161], 0
	global_load_lds_dwordx4 v231, s[56:57] offset:1024
	v_mfma_f32_16x16x32_bf16 v[114:117], v[162:165], v[158:161], 0
	s_setprio 0
	s_add_i32 s60, s60, 0x6000
	s_cmp_eq_u32 s60, 0x12000
	s_cselect_b32 s60, 0, s60
	s_add_u32 s54, s54, s72
	s_addc_u32 s55, s55, 0
	s_add_u32 s56, s56, s73
	s_addc_u32 s57, s57, 0
	s_add_i32 s61, s61, 0x6000
	s_cmp_eq_u32 s61, 0x12000
	s_cselect_b32 s61, 0, s61
	v_mbcnt_lo_u32_b32 v0, -1, 0
	v_lshlrev_b32_e32 v0, 4, v0
	s_lshl_b32 s26, s36, 1
	v_add_u32_e32 v0, s26, v0
	s_lshl_b32 s26, s41, 8
	s_add_i32 m0, s26, 0x13010
	s_mov_b64 exec, 0xffff
	global_load_lds_dwordx4 v0, s[82:83]
	s_mov_b64 exec, -1
	s_waitcnt lgkmcnt(0)
	v_add_u32_e32 v240, s61, v238
	v_add_u32_e32 v241, s61, v239
	s_setprio 1
	v_mfma_f32_16x16x32_bf16 v[2:5], v[210:213], v[178:181], v[2:5]
	v_mfma_f32_16x16x32_bf16 v[6:9], v[214:217], v[178:181], v[6:9]
	v_mfma_f32_16x16x32_bf16 v[10:13], v[218:221], v[178:181], v[10:13]
	v_mfma_f32_16x16x32_bf16 v[14:17], v[222:225], v[178:181], v[14:17]
	s_waitcnt vmcnt(14)
	s_barrier
	v_mfma_f32_16x16x32_bf16 v[30:33], v[222:225], v[182:185], v[30:33]
	s_add_i32 m0, s60, s62
	v_mfma_f32_16x16x32_bf16 v[26:29], v[218:221], v[182:185], v[26:29]
	global_load_lds_dwordx4 v226, s[54:55]
	v_mfma_f32_16x16x32_bf16 v[22:25], v[214:217], v[182:185], v[22:25]
	v_mfma_f32_16x16x32_bf16 v[18:21], v[210:213], v[182:185], v[18:21]
	v_mfma_f32_16x16x32_bf16 v[34:37], v[210:213], v[186:189], v[34:37]
	ds_read_b128 v[162:165], v241 offset:0
	v_mfma_f32_16x16x32_bf16 v[38:41], v[214:217], v[186:189], v[38:41]
	ds_read_b128 v[166:169], v241 offset:256
	v_mfma_f32_16x16x32_bf16 v[42:45], v[218:221], v[186:189], v[42:45]
	ds_read_b128 v[170:173], v241 offset:2048
	global_load_lds_dwordx4 v226, s[54:55] offset:1024
	v_mfma_f32_16x16x32_bf16 v[46:49], v[222:225], v[186:189], v[46:49]
	ds_read_b128 v[174:177], v241 offset:2304
	v_mfma_f32_16x16x32_bf16 v[62:65], v[222:225], v[190:193], v[62:65]
	ds_read_b128 v[130:133], v240 offset:0
	v_mfma_f32_16x16x32_bf16 v[58:61], v[218:221], v[190:193], v[58:61]
	ds_read_b128 v[134:137], v240 offset:1024
	v_mfma_f32_16x16x32_bf16 v[54:57], v[214:217], v[190:193], v[54:57]
	ds_read_b128 v[138:141], v240 offset:2048
	v_mfma_f32_16x16x32_bf16 v[50:53], v[210:213], v[190:193], v[50:53]
	ds_read_b128 v[142:145], v240 offset:3072
	global_load_lds_dwordx4 v226, s[54:55] offset:2048
	v_mfma_f32_16x16x32_bf16 v[66:69], v[210:213], v[194:197], v[66:69]
	ds_read_b128 v[146:149], v240 offset:4096
	v_mfma_f32_16x16x32_bf16 v[70:73], v[214:217], v[194:197], v[70:73]
	ds_read_b128 v[150:153], v240 offset:5120
	v_mfma_f32_16x16x32_bf16 v[74:77], v[218:221], v[194:197], v[74:77]
	ds_read_b128 v[154:157], v240 offset:6144
	v_mfma_f32_16x16x32_bf16 v[78:81], v[222:225], v[194:197], v[78:81]
	ds_read_b128 v[158:161], v240 offset:7168
	v_mfma_f32_16x16x32_bf16 v[94:97], v[222:225], v[198:201], v[94:97]
	global_load_lds_dwordx4 v226, s[54:55] offset:3072
	v_mfma_f32_16x16x32_bf16 v[90:93], v[218:221], v[198:201], v[90:93]
	v_mfma_f32_16x16x32_bf16 v[86:89], v[214:217], v[198:201], v[86:89]
	v_mfma_f32_16x16x32_bf16 v[82:85], v[210:213], v[198:201], v[82:85]
	v_mfma_f32_16x16x32_bf16 v[98:101], v[210:213], v[202:205], v[98:101]
	s_add_i32 m0, s60, s63
	v_mfma_f32_16x16x32_bf16 v[102:105], v[214:217], v[202:205], v[102:105]
	global_load_lds_dwordx4 v230, s[56:57]
	v_mfma_f32_16x16x32_bf16 v[106:109], v[218:221], v[202:205], v[106:109]
	v_mfma_f32_16x16x32_bf16 v[110:113], v[222:225], v[202:205], v[110:113]
	v_mfma_f32_16x16x32_bf16 v[126:129], v[222:225], v[206:209], v[126:129]
	v_mfma_f32_16x16x32_bf16 v[122:125], v[218:221], v[206:209], v[122:125]
	v_mfma_f32_16x16x32_bf16 v[118:121], v[214:217], v[206:209], v[118:121]
	global_load_lds_dwordx4 v231, s[56:57] offset:1024
	v_mfma_f32_16x16x32_bf16 v[114:117], v[210:213], v[206:209], v[114:117]
	s_setprio 0
	s_add_i32 s60, s60, 0x6000
	s_cmp_eq_u32 s60, 0x12000
	s_cselect_b32 s60, 0, s60
	s_add_u32 s54, s54, s72
	s_addc_u32 s55, s55, 0
	s_add_u32 s56, s56, s73
	s_addc_u32 s57, s57, 0
	s_add_i32 s61, s61, 0x6000
	s_cmp_eq_u32 s61, 0x12000
	s_cselect_b32 s61, 0, s61

.Lup_kloop:
	s_waitcnt lgkmcnt(0)
	v_add_u32_e32 v240, s61, v238
	v_add_u32_e32 v241, s61, v239
	s_setprio 1
	v_mfma_f32_16x16x32_bf16 v[2:5], v[162:165], v[130:133], v[2:5]
	v_mfma_f32_16x16x32_bf16 v[6:9], v[166:169], v[130:133], v[6:9]
	v_mfma_f32_16x16x32_bf16 v[10:13], v[170:173], v[130:133], v[10:13]
	v_mfma_f32_16x16x32_bf16 v[14:17], v[174:177], v[130:133], v[14:17]
	s_waitcnt vmcnt(6)
	s_barrier
	v_mfma_f32_16x16x32_bf16 v[30:33], v[174:177], v[134:137], v[30:33]
	s_add_i32 m0, s60, s62
	v_mfma_f32_16x16x32_bf16 v[26:29], v[170:173], v[134:137], v[26:29]
	global_load_lds_dwordx4 v226, s[54:55]
	v_mfma_f32_16x16x32_bf16 v[22:25], v[166:169], v[134:137], v[22:25]
	v_mfma_f32_16x16x32_bf16 v[18:21], v[162:165], v[134:137], v[18:21]
	v_mfma_f32_16x16x32_bf16 v[34:37], v[162:165], v[138:141], v[34:37]
	ds_read_b128 v[210:213], v241 offset:0
	v_mfma_f32_16x16x32_bf16 v[38:41], v[166:169], v[138:141], v[38:41]
	ds_read_b128 v[214:217], v241 offset:256
	v_mfma_f32_16x16x32_bf16 v[42:45], v[170:173], v[138:141], v[42:45]
	ds_read_b128 v[218:221], v241 offset:2048
	global_load_lds_dwordx4 v226, s[54:55] offset:1024
	v_mfma_f32_16x16x32_bf16 v[46:49], v[174:177], v[138:141], v[46:49]
	ds_read_b128 v[222:225], v241 offset:2304
	v_mfma_f32_16x16x32_bf16 v[62:65], v[174:177], v[142:145], v[62:65]
	ds_read_b128 v[178:181], v240 offset:0
	v_mfma_f32_16x16x32_bf16 v[58:61], v[170:173], v[142:145], v[58:61]
	ds_read_b128 v[182:185], v240 offset:1024
	v_mfma_f32_16x16x32_bf16 v[54:57], v[166:169], v[142:145], v[54:57]
	ds_read_b128 v[186:189], v240 offset:2048
	v_mfma_f32_16x16x32_bf16 v[50:53], v[162:165], v[142:145], v[50:53]
	ds_read_b128 v[190:193], v240 offset:3072
	global_load_lds_dwordx4 v226, s[54:55] offset:2048
	v_mfma_f32_16x16x32_bf16 v[66:69], v[162:165], v[146:149], v[66:69]
	ds_read_b128 v[194:197], v240 offset:4096
	v_mfma_f32_16x16x32_bf16 v[70:73], v[166:169], v[146:149], v[70:73]
	ds_read_b128 v[198:201], v240 offset:5120
	v_mfma_f32_16x16x32_bf16 v[74:77], v[170:173], v[146:149], v[74:77]
	ds_read_b128 v[202:205], v240 offset:6144
	v_mfma_f32_16x16x32_bf16 v[78:81], v[174:177], v[146:149], v[78:81]
	ds_read_b128 v[206:209], v240 offset:7168
	v_mfma_f32_16x16x32_bf16 v[94:97], v[174:177], v[150:153], v[94:97]
	global_load_lds_dwordx4 v226, s[54:55] offset:3072
	v_mfma_f32_16x16x32_bf16 v[90:93], v[170:173], v[150:153], v[90:93]
	v_mfma_f32_16x16x32_bf16 v[86:89], v[166:169], v[150:153], v[86:89]
	v_mfma_f32_16x16x32_bf16 v[82:85], v[162:165], v[150:153], v[82:85]
	v_mfma_f32_16x16x32_bf16 v[98:101], v[162:165], v[154:157], v[98:101]
	s_add_i32 m0, s60, s63
	v_mfma_f32_16x16x32_bf16 v[102:105], v[166:169], v[154:157], v[102:105]
	global_load_lds_dwordx4 v230, s[56:57]
	v_mfma_f32_16x16x32_bf16 v[106:109], v[170:173], v[154:157], v[106:109]
	v_mfma_f32_16x16x32_bf16 v[110:113], v[174:177], v[154:157], v[110:113]
	v_mfma_f32_16x16x32_bf16 v[126:129], v[174:177], v[158:161], v[126:129]
	v_mfma_f32_16x16x32_bf16 v[122:125], v[170:173], v[158:161], v[122:125]
	v_mfma_f32_16x16x32_bf16 v[118:121], v[166:169], v[158:161], v[118:121]
	global_load_lds_dwordx4 v231, s[56:57] offset:1024
	v_mfma_f32_16x16x32_bf16 v[114:117], v[162:165], v[158:161], v[114:117]
	s_setprio 0
	s_add_i32 s60, s60, 0x6000
	s_cmp_eq_u32 s60, 0x12000
	s_cselect_b32 s60, 0, s60
	s_add_u32 s54, s54, s72
	s_addc_u32 s55, s55, 0
	s_add_u32 s56, s56, s73
	s_addc_u32 s57, s57, 0
	s_add_i32 s61, s61, 0x6000
	s_cmp_eq_u32 s61, 0x12000
	s_cselect_b32 s61, 0, s61
	s_waitcnt lgkmcnt(0)
	v_add_u32_e32 v240, s61, v238
	v_add_u32_e32 v241, s61, v239
	s_setprio 1
	v_mfma_f32_16x16x32_bf16 v[2:5], v[210:213], v[178:181], v[2:5]
	v_mfma_f32_16x16x32_bf16 v[6:9], v[214:217], v[178:181], v[6:9]
	v_mfma_f32_16x16x32_bf16 v[10:13], v[218:221], v[178:181], v[10:13]
	v_mfma_f32_16x16x32_bf16 v[14:17], v[222:225], v[178:181], v[14:17]
	s_waitcnt vmcnt(6)
	s_barrier
	v_mfma_f32_16x16x32_bf16 v[30:33], v[222:225], v[182:185], v[30:33]
	s_add_i32 m0, s60, s62
	v_mfma_f32_16x16x32_bf16 v[26:29], v[218:221], v[182:185], v[26:29]
	global_load_lds_dwordx4 v226, s[54:55]
	v_mfma_f32_16x16x32_bf16 v[22:25], v[214:217], v[182:185], v[22:25]
	v_mfma_f32_16x16x32_bf16 v[18:21], v[210:213], v[182:185], v[18:21]
	v_mfma_f32_16x16x32_bf16 v[34:37], v[210:213], v[186:189], v[34:37]
	ds_read_b128 v[162:165], v241 offset:0
	v_mfma_f32_16x16x32_bf16 v[38:41], v[214:217], v[186:189], v[38:41]
	ds_read_b128 v[166:169], v241 offset:256
	v_mfma_f32_16x16x32_bf16 v[42:45], v[218:221], v[186:189], v[42:45]
	ds_read_b128 v[170:173], v241 offset:2048
	global_load_lds_dwordx4 v226, s[54:55] offset:1024
	v_mfma_f32_16x16x32_bf16 v[46:49], v[222:225], v[186:189], v[46:49]
	ds_read_b128 v[174:177], v241 offset:2304
	v_mfma_f32_16x16x32_bf16 v[62:65], v[222:225], v[190:193], v[62:65]
	ds_read_b128 v[130:133], v240 offset:0
	v_mfma_f32_16x16x32_bf16 v[58:61], v[218:221], v[190:193], v[58:61]
	ds_read_b128 v[134:137], v240 offset:1024
	v_mfma_f32_16x16x32_bf16 v[54:57], v[214:217], v[190:193], v[54:57]
	ds_read_b128 v[138:141], v240 offset:2048
	v_mfma_f32_16x16x32_bf16 v[50:53], v[210:213], v[190:193], v[50:53]
	ds_read_b128 v[142:145], v240 offset:3072
	global_load_lds_dwordx4 v226, s[54:55] offset:2048
	v_mfma_f32_16x16x32_bf16 v[66:69], v[210:213], v[194:197], v[66:69]
	ds_read_b128 v[146:149], v240 offset:4096
	v_mfma_f32_16x16x32_bf16 v[70:73], v[214:217], v[194:197], v[70:73]
	ds_read_b128 v[150:153], v240 offset:5120
	v_mfma_f32_16x16x32_bf16 v[74:77], v[218:221], v[194:197], v[74:77]
	ds_read_b128 v[154:157], v240 offset:6144
	v_mfma_f32_16x16x32_bf16 v[78:81], v[222:225], v[194:197], v[78:81]
	ds_read_b128 v[158:161], v240 offset:7168
	v_mfma_f32_16x16x32_bf16 v[94:97], v[222:225], v[198:201], v[94:97]
	global_load_lds_dwordx4 v226, s[54:55] offset:3072
	v_mfma_f32_16x16x32_bf16 v[90:93], v[218:221], v[198:201], v[90:93]
	v_mfma_f32_16x16x32_bf16 v[86:89], v[214:217], v[198:201], v[86:89]
	v_mfma_f32_16x16x32_bf16 v[82:85], v[210:213], v[198:201], v[82:85]
	v_mfma_f32_16x16x32_bf16 v[98:101], v[210:213], v[202:205], v[98:101]
	s_add_i32 m0, s60, s63
	v_mfma_f32_16x16x32_bf16 v[102:105], v[214:217], v[202:205], v[102:105]
	global_load_lds_dwordx4 v230, s[56:57]
	v_mfma_f32_16x16x32_bf16 v[106:109], v[218:221], v[202:205], v[106:109]
	v_mfma_f32_16x16x32_bf16 v[110:113], v[222:225], v[202:205], v[110:113]
	v_mfma_f32_16x16x32_bf16 v[126:129], v[222:225], v[206:209], v[126:129]
	v_mfma_f32_16x16x32_bf16 v[122:125], v[218:221], v[206:209], v[122:125]
	v_mfma_f32_16x16x32_bf16 v[118:121], v[214:217], v[206:209], v[118:121]
	global_load_lds_dwordx4 v231, s[56:57] offset:1024
	v_mfma_f32_16x16x32_bf16 v[114:117], v[210:213], v[206:209], v[114:117]
	s_setprio 0
	s_add_i32 s60, s60, 0x6000
	s_cmp_eq_u32 s60, 0x12000
	s_cselect_b32 s60, 0, s60
	s_add_u32 s54, s54, s72
	s_addc_u32 s55, s55, 0
	s_add_u32 s56, s56, s73
	s_addc_u32 s57, s57, 0
	s_add_i32 s61, s61, 0x6000
	s_cmp_eq_u32 s61, 0x12000
	s_cselect_b32 s61, 0, s61
	s_add_i32 s40, s40, -1
	s_cmp_lg_u32 s40, 0
	s_cbranch_scc1 .Lup_kloop
.Lup_kdone:
	s_cmp_eq_u32 s37, 0
	s_cbranch_scc1 .Lup_tail_last
	s_waitcnt lgkmcnt(0)
	v_add_u32_e32 v240, s61, v238
	v_add_u32_e32 v241, s61, v239
	s_setprio 1
	v_mfma_f32_16x16x32_bf16 v[2:5], v[162:165], v[130:133], v[2:5]
	v_mfma_f32_16x16x32_bf16 v[6:9], v[166:169], v[130:133], v[6:9]
	v_mfma_f32_16x16x32_bf16 v[10:13], v[170:173], v[130:133], v[10:13]
	v_mfma_f32_16x16x32_bf16 v[14:17], v[174:177], v[130:133], v[14:17]
	s_waitcnt vmcnt(6)
	s_barrier
	v_mfma_f32_16x16x32_bf16 v[30:33], v[174:177], v[134:137], v[30:33]
	s_add_i32 m0, s60, s62
	v_mfma_f32_16x16x32_bf16 v[26:29], v[170:173], v[134:137], v[26:29]
	global_load_lds_dwordx4 v226, s[54:55]
	v_mfma_f32_16x16x32_bf16 v[22:25], v[166:169], v[134:137], v[22:25]
	v_mfma_f32_16x16x32_bf16 v[18:21], v[162:165], v[134:137], v[18:21]
	v_mfma_f32_16x16x32_bf16 v[34:37], v[162:165], v[138:141], v[34:37]
	ds_read_b128 v[210:213], v241 offset:0
	v_mfma_f32_16x16x32_bf16 v[38:41], v[166:169], v[138:141], v[38:41]
	ds_read_b128 v[214:217], v241 offset:256
	v_mfma_f32_16x16x32_bf16 v[42:45], v[170:173], v[138:141], v[42:45]
	ds_read_b128 v[218:221], v241 offset:2048
	global_load_lds_dwordx4 v226, s[54:55] offset:1024
	v_mfma_f32_16x16x32_bf16 v[46:49], v[174:177], v[138:141], v[46:49]
	ds_read_b128 v[222:225], v241 offset:2304
	v_mfma_f32_16x16x32_bf16 v[62:65], v[174:177], v[142:145], v[62:65]
	ds_read_b128 v[178:181], v240 offset:0
	v_mfma_f32_16x16x32_bf16 v[58:61], v[170:173], v[142:145], v[58:61]
	ds_read_b128 v[182:185], v240 offset:1024
	v_mfma_f32_16x16x32_bf16 v[54:57], v[166:169], v[142:145], v[54:57]
	ds_read_b128 v[186:189], v240 offset:2048
	v_mfma_f32_16x16x32_bf16 v[50:53], v[162:165], v[142:145], v[50:53]
	ds_read_b128 v[190:193], v240 offset:3072
	global_load_lds_dwordx4 v226, s[54:55] offset:2048
	v_mfma_f32_16x16x32_bf16 v[66:69], v[162:165], v[146:149], v[66:69]
	ds_read_b128 v[194:197], v240 offset:4096
	v_mfma_f32_16x16x32_bf16 v[70:73], v[166:169], v[146:149], v[70:73]
	ds_read_b128 v[198:201], v240 offset:5120
	v_mfma_f32_16x16x32_bf16 v[74:77], v[170:173], v[146:149], v[74:77]
	ds_read_b128 v[202:205], v240 offset:6144
	v_mfma_f32_16x16x32_bf16 v[78:81], v[174:177], v[146:149], v[78:81]
	ds_read_b128 v[206:209], v240 offset:7168
	v_mfma_f32_16x16x32_bf16 v[94:97], v[174:177], v[150:153], v[94:97]
	global_load_lds_dwordx4 v226, s[54:55] offset:3072
	v_mfma_f32_16x16x32_bf16 v[90:93], v[170:173], v[150:153], v[90:93]
	v_mfma_f32_16x16x32_bf16 v[86:89], v[166:169], v[150:153], v[86:89]
	v_mfma_f32_16x16x32_bf16 v[82:85], v[162:165], v[150:153], v[82:85]
	v_mfma_f32_16x16x32_bf16 v[98:101], v[162:165], v[154:157], v[98:101]
	s_add_i32 m0, s60, s63
	v_mfma_f32_16x16x32_bf16 v[102:105], v[166:169], v[154:157], v[102:105]
	global_load_lds_dwordx4 v230, s[56:57]
	v_mfma_f32_16x16x32_bf16 v[106:109], v[170:173], v[154:157], v[106:109]
	v_mfma_f32_16x16x32_bf16 v[110:113], v[174:177], v[154:157], v[110:113]
	v_mfma_f32_16x16x32_bf16 v[126:129], v[174:177], v[158:161], v[126:129]
	v_mfma_f32_16x16x32_bf16 v[122:125], v[170:173], v[158:161], v[122:125]
	v_mfma_f32_16x16x32_bf16 v[118:121], v[166:169], v[158:161], v[118:121]
	global_load_lds_dwordx4 v231, s[56:57] offset:1024
	v_mfma_f32_16x16x32_bf16 v[114:117], v[162:165], v[158:161], v[114:117]
	s_setprio 0
	s_add_i32 s60, s60, 0x6000
	s_cmp_eq_u32 s60, 0x12000
	s_cselect_b32 s60, 0, s60
	s_add_u32 s54, s54, s72
	s_addc_u32 s55, s55, 0
	s_add_u32 s56, s56, s73
	s_addc_u32 s57, s57, 0
	s_add_i32 s61, s61, 0x6000
	s_cmp_eq_u32 s61, 0x12000
	s_cselect_b32 s61, 0, s61
	v_mov_b32_e32 v226, v232
	v_mov_b32_e32 v230, v236
	v_mov_b32_e32 v231, v237
	s_mov_b64 s[54:55], s[48:49]
	s_mov_b64 s[56:57], s[50:51]
	s_waitcnt lgkmcnt(0)
	v_add_u32_e32 v240, s61, v238
	v_add_u32_e32 v241, s61, v239
	s_setprio 1
	v_mfma_f32_16x16x32_bf16 v[2:5], v[210:213], v[178:181], v[2:5]
	v_mfma_f32_16x16x32_bf16 v[6:9], v[214:217], v[178:181], v[6:9]
	v_mfma_f32_16x16x32_bf16 v[10:13], v[218:221], v[178:181], v[10:13]
	v_mfma_f32_16x16x32_bf16 v[14:17], v[222:225], v[178:181], v[14:17]
	s_waitcnt vmcnt(6)
	s_barrier
	v_mfma_f32_16x16x32_bf16 v[30:33], v[222:225], v[182:185], v[30:33]
	s_add_i32 m0, s60, s62
	v_mfma_f32_16x16x32_bf16 v[26:29], v[218:221], v[182:185], v[26:29]
	global_load_lds_dwordx4 v226, s[54:55]
	v_mfma_f32_16x16x32_bf16 v[22:25], v[214:217], v[182:185], v[22:25]
	v_mfma_f32_16x16x32_bf16 v[18:21], v[210:213], v[182:185], v[18:21]
	v_mfma_f32_16x16x32_bf16 v[34:37], v[210:213], v[186:189], v[34:37]
	ds_read_b128 v[162:165], v241 offset:0
	v_mfma_f32_16x16x32_bf16 v[38:41], v[214:217], v[186:189], v[38:41]
	ds_read_b128 v[166:169], v241 offset:256
	v_mfma_f32_16x16x32_bf16 v[42:45], v[218:221], v[186:189], v[42:45]
	ds_read_b128 v[170:173], v241 offset:2048
	global_load_lds_dwordx4 v226, s[54:55] offset:1024
	v_mfma_f32_16x16x32_bf16 v[46:49], v[222:225], v[186:189], v[46:49]
	ds_read_b128 v[174:177], v241 offset:2304
	v_mfma_f32_16x16x32_bf16 v[62:65], v[222:225], v[190:193], v[62:65]
	ds_read_b128 v[130:133], v240 offset:0
	v_mfma_f32_16x16x32_bf16 v[58:61], v[218:221], v[190:193], v[58:61]
	ds_read_b128 v[134:137], v240 offset:1024
	v_mfma_f32_16x16x32_bf16 v[54:57], v[214:217], v[190:193], v[54:57]
	ds_read_b128 v[138:141], v240 offset:2048
	v_mfma_f32_16x16x32_bf16 v[50:53], v[210:213], v[190:193], v[50:53]
	ds_read_b128 v[142:145], v240 offset:3072
	global_load_lds_dwordx4 v226, s[54:55] offset:2048
	v_mfma_f32_16x16x32_bf16 v[66:69], v[210:213], v[194:197], v[66:69]
	ds_read_b128 v[146:149], v240 offset:4096
	v_mfma_f32_16x16x32_bf16 v[70:73], v[214:217], v[194:197], v[70:73]
	ds_read_b128 v[150:153], v240 offset:5120
	v_mfma_f32_16x16x32_bf16 v[74:77], v[218:221], v[194:197], v[74:77]
	ds_read_b128 v[154:157], v240 offset:6144
	v_mfma_f32_16x16x32_bf16 v[78:81], v[222:225], v[194:197], v[78:81]
	ds_read_b128 v[158:161], v240 offset:7168
	v_mfma_f32_16x16x32_bf16 v[94:97], v[222:225], v[198:201], v[94:97]
	global_load_lds_dwordx4 v226, s[54:55] offset:3072
	v_mfma_f32_16x16x32_bf16 v[90:93], v[218:221], v[198:201], v[90:93]
	v_mfma_f32_16x16x32_bf16 v[86:89], v[214:217], v[198:201], v[86:89]
	v_mfma_f32_16x16x32_bf16 v[82:85], v[210:213], v[198:201], v[82:85]
	v_mfma_f32_16x16x32_bf16 v[98:101], v[210:213], v[202:205], v[98:101]
	s_add_i32 m0, s60, s63
	v_mfma_f32_16x16x32_bf16 v[102:105], v[214:217], v[202:205], v[102:105]
	global_load_lds_dwordx4 v230, s[56:57]
	v_mfma_f32_16x16x32_bf16 v[106:109], v[218:221], v[202:205], v[106:109]
	v_mfma_f32_16x16x32_bf16 v[110:113], v[222:225], v[202:205], v[110:113]
	v_mfma_f32_16x16x32_bf16 v[126:129], v[222:225], v[206:209], v[126:129]
	v_mfma_f32_16x16x32_bf16 v[122:125], v[218:221], v[206:209], v[122:125]
	v_mfma_f32_16x16x32_bf16 v[118:121], v[214:217], v[206:209], v[118:121]
	global_load_lds_dwordx4 v231, s[56:57] offset:1024
	v_mfma_f32_16x16x32_bf16 v[114:117], v[210:213], v[206:209], v[114:117]
	s_setprio 0
	s_add_i32 s60, s60, 0x6000
	s_cmp_eq_u32 s60, 0x12000
	s_cselect_b32 s60, 0, s60
	s_add_u32 s54, s54, s72
	s_addc_u32 s55, s55, 0
	s_add_u32 s56, s56, s73
	s_addc_u32 s57, s57, 0
	s_add_i32 s61, s61, 0x6000
	s_cmp_eq_u32 s61, 0x12000
	s_cselect_b32 s61, 0, s61
	s_waitcnt lgkmcnt(0)
	v_add_u32_e32 v240, s61, v238
	v_add_u32_e32 v241, s61, v239
	s_setprio 1
	v_mfma_f32_16x16x32_bf16 v[2:5], v[162:165], v[130:133], v[2:5]
	v_mfma_f32_16x16x32_bf16 v[6:9], v[166:169], v[130:133], v[6:9]
	v_mfma_f32_16x16x32_bf16 v[10:13], v[170:173], v[130:133], v[10:13]
	v_mfma_f32_16x16x32_bf16 v[14:17], v[174:177], v[130:133], v[14:17]
	s_waitcnt vmcnt(6)
	s_barrier
	v_mfma_f32_16x16x32_bf16 v[30:33], v[174:177], v[134:137], v[30:33]
	s_add_i32 m0, s60, s62
	v_mfma_f32_16x16x32_bf16 v[26:29], v[170:173], v[134:137], v[26:29]
	global_load_lds_dwordx4 v226, s[54:55]
	v_mfma_f32_16x16x32_bf16 v[22:25], v[166:169], v[134:137], v[22:25]
	v_mfma_f32_16x16x32_bf16 v[18:21], v[162:165], v[134:137], v[18:21]
	v_mfma_f32_16x16x32_bf16 v[34:37], v[162:165], v[138:141], v[34:37]
	ds_read_b128 v[210:213], v241 offset:0
	v_mfma_f32_16x16x32_bf16 v[38:41], v[166:169], v[138:141], v[38:41]
	ds_read_b128 v[214:217], v241 offset:256
	v_mfma_f32_16x16x32_bf16 v[42:45], v[170:173], v[138:141], v[42:45]
	ds_read_b128 v[218:221], v241 offset:2048
	global_load_lds_dwordx4 v226, s[54:55] offset:1024
	v_mfma_f32_16x16x32_bf16 v[46:49], v[174:177], v[138:141], v[46:49]
	ds_read_b128 v[222:225], v241 offset:2304
	v_mfma_f32_16x16x32_bf16 v[62:65], v[174:177], v[142:145], v[62:65]
	ds_read_b128 v[178:181], v240 offset:0
	v_mfma_f32_16x16x32_bf16 v[58:61], v[170:173], v[142:145], v[58:61]
	ds_read_b128 v[182:185], v240 offset:1024
	v_mfma_f32_16x16x32_bf16 v[54:57], v[166:169], v[142:145], v[54:57]
	ds_read_b128 v[186:189], v240 offset:2048
	v_mfma_f32_16x16x32_bf16 v[50:53], v[162:165], v[142:145], v[50:53]
	ds_read_b128 v[190:193], v240 offset:3072
	global_load_lds_dwordx4 v226, s[54:55] offset:2048
	v_mfma_f32_16x16x32_bf16 v[66:69], v[162:165], v[146:149], v[66:69]
	ds_read_b128 v[194:197], v240 offset:4096
	v_mfma_f32_16x16x32_bf16 v[70:73], v[166:169], v[146:149], v[70:73]
	ds_read_b128 v[198:201], v240 offset:5120
	v_mfma_f32_16x16x32_bf16 v[74:77], v[170:173], v[146:149], v[74:77]
	ds_read_b128 v[202:205], v240 offset:6144
	v_mfma_f32_16x16x32_bf16 v[78:81], v[174:177], v[146:149], v[78:81]
	ds_read_b128 v[206:209], v240 offset:7168
	v_mfma_f32_16x16x32_bf16 v[94:97], v[174:177], v[150:153], v[94:97]
	global_load_lds_dwordx4 v226, s[54:55] offset:3072
	v_mfma_f32_16x16x32_bf16 v[90:93], v[170:173], v[150:153], v[90:93]
	v_mfma_f32_16x16x32_bf16 v[86:89], v[166:169], v[150:153], v[86:89]
	v_mfma_f32_16x16x32_bf16 v[82:85], v[162:165], v[150:153], v[82:85]
	v_mfma_f32_16x16x32_bf16 v[98:101], v[162:165], v[154:157], v[98:101]
	s_add_i32 m0, s60, s63
	v_mfma_f32_16x16x32_bf16 v[102:105], v[166:169], v[154:157], v[102:105]
	global_load_lds_dwordx4 v230, s[56:57]
	v_mfma_f32_16x16x32_bf16 v[106:109], v[170:173], v[154:157], v[106:109]
	v_mfma_f32_16x16x32_bf16 v[110:113], v[174:177], v[154:157], v[110:113]
	v_mfma_f32_16x16x32_bf16 v[126:129], v[174:177], v[158:161], v[126:129]
	v_mfma_f32_16x16x32_bf16 v[122:125], v[170:173], v[158:161], v[122:125]
	v_mfma_f32_16x16x32_bf16 v[118:121], v[166:169], v[158:161], v[118:121]
	global_load_lds_dwordx4 v231, s[56:57] offset:1024
	v_mfma_f32_16x16x32_bf16 v[114:117], v[162:165], v[158:161], v[114:117]
	s_setprio 0
	s_add_i32 s60, s60, 0x6000
	s_cmp_eq_u32 s60, 0x12000
	s_cselect_b32 s60, 0, s60
	s_add_u32 s54, s54, s72
	s_addc_u32 s55, s55, 0
	s_add_u32 s56, s56, s73
	s_addc_u32 s57, s57, 0
	s_add_i32 s61, s61, 0x6000
	s_cmp_eq_u32 s61, 0x12000
	s_cselect_b32 s61, 0, s61
	s_waitcnt lgkmcnt(0)
	v_add_u32_e32 v240, s61, v238
	v_add_u32_e32 v241, s61, v239
	s_setprio 1
	v_mfma_f32_16x16x32_bf16 v[2:5], v[210:213], v[178:181], v[2:5]
	v_mfma_f32_16x16x32_bf16 v[6:9], v[214:217], v[178:181], v[6:9]
	v_mfma_f32_16x16x32_bf16 v[10:13], v[218:221], v[178:181], v[10:13]
	v_mfma_f32_16x16x32_bf16 v[14:17], v[222:225], v[178:181], v[14:17]
	s_waitcnt vmcnt(6)
	s_barrier
	v_mfma_f32_16x16x32_bf16 v[30:33], v[222:225], v[182:185], v[30:33]
	s_add_i32 m0, s60, s62
	v_mfma_f32_16x16x32_bf16 v[26:29], v[218:221], v[182:185], v[26:29]
	global_load_lds_dwordx4 v226, s[54:55]
	v_mfma_f32_16x16x32_bf16 v[22:25], v[214:217], v[182:185], v[22:25]
	v_mfma_f32_16x16x32_bf16 v[18:21], v[210:213], v[182:185], v[18:21]
	v_mfma_f32_16x16x32_bf16 v[34:37], v[210:213], v[186:189], v[34:37]
	ds_read_b128 v[162:165], v241 offset:0
	v_mfma_f32_16x16x32_bf16 v[38:41], v[214:217], v[186:189], v[38:41]
	ds_read_b128 v[166:169], v241 offset:256
	v_mfma_f32_16x16x32_bf16 v[42:45], v[218:221], v[186:189], v[42:45]
	ds_read_b128 v[170:173], v241 offset:2048
	global_load_lds_dwordx4 v226, s[54:55] offset:1024
	v_mfma_f32_16x16x32_bf16 v[46:49], v[222:225], v[186:189], v[46:49]
	ds_read_b128 v[174:177], v241 offset:2304
	v_mfma_f32_16x16x32_bf16 v[62:65], v[222:225], v[190:193], v[62:65]
	ds_read_b128 v[130:133], v240 offset:0
	v_mfma_f32_16x16x32_bf16 v[58:61], v[218:221], v[190:193], v[58:61]
	ds_read_b128 v[134:137], v240 offset:1024
	v_mfma_f32_16x16x32_bf16 v[54:57], v[214:217], v[190:193], v[54:57]
	ds_read_b128 v[138:141], v240 offset:2048
	v_mfma_f32_16x16x32_bf16 v[50:53], v[210:213], v[190:193], v[50:53]
	ds_read_b128 v[142:145], v240 offset:3072
	global_load_lds_dwordx4 v226, s[54:55] offset:2048
	v_mfma_f32_16x16x32_bf16 v[66:69], v[210:213], v[194:197], v[66:69]
	ds_read_b128 v[146:149], v240 offset:4096
	v_mfma_f32_16x16x32_bf16 v[70:73], v[214:217], v[194:197], v[70:73]
	ds_read_b128 v[150:153], v240 offset:5120
	v_mfma_f32_16x16x32_bf16 v[74:77], v[218:221], v[194:197], v[74:77]
	ds_read_b128 v[154:157], v240 offset:6144
	v_mfma_f32_16x16x32_bf16 v[78:81], v[222:225], v[194:197], v[78:81]
	ds_read_b128 v[158:161], v240 offset:7168
	v_mfma_f32_16x16x32_bf16 v[94:97], v[222:225], v[198:201], v[94:97]
	global_load_lds_dwordx4 v226, s[54:55] offset:3072
	v_mfma_f32_16x16x32_bf16 v[90:93], v[218:221], v[198:201], v[90:93]
	v_mfma_f32_16x16x32_bf16 v[86:89], v[214:217], v[198:201], v[86:89]
	v_mfma_f32_16x16x32_bf16 v[82:85], v[210:213], v[198:201], v[82:85]
	v_mfma_f32_16x16x32_bf16 v[98:101], v[210:213], v[202:205], v[98:101]
	s_add_i32 m0, s60, s63
	v_mfma_f32_16x16x32_bf16 v[102:105], v[214:217], v[202:205], v[102:105]
	global_load_lds_dwordx4 v230, s[56:57]
	v_mfma_f32_16x16x32_bf16 v[106:109], v[218:221], v[202:205], v[106:109]
	v_mfma_f32_16x16x32_bf16 v[110:113], v[222:225], v[202:205], v[110:113]
	v_mfma_f32_16x16x32_bf16 v[126:129], v[222:225], v[206:209], v[126:129]
	v_mfma_f32_16x16x32_bf16 v[122:125], v[218:221], v[206:209], v[122:125]
	v_mfma_f32_16x16x32_bf16 v[118:121], v[214:217], v[206:209], v[118:121]
	global_load_lds_dwordx4 v231, s[56:57] offset:1024
	v_mfma_f32_16x16x32_bf16 v[114:117], v[210:213], v[206:209], v[114:117]
	s_setprio 0
	s_add_i32 s60, s60, 0x6000
	s_cmp_eq_u32 s60, 0x12000
	s_cselect_b32 s60, 0, s60
	s_add_u32 s54, s54, s72
	s_addc_u32 s55, s55, 0
	s_add_u32 s56, s56, s73
	s_addc_u32 s57, s57, 0
	s_add_i32 s61, s61, 0x6000
	s_cmp_eq_u32 s61, 0x12000
	s_cselect_b32 s61, 0, s61
	s_and_b32 s39, s35, 0xfff
	s_lshr_b32 s21, s36, 7
	s_waitcnt vmcnt(18)
	v_mbcnt_lo_u32_b32 v217, -1, 0
	v_mbcnt_hi_u32_b32 v217, -1, v217
	v_lshlrev_b32_e32 v217, 5, v217
	s_lshl_b32 s26, s43, 11
	v_add_u32_e32 v248, s26, v217
	s_add_i32 s26, s26, 0x12010
	v_add_u32_e32 v217, s26, v217
	s_cmp_eq_u32 s42, 0
	s_cbranch_scc0 .Lup_en_nowr
	ds_write_b128 v217, v[114:117]
	ds_write_b128 v217, v[118:121] offset:16
	s_branch .Lup_en_wrd

.Lup_tail_last:
	s_waitcnt lgkmcnt(0)
	v_add_u32_e32 v240, s61, v238
	v_add_u32_e32 v241, s61, v239
	s_setprio 1
	v_mfma_f32_16x16x32_bf16 v[2:5], v[162:165], v[130:133], v[2:5]
	v_mfma_f32_16x16x32_bf16 v[6:9], v[166:169], v[130:133], v[6:9]
	v_mfma_f32_16x16x32_bf16 v[10:13], v[170:173], v[130:133], v[10:13]
	v_mfma_f32_16x16x32_bf16 v[14:17], v[174:177], v[130:133], v[14:17]
	s_waitcnt vmcnt(6)
	s_barrier
	v_mfma_f32_16x16x32_bf16 v[30:33], v[174:177], v[134:137], v[30:33]
	s_add_i32 m0, s60, s62
	v_mfma_f32_16x16x32_bf16 v[26:29], v[170:173], v[134:137], v[26:29]
	global_load_lds_dwordx4 v226, s[54:55]
	v_mfma_f32_16x16x32_bf16 v[22:25], v[166:169], v[134:137], v[22:25]
	v_mfma_f32_16x16x32_bf16 v[18:21], v[162:165], v[134:137], v[18:21]
	v_mfma_f32_16x16x32_bf16 v[34:37], v[162:165], v[138:141], v[34:37]
	ds_read_b128 v[210:213], v241 offset:0
	v_mfma_f32_16x16x32_bf16 v[38:41], v[166:169], v[138:141], v[38:41]
	ds_read_b128 v[214:217], v241 offset:256
	v_mfma_f32_16x16x32_bf16 v[42:45], v[170:173], v[138:141], v[42:45]
	ds_read_b128 v[218:221], v241 offset:2048
	global_load_lds_dwordx4 v226, s[54:55] offset:1024
	v_mfma_f32_16x16x32_bf16 v[46:49], v[174:177], v[138:141], v[46:49]
	ds_read_b128 v[222:225], v241 offset:2304
	v_mfma_f32_16x16x32_bf16 v[62:65], v[174:177], v[142:145], v[62:65]
	ds_read_b128 v[178:181], v240 offset:0
	v_mfma_f32_16x16x32_bf16 v[58:61], v[170:173], v[142:145], v[58:61]
	ds_read_b128 v[182:185], v240 offset:1024
	v_mfma_f32_16x16x32_bf16 v[54:57], v[166:169], v[142:145], v[54:57]
	ds_read_b128 v[186:189], v240 offset:2048
	v_mfma_f32_16x16x32_bf16 v[50:53], v[162:165], v[142:145], v[50:53]
	ds_read_b128 v[190:193], v240 offset:3072
	global_load_lds_dwordx4 v226, s[54:55] offset:2048
	v_mfma_f32_16x16x32_bf16 v[66:69], v[162:165], v[146:149], v[66:69]
	ds_read_b128 v[194:197], v240 offset:4096
	v_mfma_f32_16x16x32_bf16 v[70:73], v[166:169], v[146:149], v[70:73]
	ds_read_b128 v[198:201], v240 offset:5120
	v_mfma_f32_16x16x32_bf16 v[74:77], v[170:173], v[146:149], v[74:77]
	ds_read_b128 v[202:205], v240 offset:6144
	v_mfma_f32_16x16x32_bf16 v[78:81], v[174:177], v[146:149], v[78:81]
	ds_read_b128 v[206:209], v240 offset:7168
	v_mfma_f32_16x16x32_bf16 v[94:97], v[174:177], v[150:153], v[94:97]
	global_load_lds_dwordx4 v226, s[54:55] offset:3072
	v_mfma_f32_16x16x32_bf16 v[90:93], v[170:173], v[150:153], v[90:93]
	v_mfma_f32_16x16x32_bf16 v[86:89], v[166:169], v[150:153], v[86:89]
	v_mfma_f32_16x16x32_bf16 v[82:85], v[162:165], v[150:153], v[82:85]
	v_mfma_f32_16x16x32_bf16 v[98:101], v[162:165], v[154:157], v[98:101]
	s_add_i32 m0, s60, s63
	v_mfma_f32_16x16x32_bf16 v[102:105], v[166:169], v[154:157], v[102:105]
	global_load_lds_dwordx4 v230, s[56:57]
	v_mfma_f32_16x16x32_bf16 v[106:109], v[170:173], v[154:157], v[106:109]
	v_mfma_f32_16x16x32_bf16 v[110:113], v[174:177], v[154:157], v[110:113]
	v_mfma_f32_16x16x32_bf16 v[126:129], v[174:177], v[158:161], v[126:129]
	v_mfma_f32_16x16x32_bf16 v[122:125], v[170:173], v[158:161], v[122:125]
	v_mfma_f32_16x16x32_bf16 v[118:121], v[166:169], v[158:161], v[118:121]
	global_load_lds_dwordx4 v231, s[56:57] offset:1024
	v_mfma_f32_16x16x32_bf16 v[114:117], v[162:165], v[158:161], v[114:117]
	s_setprio 0
	s_add_i32 s60, s60, 0x6000
	s_cmp_eq_u32 s60, 0x12000
	s_cselect_b32 s60, 0, s60
	s_add_u32 s54, s54, s72
	s_addc_u32 s55, s55, 0
	s_add_u32 s56, s56, s73
	s_addc_u32 s57, s57, 0
	s_add_i32 s61, s61, 0x6000
	s_cmp_eq_u32 s61, 0x12000
	s_cselect_b32 s61, 0, s61
	s_waitcnt lgkmcnt(0)
	v_add_u32_e32 v240, s61, v238
	v_add_u32_e32 v241, s61, v239
	s_setprio 1
	v_mfma_f32_16x16x32_bf16 v[2:5], v[210:213], v[178:181], v[2:5]
	v_mfma_f32_16x16x32_bf16 v[6:9], v[214:217], v[178:181], v[6:9]
	v_mfma_f32_16x16x32_bf16 v[10:13], v[218:221], v[178:181], v[10:13]
	v_mfma_f32_16x16x32_bf16 v[14:17], v[222:225], v[178:181], v[14:17]
	s_waitcnt vmcnt(6)
	s_barrier
	v_mfma_f32_16x16x32_bf16 v[30:33], v[222:225], v[182:185], v[30:33]
	v_mfma_f32_16x16x32_bf16 v[26:29], v[218:221], v[182:185], v[26:29]
	v_mfma_f32_16x16x32_bf16 v[22:25], v[214:217], v[182:185], v[22:25]
	v_mfma_f32_16x16x32_bf16 v[18:21], v[210:213], v[182:185], v[18:21]
	v_mfma_f32_16x16x32_bf16 v[34:37], v[210:213], v[186:189], v[34:37]
	ds_read_b128 v[162:165], v241 offset:0
	v_mfma_f32_16x16x32_bf16 v[38:41], v[214:217], v[186:189], v[38:41]
	ds_read_b128 v[166:169], v241 offset:256
	v_mfma_f32_16x16x32_bf16 v[42:45], v[218:221], v[186:189], v[42:45]
	ds_read_b128 v[170:173], v241 offset:2048
	v_mfma_f32_16x16x32_bf16 v[46:49], v[222:225], v[186:189], v[46:49]
	ds_read_b128 v[174:177], v241 offset:2304
	v_mfma_f32_16x16x32_bf16 v[62:65], v[222:225], v[190:193], v[62:65]
	ds_read_b128 v[130:133], v240 offset:0
	v_mfma_f32_16x16x32_bf16 v[58:61], v[218:221], v[190:193], v[58:61]
	ds_read_b128 v[134:137], v240 offset:1024
	v_mfma_f32_16x16x32_bf16 v[54:57], v[214:217], v[190:193], v[54:57]
	ds_read_b128 v[138:141], v240 offset:2048
	v_mfma_f32_16x16x32_bf16 v[50:53], v[210:213], v[190:193], v[50:53]
	ds_read_b128 v[142:145], v240 offset:3072
	v_mfma_f32_16x16x32_bf16 v[66:69], v[210:213], v[194:197], v[66:69]
	ds_read_b128 v[146:149], v240 offset:4096
	v_mfma_f32_16x16x32_bf16 v[70:73], v[214:217], v[194:197], v[70:73]
	ds_read_b128 v[150:153], v240 offset:5120
	v_mfma_f32_16x16x32_bf16 v[74:77], v[218:221], v[194:197], v[74:77]
	ds_read_b128 v[154:157], v240 offset:6144
	v_mfma_f32_16x16x32_bf16 v[78:81], v[222:225], v[194:197], v[78:81]
	ds_read_b128 v[158:161], v240 offset:7168
	v_mfma_f32_16x16x32_bf16 v[94:97], v[222:225], v[198:201], v[94:97]
	v_mfma_f32_16x16x32_bf16 v[90:93], v[218:221], v[198:201], v[90:93]
	v_mfma_f32_16x16x32_bf16 v[86:89], v[214:217], v[198:201], v[86:89]
	v_mfma_f32_16x16x32_bf16 v[82:85], v[210:213], v[198:201], v[82:85]
	v_mfma_f32_16x16x32_bf16 v[98:101], v[210:213], v[202:205], v[98:101]
	v_mfma_f32_16x16x32_bf16 v[102:105], v[214:217], v[202:205], v[102:105]
	v_mfma_f32_16x16x32_bf16 v[106:109], v[218:221], v[202:205], v[106:109]
	v_mfma_f32_16x16x32_bf16 v[110:113], v[222:225], v[202:205], v[110:113]
	v_mfma_f32_16x16x32_bf16 v[126:129], v[222:225], v[206:209], v[126:129]
	v_mfma_f32_16x16x32_bf16 v[122:125], v[218:221], v[206:209], v[122:125]
	v_mfma_f32_16x16x32_bf16 v[118:121], v[214:217], v[206:209], v[118:121]
	v_mfma_f32_16x16x32_bf16 v[114:117], v[210:213], v[206:209], v[114:117]
	s_setprio 0
	s_add_i32 s61, s61, 0x6000
	s_cmp_eq_u32 s61, 0x12000
	s_cselect_b32 s61, 0, s61
	s_waitcnt lgkmcnt(0)
	v_add_u32_e32 v240, s61, v238
	v_add_u32_e32 v241, s61, v239
	s_setprio 1
	v_mfma_f32_16x16x32_bf16 v[2:5], v[162:165], v[130:133], v[2:5]
	v_mfma_f32_16x16x32_bf16 v[6:9], v[166:169], v[130:133], v[6:9]
	v_mfma_f32_16x16x32_bf16 v[10:13], v[170:173], v[130:133], v[10:13]
	v_mfma_f32_16x16x32_bf16 v[14:17], v[174:177], v[130:133], v[14:17]
	s_waitcnt vmcnt(0)
	s_barrier
	v_mfma_f32_16x16x32_bf16 v[30:33], v[174:177], v[134:137], v[30:33]
	v_mfma_f32_16x16x32_bf16 v[26:29], v[170:173], v[134:137], v[26:29]
	v_mfma_f32_16x16x32_bf16 v[22:25], v[166:169], v[134:137], v[22:25]
	v_mfma_f32_16x16x32_bf16 v[18:21], v[162:165], v[134:137], v[18:21]
	v_mfma_f32_16x16x32_bf16 v[34:37], v[162:165], v[138:141], v[34:37]
	ds_read_b128 v[210:213], v241 offset:0
	v_mfma_f32_16x16x32_bf16 v[38:41], v[166:169], v[138:141], v[38:41]
	ds_read_b128 v[214:217], v241 offset:256
	v_mfma_f32_16x16x32_bf16 v[42:45], v[170:173], v[138:141], v[42:45]
	ds_read_b128 v[218:221], v241 offset:2048
	v_mfma_f32_16x16x32_bf16 v[46:49], v[174:177], v[138:141], v[46:49]
	ds_read_b128 v[222:225], v241 offset:2304
	v_mfma_f32_16x16x32_bf16 v[62:65], v[174:177], v[142:145], v[62:65]
	ds_read_b128 v[178:181], v240 offset:0
	v_mfma_f32_16x16x32_bf16 v[58:61], v[170:173], v[142:145], v[58:61]
	ds_read_b128 v[182:185], v240 offset:1024
	v_mfma_f32_16x16x32_bf16 v[54:57], v[166:169], v[142:145], v[54:57]
	ds_read_b128 v[186:189], v240 offset:2048
	v_mfma_f32_16x16x32_bf16 v[50:53], v[162:165], v[142:145], v[50:53]
	ds_read_b128 v[190:193], v240 offset:3072
	v_mfma_f32_16x16x32_bf16 v[66:69], v[162:165], v[146:149], v[66:69]
	ds_read_b128 v[194:197], v240 offset:4096
	v_mfma_f32_16x16x32_bf16 v[70:73], v[166:169], v[146:149], v[70:73]
	ds_read_b128 v[198:201], v240 offset:5120
	v_mfma_f32_16x16x32_bf16 v[74:77], v[170:173], v[146:149], v[74:77]
	ds_read_b128 v[202:205], v240 offset:6144
	v_mfma_f32_16x16x32_bf16 v[78:81], v[174:177], v[146:149], v[78:81]
	ds_read_b128 v[206:209], v240 offset:7168
	v_mfma_f32_16x16x32_bf16 v[94:97], v[174:177], v[150:153], v[94:97]
	v_mfma_f32_16x16x32_bf16 v[90:93], v[170:173], v[150:153], v[90:93]
	v_mfma_f32_16x16x32_bf16 v[86:89], v[166:169], v[150:153], v[86:89]
	v_mfma_f32_16x16x32_bf16 v[82:85], v[162:165], v[150:153], v[82:85]
	v_mfma_f32_16x16x32_bf16 v[98:101], v[162:165], v[154:157], v[98:101]
	v_mfma_f32_16x16x32_bf16 v[102:105], v[166:169], v[154:157], v[102:105]
	v_mfma_f32_16x16x32_bf16 v[106:109], v[170:173], v[154:157], v[106:109]
	v_mfma_f32_16x16x32_bf16 v[110:113], v[174:177], v[154:157], v[110:113]
	v_mfma_f32_16x16x32_bf16 v[126:129], v[174:177], v[158:161], v[126:129]
	v_mfma_f32_16x16x32_bf16 v[122:125], v[170:173], v[158:161], v[122:125]
	v_mfma_f32_16x16x32_bf16 v[118:121], v[166:169], v[158:161], v[118:121]
	v_mfma_f32_16x16x32_bf16 v[114:117], v[162:165], v[158:161], v[114:117]
	s_setprio 0
	s_add_i32 s61, s61, 0x6000
	s_cmp_eq_u32 s61, 0x12000
	s_cselect_b32 s61, 0, s61
	s_waitcnt lgkmcnt(0)
	s_setprio 1
	v_mfma_f32_16x16x32_bf16 v[2:5], v[210:213], v[178:181], v[2:5]
	v_mfma_f32_16x16x32_bf16 v[6:9], v[214:217], v[178:181], v[6:9]
	v_mfma_f32_16x16x32_bf16 v[10:13], v[218:221], v[178:181], v[10:13]
	v_mfma_f32_16x16x32_bf16 v[14:17], v[222:225], v[178:181], v[14:17]
	s_barrier
	v_mfma_f32_16x16x32_bf16 v[30:33], v[222:225], v[182:185], v[30:33]
	v_mfma_f32_16x16x32_bf16 v[26:29], v[218:221], v[182:185], v[26:29]
	v_mfma_f32_16x16x32_bf16 v[22:25], v[214:217], v[182:185], v[22:25]
	v_mfma_f32_16x16x32_bf16 v[18:21], v[210:213], v[182:185], v[18:21]
	v_mfma_f32_16x16x32_bf16 v[34:37], v[210:213], v[186:189], v[34:37]
	v_mfma_f32_16x16x32_bf16 v[38:41], v[214:217], v[186:189], v[38:41]
	v_mfma_f32_16x16x32_bf16 v[42:45], v[218:221], v[186:189], v[42:45]
	v_mfma_f32_16x16x32_bf16 v[46:49], v[222:225], v[186:189], v[46:49]
	v_mfma_f32_16x16x32_bf16 v[62:65], v[222:225], v[190:193], v[62:65]
	v_mfma_f32_16x16x32_bf16 v[58:61], v[218:221], v[190:193], v[58:61]
	v_mfma_f32_16x16x32_bf16 v[54:57], v[214:217], v[190:193], v[54:57]
	v_mfma_f32_16x16x32_bf16 v[50:53], v[210:213], v[190:193], v[50:53]
	v_mfma_f32_16x16x32_bf16 v[66:69], v[210:213], v[194:197], v[66:69]
	v_mfma_f32_16x16x32_bf16 v[70:73], v[214:217], v[194:197], v[70:73]
	v_mfma_f32_16x16x32_bf16 v[74:77], v[218:221], v[194:197], v[74:77]
	v_mfma_f32_16x16x32_bf16 v[78:81], v[222:225], v[194:197], v[78:81]
	v_mfma_f32_16x16x32_bf16 v[94:97], v[222:225], v[198:201], v[94:97]
	v_mfma_f32_16x16x32_bf16 v[90:93], v[218:221], v[198:201], v[90:93]
	v_mfma_f32_16x16x32_bf16 v[86:89], v[214:217], v[198:201], v[86:89]
	v_mfma_f32_16x16x32_bf16 v[82:85], v[210:213], v[198:201], v[82:85]
	v_mfma_f32_16x16x32_bf16 v[98:101], v[210:213], v[202:205], v[98:101]
	v_mfma_f32_16x16x32_bf16 v[102:105], v[214:217], v[202:205], v[102:105]
	v_mfma_f32_16x16x32_bf16 v[106:109], v[218:221], v[202:205], v[106:109]
	v_mfma_f32_16x16x32_bf16 v[110:113], v[222:225], v[202:205], v[110:113]
	v_mfma_f32_16x16x32_bf16 v[126:129], v[222:225], v[206:209], v[126:129]
	v_mfma_f32_16x16x32_bf16 v[122:125], v[218:221], v[206:209], v[122:125]
	v_mfma_f32_16x16x32_bf16 v[118:121], v[214:217], v[206:209], v[118:121]
	v_mfma_f32_16x16x32_bf16 v[114:117], v[210:213], v[206:209], v[114:117]
	s_setprio 0
	s_and_b32 s39, s35, 0xfff
	s_lshr_b32 s21, s36, 7
	s_waitcnt vmcnt(0)
	v_mbcnt_lo_u32_b32 v217, -1, 0
	v_mbcnt_hi_u32_b32 v217, -1, v217
	v_lshlrev_b32_e32 v217, 5, v217
	s_lshl_b32 s26, s43, 11
	v_add_u32_e32 v248, s26, v217
	s_add_i32 s26, s26, 0x12010
	v_add_u32_e32 v217, s26, v217
	s_cmp_eq_u32 s42, 0
	s_cbranch_scc0 .Lup_el_nowr
	ds_write_b128 v217, v[114:117]
	ds_write_b128 v217, v[118:121] offset:16
	s_branch .Lup_el_wrd

.Lpj_nn_a:
	s_waitcnt lgkmcnt(0)
	v_add_u32_e32 v240, s61, v238
	v_add_u32_e32 v241, s61, v239
	s_setprio 1
	v_mfma_f32_16x16x32_bf16 v[2:5], v[162:165], v[130:133], 0
	v_mfma_f32_16x16x32_bf16 v[6:9], v[166:169], v[130:133], 0
	v_mfma_f32_16x16x32_bf16 v[10:13], v[170:173], v[130:133], 0
	v_mfma_f32_16x16x32_bf16 v[14:17], v[174:177], v[130:133], 0
	s_waitcnt vmcnt(6)
	s_barrier
	v_mfma_f32_16x16x32_bf16 v[30:33], v[174:177], v[134:137], 0
	s_add_i32 m0, s60, s62
	v_mfma_f32_16x16x32_bf16 v[26:29], v[170:173], v[134:137], 0
	global_load_lds_dwordx4 v226, s[54:55]
	v_mfma_f32_16x16x32_bf16 v[22:25], v[166:169], v[134:137], 0
	v_mfma_f32_16x16x32_bf16 v[18:21], v[162:165], v[134:137], 0
	v_mfma_f32_16x16x32_bf16 v[34:37], v[162:165], v[138:141], 0
	ds_read_b128 v[210:213], v241 offset:0
	v_mfma_f32_16x16x32_bf16 v[38:41], v[166:169], v[138:141], 0
	ds_read_b128 v[214:217], v241 offset:256
	v_mfma_f32_16x16x32_bf16 v[42:45], v[170:173], v[138:141], 0
	ds_read_b128 v[218:221], v241 offset:2048
	global_load_lds_dwordx4 v226, s[54:55] offset:1024
	v_mfma_f32_16x16x32_bf16 v[46:49], v[174:177], v[138:141], 0
	ds_read_b128 v[222:225], v241 offset:2304
	v_mfma_f32_16x16x32_bf16 v[62:65], v[174:177], v[142:145], 0
	ds_read_b128 v[178:181], v240 offset:0
	v_mfma_f32_16x16x32_bf16 v[58:61], v[170:173], v[142:145], 0
	ds_read_b128 v[182:185], v240 offset:1024
	v_mfma_f32_16x16x32_bf16 v[54:57], v[166:169], v[142:145], 0
	ds_read_b128 v[186:189], v240 offset:2048
	v_mfma_f32_16x16x32_bf16 v[50:53], v[162:165], v[142:145], 0
	ds_read_b128 v[190:193], v240 offset:3072
	global_load_lds_dwordx4 v226, s[54:55] offset:2048
	v_mfma_f32_16x16x32_bf16 v[66:69], v[162:165], v[146:149], 0
	ds_read_b128 v[194:197], v240 offset:4096
	v_mfma_f32_16x16x32_bf16 v[70:73], v[166:169], v[146:149], 0
	ds_read_b128 v[198:201], v240 offset:5120
	v_mfma_f32_16x16x32_bf16 v[74:77], v[170:173], v[146:149], 0
	ds_read_b128 v[202:205], v240 offset:6144
	v_mfma_f32_16x16x32_bf16 v[78:81], v[174:177], v[146:149], 0
	ds_read_b128 v[206:209], v240 offset:7168
	v_mfma_f32_16x16x32_bf16 v[94:97], v[174:177], v[150:153], 0
	global_load_lds_dwordx4 v226, s[54:55] offset:3072
	v_mfma_f32_16x16x32_bf16 v[90:93], v[170:173], v[150:153], 0
	v_mfma_f32_16x16x32_bf16 v[86:89], v[166:169], v[150:153], 0
	v_mfma_f32_16x16x32_bf16 v[82:85], v[162:165], v[150:153], 0
	v_mfma_f32_16x16x32_bf16 v[98:101], v[162:165], v[154:157], 0
	s_add_i32 m0, s60, s63
	v_mfma_f32_16x16x32_bf16 v[102:105], v[166:169], v[154:157], 0
	global_load_lds_dwordx4 v230, s[56:57]
	v_mfma_f32_16x16x32_bf16 v[106:109], v[170:173], v[154:157], 0
	v_mfma_f32_16x16x32_bf16 v[110:113], v[174:177], v[154:157], 0
	v_mfma_f32_16x16x32_bf16 v[126:129], v[174:177], v[158:161], 0
	v_mfma_f32_16x16x32_bf16 v[122:125], v[170:173], v[158:161], 0
	v_mfma_f32_16x16x32_bf16 v[118:121], v[166:169], v[158:161], 0
	global_load_lds_dwordx4 v231, s[56:57] offset:1024
	v_mfma_f32_16x16x32_bf16 v[114:117], v[162:165], v[158:161], 0
	s_setprio 0
	s_add_i32 s60, s60, 0x6000
	s_cmp_eq_u32 s60, 0x12000
	s_cselect_b32 s60, 0, s60
	s_add_u32 s54, s54, s72
	s_addc_u32 s55, s55, 0
	s_add_u32 s56, s56, s73
	s_addc_u32 s57, s57, 0
	s_add_i32 s61, s61, 0x6000
	s_cmp_eq_u32 s61, 0x12000
	s_cselect_b32 s61, 0, s61
	s_waitcnt lgkmcnt(0)
	v_add_u32_e32 v240, s61, v238
	v_add_u32_e32 v241, s61, v239
	s_setprio 1
	v_mfma_f32_16x16x32_bf16 v[2:5], v[210:213], v[178:181], v[2:5]
	v_mfma_f32_16x16x32_bf16 v[6:9], v[214:217], v[178:181], v[6:9]
	v_mfma_f32_16x16x32_bf16 v[10:13], v[218:221], v[178:181], v[10:13]
	v_mfma_f32_16x16x32_bf16 v[14:17], v[222:225], v[178:181], v[14:17]
	s_waitcnt vmcnt(6)
	s_barrier
	v_mfma_f32_16x16x32_bf16 v[30:33], v[222:225], v[182:185], v[30:33]
	s_add_i32 m0, s60, s62
	v_mfma_f32_16x16x32_bf16 v[26:29], v[218:221], v[182:185], v[26:29]
	global_load_lds_dwordx4 v226, s[54:55]
	v_mfma_f32_16x16x32_bf16 v[22:25], v[214:217], v[182:185], v[22:25]
	v_mfma_f32_16x16x32_bf16 v[18:21], v[210:213], v[182:185], v[18:21]
	v_mfma_f32_16x16x32_bf16 v[34:37], v[210:213], v[186:189], v[34:37]
	ds_read_b128 v[162:165], v241 offset:0
	v_mfma_f32_16x16x32_bf16 v[38:41], v[214:217], v[186:189], v[38:41]
	ds_read_b128 v[166:169], v241 offset:256
	v_mfma_f32_16x16x32_bf16 v[42:45], v[218:221], v[186:189], v[42:45]
	ds_read_b128 v[170:173], v241 offset:2048
	global_load_lds_dwordx4 v226, s[54:55] offset:1024
	v_mfma_f32_16x16x32_bf16 v[46:49], v[222:225], v[186:189], v[46:49]
	ds_read_b128 v[174:177], v241 offset:2304
	v_mfma_f32_16x16x32_bf16 v[62:65], v[222:225], v[190:193], v[62:65]
	ds_read_b128 v[130:133], v240 offset:0
	v_mfma_f32_16x16x32_bf16 v[58:61], v[218:221], v[190:193], v[58:61]
	ds_read_b128 v[134:137], v240 offset:1024
	v_mfma_f32_16x16x32_bf16 v[54:57], v[214:217], v[190:193], v[54:57]
	ds_read_b128 v[138:141], v240 offset:2048
	v_mfma_f32_16x16x32_bf16 v[50:53], v[210:213], v[190:193], v[50:53]
	ds_read_b128 v[142:145], v240 offset:3072
	global_load_lds_dwordx4 v226, s[54:55] offset:2048
	v_mfma_f32_16x16x32_bf16 v[66:69], v[210:213], v[194:197], v[66:69]
	ds_read_b128 v[146:149], v240 offset:4096
	v_mfma_f32_16x16x32_bf16 v[70:73], v[214:217], v[194:197], v[70:73]
	ds_read_b128 v[150:153], v240 offset:5120
	v_mfma_f32_16x16x32_bf16 v[74:77], v[218:221], v[194:197], v[74:77]
	ds_read_b128 v[154:157], v240 offset:6144
	v_mfma_f32_16x16x32_bf16 v[78:81], v[222:225], v[194:197], v[78:81]
	ds_read_b128 v[158:161], v240 offset:7168
	v_mfma_f32_16x16x32_bf16 v[94:97], v[222:225], v[198:201], v[94:97]
	global_load_lds_dwordx4 v226, s[54:55] offset:3072
	v_mfma_f32_16x16x32_bf16 v[90:93], v[218:221], v[198:201], v[90:93]
	v_mfma_f32_16x16x32_bf16 v[86:89], v[214:217], v[198:201], v[86:89]
	v_mfma_f32_16x16x32_bf16 v[82:85], v[210:213], v[198:201], v[82:85]
	v_mfma_f32_16x16x32_bf16 v[98:101], v[210:213], v[202:205], v[98:101]
	s_add_i32 m0, s60, s63
	v_mfma_f32_16x16x32_bf16 v[102:105], v[214:217], v[202:205], v[102:105]
	global_load_lds_dwordx4 v230, s[56:57]
	v_mfma_f32_16x16x32_bf16 v[106:109], v[218:221], v[202:205], v[106:109]
	v_mfma_f32_16x16x32_bf16 v[110:113], v[222:225], v[202:205], v[110:113]
	v_mfma_f32_16x16x32_bf16 v[126:129], v[222:225], v[206:209], v[126:129]
	v_mfma_f32_16x16x32_bf16 v[122:125], v[218:221], v[206:209], v[122:125]
	v_mfma_f32_16x16x32_bf16 v[118:121], v[214:217], v[206:209], v[118:121]
	global_load_lds_dwordx4 v231, s[56:57] offset:1024
	v_mfma_f32_16x16x32_bf16 v[114:117], v[210:213], v[206:209], v[114:117]
	s_setprio 0
	s_add_i32 s60, s60, 0x6000
	s_cmp_eq_u32 s60, 0x12000
	s_cselect_b32 s60, 0, s60
	s_add_u32 s54, s54, s72
	s_addc_u32 s55, s55, 0
	s_add_u32 s56, s56, s73
	s_addc_u32 s57, s57, 0
	s_add_i32 s61, s61, 0x6000
	s_cmp_eq_u32 s61, 0x12000
	s_cselect_b32 s61, 0, s61
	s_branch .Lpj_main

.Lpj_nn_b:
	s_waitcnt lgkmcnt(0)
	v_add_u32_e32 v240, s61, v238
	v_add_u32_e32 v241, s61, v239
	s_setprio 1
	v_mfma_f32_16x16x32_bf16 v[2:5], v[162:165], v[130:133], 0
	v_mfma_f32_16x16x32_bf16 v[6:9], v[166:169], v[130:133], 0
	v_mfma_f32_16x16x32_bf16 v[10:13], v[170:173], v[130:133], 0
	v_mfma_f32_16x16x32_bf16 v[14:17], v[174:177], v[130:133], 0
	s_waitcnt vmcnt(63)
	s_barrier
	v_mfma_f32_16x16x32_bf16 v[30:33], v[174:177], v[134:137], 0
	s_add_i32 m0, s60, s62
	v_mfma_f32_16x16x32_bf16 v[26:29], v[170:173], v[134:137], 0
	global_load_lds_dwordx4 v226, s[54:55]
	v_mfma_f32_16x16x32_bf16 v[22:25], v[166:169], v[134:137], 0
	v_mfma_f32_16x16x32_bf16 v[18:21], v[162:165], v[134:137], 0
	v_mfma_f32_16x16x32_bf16 v[34:37], v[162:165], v[138:141], 0
	ds_read_b128 v[210:213], v241 offset:0
	v_mfma_f32_16x16x32_bf16 v[38:41], v[166:169], v[138:141], 0
	ds_read_b128 v[214:217], v241 offset:256
	v_mfma_f32_16x16x32_bf16 v[42:45], v[170:173], v[138:141], 0
	ds_read_b128 v[218:221], v241 offset:2048
	global_load_lds_dwordx4 v226, s[54:55] offset:1024
	v_mfma_f32_16x16x32_bf16 v[46:49], v[174:177], v[138:141], 0
	ds_read_b128 v[222:225], v241 offset:2304
	v_mfma_f32_16x16x32_bf16 v[62:65], v[174:177], v[142:145], 0
	ds_read_b128 v[178:181], v240 offset:0
	v_mfma_f32_16x16x32_bf16 v[58:61], v[170:173], v[142:145], 0
	ds_read_b128 v[182:185], v240 offset:1024
	v_mfma_f32_16x16x32_bf16 v[54:57], v[166:169], v[142:145], 0
	ds_read_b128 v[186:189], v240 offset:2048
	v_mfma_f32_16x16x32_bf16 v[50:53], v[162:165], v[142:145], 0
	ds_read_b128 v[190:193], v240 offset:3072
	global_load_lds_dwordx4 v226, s[54:55] offset:2048
	v_mfma_f32_16x16x32_bf16 v[66:69], v[162:165], v[146:149], 0
	ds_read_b128 v[194:197], v240 offset:4096
	v_mfma_f32_16x16x32_bf16 v[70:73], v[166:169], v[146:149], 0
	ds_read_b128 v[198:201], v240 offset:5120
	v_mfma_f32_16x16x32_bf16 v[74:77], v[170:173], v[146:149], 0
	ds_read_b128 v[202:205], v240 offset:6144
	v_mfma_f32_16x16x32_bf16 v[78:81], v[174:177], v[146:149], 0
	ds_read_b128 v[206:209], v240 offset:7168
	v_mfma_f32_16x16x32_bf16 v[94:97], v[174:177], v[150:153], 0
	global_load_lds_dwordx4 v226, s[54:55] offset:3072
	v_mfma_f32_16x16x32_bf16 v[90:93], v[170:173], v[150:153], 0
	v_mfma_f32_16x16x32_bf16 v[86:89], v[166:169], v[150:153], 0
	v_mfma_f32_16x16x32_bf16 v[82:85], v[162:165], v[150:153], 0
	v_mfma_f32_16x16x32_bf16 v[98:101], v[162:165], v[154:157], 0
	s_add_i32 m0, s60, s63
	v_mfma_f32_16x16x32_bf16 v[102:105], v[166:169], v[154:157], 0
	global_load_lds_dwordx4 v230, s[56:57]
	v_mfma_f32_16x16x32_bf16 v[106:109], v[170:173], v[154:157], 0
	v_mfma_f32_16x16x32_bf16 v[110:113], v[174:177], v[154:157], 0
	v_mfma_f32_16x16x32_bf16 v[126:129], v[174:177], v[158:161], 0
	v_mfma_f32_16x16x32_bf16 v[122:125], v[170:173], v[158:161], 0
	v_mfma_f32_16x16x32_bf16 v[118:121], v[166:169], v[158:161], 0
	global_load_lds_dwordx4 v231, s[56:57] offset:1024
	v_mfma_f32_16x16x32_bf16 v[114:117], v[162:165], v[158:161], 0
	s_setprio 0
	s_add_i32 s60, s60, 0x6000
	s_cmp_eq_u32 s60, 0x12000
	s_cselect_b32 s60, 0, s60
	s_add_u32 s54, s54, s72
	s_addc_u32 s55, s55, 0
	s_add_u32 s56, s56, s73
	s_addc_u32 s57, s57, 0
	s_add_i32 s61, s61, 0x6000
	s_cmp_eq_u32 s61, 0x12000
	s_cselect_b32 s61, 0, s61
	s_waitcnt lgkmcnt(0)
	v_add_u32_e32 v240, s61, v238
	v_add_u32_e32 v241, s61, v239
	s_setprio 1
	v_mfma_f32_16x16x32_bf16 v[2:5], v[210:213], v[178:181], v[2:5]
	v_mfma_f32_16x16x32_bf16 v[6:9], v[214:217], v[178:181], v[6:9]
	v_mfma_f32_16x16x32_bf16 v[10:13], v[218:221], v[178:181], v[10:13]
	v_mfma_f32_16x16x32_bf16 v[14:17], v[222:225], v[178:181], v[14:17]
	s_waitcnt vmcnt(63)
	s_barrier
	v_mfma_f32_16x16x32_bf16 v[30:33], v[222:225], v[182:185], v[30:33]
	s_add_i32 m0, s60, s62
	v_mfma_f32_16x16x32_bf16 v[26:29], v[218:221], v[182:185], v[26:29]
	global_load_lds_dwordx4 v226, s[54:55]
	v_mfma_f32_16x16x32_bf16 v[22:25], v[214:217], v[182:185], v[22:25]
	v_mfma_f32_16x16x32_bf16 v[18:21], v[210:213], v[182:185], v[18:21]
	v_mfma_f32_16x16x32_bf16 v[34:37], v[210:213], v[186:189], v[34:37]
	ds_read_b128 v[162:165], v241 offset:0
	v_mfma_f32_16x16x32_bf16 v[38:41], v[214:217], v[186:189], v[38:41]
	ds_read_b128 v[166:169], v241 offset:256
	v_mfma_f32_16x16x32_bf16 v[42:45], v[218:221], v[186:189], v[42:45]
	ds_read_b128 v[170:173], v241 offset:2048
	global_load_lds_dwordx4 v226, s[54:55] offset:1024
	v_mfma_f32_16x16x32_bf16 v[46:49], v[222:225], v[186:189], v[46:49]
	ds_read_b128 v[174:177], v241 offset:2304
	v_mfma_f32_16x16x32_bf16 v[62:65], v[222:225], v[190:193], v[62:65]
	ds_read_b128 v[130:133], v240 offset:0
	v_mfma_f32_16x16x32_bf16 v[58:61], v[218:221], v[190:193], v[58:61]
	ds_read_b128 v[134:137], v240 offset:1024
	v_mfma_f32_16x16x32_bf16 v[54:57], v[214:217], v[190:193], v[54:57]
	ds_read_b128 v[138:141], v240 offset:2048
	v_mfma_f32_16x16x32_bf16 v[50:53], v[210:213], v[190:193], v[50:53]
	ds_read_b128 v[142:145], v240 offset:3072
	global_load_lds_dwordx4 v226, s[54:55] offset:2048
	v_mfma_f32_16x16x32_bf16 v[66:69], v[210:213], v[194:197], v[66:69]
	ds_read_b128 v[146:149], v240 offset:4096
	v_mfma_f32_16x16x32_bf16 v[70:73], v[214:217], v[194:197], v[70:73]
	ds_read_b128 v[150:153], v240 offset:5120
	v_mfma_f32_16x16x32_bf16 v[74:77], v[218:221], v[194:197], v[74:77]
	ds_read_b128 v[154:157], v240 offset:6144
	v_mfma_f32_16x16x32_bf16 v[78:81], v[222:225], v[194:197], v[78:81]
	ds_read_b128 v[158:161], v240 offset:7168
	v_mfma_f32_16x16x32_bf16 v[94:97], v[222:225], v[198:201], v[94:97]
	global_load_lds_dwordx4 v226, s[54:55] offset:3072
	v_mfma_f32_16x16x32_bf16 v[90:93], v[218:221], v[198:201], v[90:93]
	v_mfma_f32_16x16x32_bf16 v[86:89], v[214:217], v[198:201], v[86:89]
	v_mfma_f32_16x16x32_bf16 v[82:85], v[210:213], v[198:201], v[82:85]
	v_mfma_f32_16x16x32_bf16 v[98:101], v[210:213], v[202:205], v[98:101]
	s_add_i32 m0, s60, s63
	v_mfma_f32_16x16x32_bf16 v[102:105], v[214:217], v[202:205], v[102:105]
	global_load_lds_dwordx4 v230, s[56:57]
	v_mfma_f32_16x16x32_bf16 v[106:109], v[218:221], v[202:205], v[106:109]
	v_mfma_f32_16x16x32_bf16 v[110:113], v[222:225], v[202:205], v[110:113]
	v_mfma_f32_16x16x32_bf16 v[126:129], v[222:225], v[206:209], v[126:129]
	v_mfma_f32_16x16x32_bf16 v[122:125], v[218:221], v[206:209], v[122:125]
	v_mfma_f32_16x16x32_bf16 v[118:121], v[214:217], v[206:209], v[118:121]
	global_load_lds_dwordx4 v231, s[56:57] offset:1024
	v_mfma_f32_16x16x32_bf16 v[114:117], v[210:213], v[206:209], v[114:117]
	s_setprio 0
	s_add_i32 s60, s60, 0x6000
	s_cmp_eq_u32 s60, 0x12000
	s_cselect_b32 s60, 0, s60
	s_add_u32 s54, s54, s72
	s_addc_u32 s55, s55, 0
	s_add_u32 s56, s56, s73
	s_addc_u32 s57, s57, 0
	s_add_i32 s61, s61, 0x6000
	s_cmp_eq_u32 s61, 0x12000
	s_cselect_b32 s61, 0, s61

.Lpj_kdone:
	s_cmp_eq_u32 s37, 0
	s_cbranch_scc1 .Lpj_tail_last
	s_waitcnt lgkmcnt(0)
	v_add_u32_e32 v240, s61, v238
	v_add_u32_e32 v241, s61, v239
	s_setprio 1
	v_mfma_f32_16x16x32_bf16 v[2:5], v[162:165], v[130:133], v[2:5]
	v_mfma_f32_16x16x32_bf16 v[6:9], v[166:169], v[130:133], v[6:9]
	v_mfma_f32_16x16x32_bf16 v[10:13], v[170:173], v[130:133], v[10:13]
	v_mfma_f32_16x16x32_bf16 v[14:17], v[174:177], v[130:133], v[14:17]
	s_waitcnt vmcnt(6)
	s_barrier
	v_mfma_f32_16x16x32_bf16 v[30:33], v[174:177], v[134:137], v[30:33]
	s_add_i32 m0, s60, s62
	v_mfma_f32_16x16x32_bf16 v[26:29], v[170:173], v[134:137], v[26:29]
	global_load_lds_dwordx4 v226, s[54:55]
	v_mfma_f32_16x16x32_bf16 v[22:25], v[166:169], v[134:137], v[22:25]
	v_mfma_f32_16x16x32_bf16 v[18:21], v[162:165], v[134:137], v[18:21]
	v_mfma_f32_16x16x32_bf16 v[34:37], v[162:165], v[138:141], v[34:37]
	ds_read_b128 v[210:213], v241 offset:0
	v_mfma_f32_16x16x32_bf16 v[38:41], v[166:169], v[138:141], v[38:41]
	ds_read_b128 v[214:217], v241 offset:256
	v_mfma_f32_16x16x32_bf16 v[42:45], v[170:173], v[138:141], v[42:45]
	ds_read_b128 v[218:221], v241 offset:2048
	global_load_lds_dwordx4 v226, s[54:55] offset:1024
	v_mfma_f32_16x16x32_bf16 v[46:49], v[174:177], v[138:141], v[46:49]
	ds_read_b128 v[222:225], v241 offset:2304
	v_mfma_f32_16x16x32_bf16 v[62:65], v[174:177], v[142:145], v[62:65]
	ds_read_b128 v[178:181], v240 offset:0
	v_mfma_f32_16x16x32_bf16 v[58:61], v[170:173], v[142:145], v[58:61]
	ds_read_b128 v[182:185], v240 offset:1024
	v_mfma_f32_16x16x32_bf16 v[54:57], v[166:169], v[142:145], v[54:57]
	ds_read_b128 v[186:189], v240 offset:2048
	v_mfma_f32_16x16x32_bf16 v[50:53], v[162:165], v[142:145], v[50:53]
	ds_read_b128 v[190:193], v240 offset:3072
	global_load_lds_dwordx4 v226, s[54:55] offset:2048
	v_mfma_f32_16x16x32_bf16 v[66:69], v[162:165], v[146:149], v[66:69]
	ds_read_b128 v[194:197], v240 offset:4096
	v_mfma_f32_16x16x32_bf16 v[70:73], v[166:169], v[146:149], v[70:73]
	ds_read_b128 v[198:201], v240 offset:5120
	v_mfma_f32_16x16x32_bf16 v[74:77], v[170:173], v[146:149], v[74:77]
	ds_read_b128 v[202:205], v240 offset:6144
	v_mfma_f32_16x16x32_bf16 v[78:81], v[174:177], v[146:149], v[78:81]
	ds_read_b128 v[206:209], v240 offset:7168
	v_mfma_f32_16x16x32_bf16 v[94:97], v[174:177], v[150:153], v[94:97]
	global_load_lds_dwordx4 v226, s[54:55] offset:3072
	v_mfma_f32_16x16x32_bf16 v[90:93], v[170:173], v[150:153], v[90:93]
	v_mfma_f32_16x16x32_bf16 v[86:89], v[166:169], v[150:153], v[86:89]
	v_mfma_f32_16x16x32_bf16 v[82:85], v[162:165], v[150:153], v[82:85]
	v_mfma_f32_16x16x32_bf16 v[98:101], v[162:165], v[154:157], v[98:101]
	s_add_i32 m0, s60, s63
	v_mfma_f32_16x16x32_bf16 v[102:105], v[166:169], v[154:157], v[102:105]
	global_load_lds_dwordx4 v230, s[56:57]
	v_mfma_f32_16x16x32_bf16 v[106:109], v[170:173], v[154:157], v[106:109]
	v_mfma_f32_16x16x32_bf16 v[110:113], v[174:177], v[154:157], v[110:113]
	v_mfma_f32_16x16x32_bf16 v[126:129], v[174:177], v[158:161], v[126:129]
	v_mfma_f32_16x16x32_bf16 v[122:125], v[170:173], v[158:161], v[122:125]
	v_mfma_f32_16x16x32_bf16 v[118:121], v[166:169], v[158:161], v[118:121]
	global_load_lds_dwordx4 v231, s[56:57] offset:1024
	v_mfma_f32_16x16x32_bf16 v[114:117], v[162:165], v[158:161], v[114:117]
	s_setprio 0
	s_add_i32 s60, s60, 0x6000
	s_cmp_eq_u32 s60, 0x12000
	s_cselect_b32 s60, 0, s60
	s_add_u32 s54, s54, s72
	s_addc_u32 s55, s55, 0
	s_add_u32 s56, s56, s73
	s_addc_u32 s57, s57, 0
	s_add_i32 s61, s61, 0x6000
	s_cmp_eq_u32 s61, 0x12000
	s_cselect_b32 s61, 0, s61
	v_mov_b32_e32 v226, v232
	v_mov_b32_e32 v230, v236
	v_mov_b32_e32 v231, v237
	s_mov_b64 s[54:55], s[48:49]
	s_mov_b64 s[56:57], s[50:51]
	s_waitcnt lgkmcnt(0)
	v_add_u32_e32 v240, s61, v238
	v_add_u32_e32 v241, s61, v239
	s_setprio 1
	v_mfma_f32_16x16x32_bf16 v[2:5], v[210:213], v[178:181], v[2:5]
	v_mfma_f32_16x16x32_bf16 v[6:9], v[214:217], v[178:181], v[6:9]
	v_mfma_f32_16x16x32_bf16 v[10:13], v[218:221], v[178:181], v[10:13]
	v_mfma_f32_16x16x32_bf16 v[14:17], v[222:225], v[178:181], v[14:17]
	s_waitcnt vmcnt(6)
	s_barrier
	v_mfma_f32_16x16x32_bf16 v[30:33], v[222:225], v[182:185], v[30:33]
	s_add_i32 m0, s60, s62
	v_mfma_f32_16x16x32_bf16 v[26:29], v[218:221], v[182:185], v[26:29]
	global_load_lds_dwordx4 v226, s[54:55]
	v_mfma_f32_16x16x32_bf16 v[22:25], v[214:217], v[182:185], v[22:25]
	v_mfma_f32_16x16x32_bf16 v[18:21], v[210:213], v[182:185], v[18:21]
	v_mfma_f32_16x16x32_bf16 v[34:37], v[210:213], v[186:189], v[34:37]
	ds_read_b128 v[162:165], v241 offset:0
	v_mfma_f32_16x16x32_bf16 v[38:41], v[214:217], v[186:189], v[38:41]
	ds_read_b128 v[166:169], v241 offset:256
	v_mfma_f32_16x16x32_bf16 v[42:45], v[218:221], v[186:189], v[42:45]
	ds_read_b128 v[170:173], v241 offset:2048
	global_load_lds_dwordx4 v226, s[54:55] offset:1024
	v_mfma_f32_16x16x32_bf16 v[46:49], v[222:225], v[186:189], v[46:49]
	ds_read_b128 v[174:177], v241 offset:2304
	v_mfma_f32_16x16x32_bf16 v[62:65], v[222:225], v[190:193], v[62:65]
	ds_read_b128 v[130:133], v240 offset:0
	v_mfma_f32_16x16x32_bf16 v[58:61], v[218:221], v[190:193], v[58:61]
	ds_read_b128 v[134:137], v240 offset:1024
	v_mfma_f32_16x16x32_bf16 v[54:57], v[214:217], v[190:193], v[54:57]
	ds_read_b128 v[138:141], v240 offset:2048
	v_mfma_f32_16x16x32_bf16 v[50:53], v[210:213], v[190:193], v[50:53]
	ds_read_b128 v[142:145], v240 offset:3072
	global_load_lds_dwordx4 v226, s[54:55] offset:2048
	v_mfma_f32_16x16x32_bf16 v[66:69], v[210:213], v[194:197], v[66:69]
	ds_read_b128 v[146:149], v240 offset:4096
	v_mfma_f32_16x16x32_bf16 v[70:73], v[214:217], v[194:197], v[70:73]
	ds_read_b128 v[150:153], v240 offset:5120
	v_mfma_f32_16x16x32_bf16 v[74:77], v[218:221], v[194:197], v[74:77]
	ds_read_b128 v[154:157], v240 offset:6144
	v_mfma_f32_16x16x32_bf16 v[78:81], v[222:225], v[194:197], v[78:81]
	ds_read_b128 v[158:161], v240 offset:7168
	v_mfma_f32_16x16x32_bf16 v[94:97], v[222:225], v[198:201], v[94:97]
	global_load_lds_dwordx4 v226, s[54:55] offset:3072
	v_mfma_f32_16x16x32_bf16 v[90:93], v[218:221], v[198:201], v[90:93]
	v_mfma_f32_16x16x32_bf16 v[86:89], v[214:217], v[198:201], v[86:89]
	v_mfma_f32_16x16x32_bf16 v[82:85], v[210:213], v[198:201], v[82:85]
	v_mfma_f32_16x16x32_bf16 v[98:101], v[210:213], v[202:205], v[98:101]
	s_add_i32 m0, s60, s63
	v_mfma_f32_16x16x32_bf16 v[102:105], v[214:217], v[202:205], v[102:105]
	global_load_lds_dwordx4 v230, s[56:57]
	v_mfma_f32_16x16x32_bf16 v[106:109], v[218:221], v[202:205], v[106:109]
	v_mfma_f32_16x16x32_bf16 v[110:113], v[222:225], v[202:205], v[110:113]
	v_mfma_f32_16x16x32_bf16 v[126:129], v[222:225], v[206:209], v[126:129]
	v_mfma_f32_16x16x32_bf16 v[122:125], v[218:221], v[206:209], v[122:125]
	v_mfma_f32_16x16x32_bf16 v[118:121], v[214:217], v[206:209], v[118:121]
	global_load_lds_dwordx4 v231, s[56:57] offset:1024
	v_mfma_f32_16x16x32_bf16 v[114:117], v[210:213], v[206:209], v[114:117]
	s_setprio 0
	s_add_i32 s60, s60, 0x6000
	s_cmp_eq_u32 s60, 0x12000
	s_cselect_b32 s60, 0, s60
	s_add_u32 s54, s54, s72
	s_addc_u32 s55, s55, 0
	s_add_u32 s56, s56, s73
	s_addc_u32 s57, s57, 0
	s_add_i32 s61, s61, 0x6000
	s_cmp_eq_u32 s61, 0x12000
	s_cselect_b32 s61, 0, s61
	s_waitcnt lgkmcnt(0)
	v_add_u32_e32 v240, s61, v238
	v_add_u32_e32 v241, s61, v239
	s_setprio 1
	v_mfma_f32_16x16x32_bf16 v[2:5], v[162:165], v[130:133], v[2:5]
	v_mfma_f32_16x16x32_bf16 v[6:9], v[166:169], v[130:133], v[6:9]
	v_mfma_f32_16x16x32_bf16 v[10:13], v[170:173], v[130:133], v[10:13]
	v_mfma_f32_16x16x32_bf16 v[14:17], v[174:177], v[130:133], v[14:17]
	s_waitcnt vmcnt(6)
	s_barrier
	v_mfma_f32_16x16x32_bf16 v[30:33], v[174:177], v[134:137], v[30:33]
	s_add_i32 m0, s60, s62
	v_mfma_f32_16x16x32_bf16 v[26:29], v[170:173], v[134:137], v[26:29]
	global_load_lds_dwordx4 v226, s[54:55]
	v_mfma_f32_16x16x32_bf16 v[22:25], v[166:169], v[134:137], v[22:25]
	v_mfma_f32_16x16x32_bf16 v[18:21], v[162:165], v[134:137], v[18:21]
	v_mfma_f32_16x16x32_bf16 v[34:37], v[162:165], v[138:141], v[34:37]
	ds_read_b128 v[210:213], v241 offset:0
	v_mfma_f32_16x16x32_bf16 v[38:41], v[166:169], v[138:141], v[38:41]
	ds_read_b128 v[214:217], v241 offset:256
	v_mfma_f32_16x16x32_bf16 v[42:45], v[170:173], v[138:141], v[42:45]
	ds_read_b128 v[218:221], v241 offset:2048
	global_load_lds_dwordx4 v226, s[54:55] offset:1024
	v_mfma_f32_16x16x32_bf16 v[46:49], v[174:177], v[138:141], v[46:49]
	ds_read_b128 v[222:225], v241 offset:2304
	v_mfma_f32_16x16x32_bf16 v[62:65], v[174:177], v[142:145], v[62:65]
	ds_read_b128 v[178:181], v240 offset:0
	v_mfma_f32_16x16x32_bf16 v[58:61], v[170:173], v[142:145], v[58:61]
	ds_read_b128 v[182:185], v240 offset:1024
	v_mfma_f32_16x16x32_bf16 v[54:57], v[166:169], v[142:145], v[54:57]
	ds_read_b128 v[186:189], v240 offset:2048
	v_mfma_f32_16x16x32_bf16 v[50:53], v[162:165], v[142:145], v[50:53]
	ds_read_b128 v[190:193], v240 offset:3072
	global_load_lds_dwordx4 v226, s[54:55] offset:2048
	v_mfma_f32_16x16x32_bf16 v[66:69], v[162:165], v[146:149], v[66:69]
	ds_read_b128 v[194:197], v240 offset:4096
	v_mfma_f32_16x16x32_bf16 v[70:73], v[166:169], v[146:149], v[70:73]
	ds_read_b128 v[198:201], v240 offset:5120
	v_mfma_f32_16x16x32_bf16 v[74:77], v[170:173], v[146:149], v[74:77]
	ds_read_b128 v[202:205], v240 offset:6144
	v_mfma_f32_16x16x32_bf16 v[78:81], v[174:177], v[146:149], v[78:81]
	ds_read_b128 v[206:209], v240 offset:7168
	v_mfma_f32_16x16x32_bf16 v[94:97], v[174:177], v[150:153], v[94:97]
	global_load_lds_dwordx4 v226, s[54:55] offset:3072
	v_mfma_f32_16x16x32_bf16 v[90:93], v[170:173], v[150:153], v[90:93]
	v_mfma_f32_16x16x32_bf16 v[86:89], v[166:169], v[150:153], v[86:89]
	v_mfma_f32_16x16x32_bf16 v[82:85], v[162:165], v[150:153], v[82:85]
	v_mfma_f32_16x16x32_bf16 v[98:101], v[162:165], v[154:157], v[98:101]
	s_add_i32 m0, s60, s63
	v_mfma_f32_16x16x32_bf16 v[102:105], v[166:169], v[154:157], v[102:105]
	global_load_lds_dwordx4 v230, s[56:57]
	v_mfma_f32_16x16x32_bf16 v[106:109], v[170:173], v[154:157], v[106:109]
	v_mfma_f32_16x16x32_bf16 v[110:113], v[174:177], v[154:157], v[110:113]
	v_mfma_f32_16x16x32_bf16 v[126:129], v[174:177], v[158:161], v[126:129]
	v_mfma_f32_16x16x32_bf16 v[122:125], v[170:173], v[158:161], v[122:125]
	v_mfma_f32_16x16x32_bf16 v[118:121], v[166:169], v[158:161], v[118:121]
	global_load_lds_dwordx4 v231, s[56:57] offset:1024
	v_mfma_f32_16x16x32_bf16 v[114:117], v[162:165], v[158:161], v[114:117]
	s_setprio 0
	s_add_i32 s60, s60, 0x6000
	s_cmp_eq_u32 s60, 0x12000
	s_cselect_b32 s60, 0, s60
	s_add_u32 s54, s54, s72
	s_addc_u32 s55, s55, 0
	s_add_u32 s56, s56, s73
	s_addc_u32 s57, s57, 0
	s_add_i32 s61, s61, 0x6000
	s_cmp_eq_u32 s61, 0x12000
	s_cselect_b32 s61, 0, s61
	s_waitcnt lgkmcnt(0)
	v_add_u32_e32 v240, s61, v238
	v_add_u32_e32 v241, s61, v239
	s_setprio 1
	v_mfma_f32_16x16x32_bf16 v[2:5], v[210:213], v[178:181], v[2:5]
	v_mfma_f32_16x16x32_bf16 v[6:9], v[214:217], v[178:181], v[6:9]
	v_mfma_f32_16x16x32_bf16 v[10:13], v[218:221], v[178:181], v[10:13]
	v_mfma_f32_16x16x32_bf16 v[14:17], v[222:225], v[178:181], v[14:17]
	s_waitcnt vmcnt(6)
	s_barrier
	v_mfma_f32_16x16x32_bf16 v[30:33], v[222:225], v[182:185], v[30:33]
	s_add_i32 m0, s60, s62
	v_mfma_f32_16x16x32_bf16 v[26:29], v[218:221], v[182:185], v[26:29]
	global_load_lds_dwordx4 v226, s[54:55]
	v_mfma_f32_16x16x32_bf16 v[22:25], v[214:217], v[182:185], v[22:25]
	v_mfma_f32_16x16x32_bf16 v[18:21], v[210:213], v[182:185], v[18:21]
	v_mfma_f32_16x16x32_bf16 v[34:37], v[210:213], v[186:189], v[34:37]
	ds_read_b128 v[162:165], v241 offset:0
	v_mfma_f32_16x16x32_bf16 v[38:41], v[214:217], v[186:189], v[38:41]
	ds_read_b128 v[166:169], v241 offset:256
	v_mfma_f32_16x16x32_bf16 v[42:45], v[218:221], v[186:189], v[42:45]
	ds_read_b128 v[170:173], v241 offset:2048
	global_load_lds_dwordx4 v226, s[54:55] offset:1024
	v_mfma_f32_16x16x32_bf16 v[46:49], v[222:225], v[186:189], v[46:49]
	ds_read_b128 v[174:177], v241 offset:2304
	v_mfma_f32_16x16x32_bf16 v[62:65], v[222:225], v[190:193], v[62:65]
	ds_read_b128 v[130:133], v240 offset:0
	v_mfma_f32_16x16x32_bf16 v[58:61], v[218:221], v[190:193], v[58:61]
	ds_read_b128 v[134:137], v240 offset:1024
	v_mfma_f32_16x16x32_bf16 v[54:57], v[214:217], v[190:193], v[54:57]
	ds_read_b128 v[138:141], v240 offset:2048
	v_mfma_f32_16x16x32_bf16 v[50:53], v[210:213], v[190:193], v[50:53]
	ds_read_b128 v[142:145], v240 offset:3072
	global_load_lds_dwordx4 v226, s[54:55] offset:2048
	v_mfma_f32_16x16x32_bf16 v[66:69], v[210:213], v[194:197], v[66:69]
	ds_read_b128 v[146:149], v240 offset:4096
	v_mfma_f32_16x16x32_bf16 v[70:73], v[214:217], v[194:197], v[70:73]
	ds_read_b128 v[150:153], v240 offset:5120
	v_mfma_f32_16x16x32_bf16 v[74:77], v[218:221], v[194:197], v[74:77]
	ds_read_b128 v[154:157], v240 offset:6144
	v_mfma_f32_16x16x32_bf16 v[78:81], v[222:225], v[194:197], v[78:81]
	ds_read_b128 v[158:161], v240 offset:7168
	v_mfma_f32_16x16x32_bf16 v[94:97], v[222:225], v[198:201], v[94:97]
	global_load_lds_dwordx4 v226, s[54:55] offset:3072
	v_mfma_f32_16x16x32_bf16 v[90:93], v[218:221], v[198:201], v[90:93]
	v_mfma_f32_16x16x32_bf16 v[86:89], v[214:217], v[198:201], v[86:89]
	v_mfma_f32_16x16x32_bf16 v[82:85], v[210:213], v[198:201], v[82:85]
	v_mfma_f32_16x16x32_bf16 v[98:101], v[210:213], v[202:205], v[98:101]
	s_add_i32 m0, s60, s63
	v_mfma_f32_16x16x32_bf16 v[102:105], v[214:217], v[202:205], v[102:105]
	global_load_lds_dwordx4 v230, s[56:57]
	v_mfma_f32_16x16x32_bf16 v[106:109], v[218:221], v[202:205], v[106:109]
	v_mfma_f32_16x16x32_bf16 v[110:113], v[222:225], v[202:205], v[110:113]
	v_mfma_f32_16x16x32_bf16 v[126:129], v[222:225], v[206:209], v[126:129]
	v_mfma_f32_16x16x32_bf16 v[122:125], v[218:221], v[206:209], v[122:125]
	v_mfma_f32_16x16x32_bf16 v[118:121], v[214:217], v[206:209], v[118:121]
	global_load_lds_dwordx4 v231, s[56:57] offset:1024
	v_mfma_f32_16x16x32_bf16 v[114:117], v[210:213], v[206:209], v[114:117]
	s_setprio 0
	s_add_i32 s60, s60, 0x6000
	s_cmp_eq_u32 s60, 0x12000
	s_cselect_b32 s60, 0, s60
	s_add_u32 s54, s54, s72
	s_addc_u32 s55, s55, 0
	s_add_u32 s56, s56, s73
	s_addc_u32 s57, s57, 0
	s_add_i32 s61, s61, 0x6000
	s_cmp_eq_u32 s61, 0x12000
	s_cselect_b32 s61, 0, s61
	s_branch .Lpj_epi

.Lpj_tail_last:
	s_waitcnt lgkmcnt(0)
	v_add_u32_e32 v240, s61, v238
	v_add_u32_e32 v241, s61, v239
	s_setprio 1
	v_mfma_f32_16x16x32_bf16 v[2:5], v[162:165], v[130:133], v[2:5]
	v_mfma_f32_16x16x32_bf16 v[6:9], v[166:169], v[130:133], v[6:9]
	v_mfma_f32_16x16x32_bf16 v[10:13], v[170:173], v[130:133], v[10:13]
	v_mfma_f32_16x16x32_bf16 v[14:17], v[174:177], v[130:133], v[14:17]
	s_waitcnt vmcnt(6)
	s_barrier
	v_mfma_f32_16x16x32_bf16 v[30:33], v[174:177], v[134:137], v[30:33]
	s_add_i32 m0, s60, s62
	v_mfma_f32_16x16x32_bf16 v[26:29], v[170:173], v[134:137], v[26:29]
	global_load_lds_dwordx4 v226, s[54:55]
	v_mfma_f32_16x16x32_bf16 v[22:25], v[166:169], v[134:137], v[22:25]
	v_mfma_f32_16x16x32_bf16 v[18:21], v[162:165], v[134:137], v[18:21]
	v_mfma_f32_16x16x32_bf16 v[34:37], v[162:165], v[138:141], v[34:37]
	ds_read_b128 v[210:213], v241 offset:0
	v_mfma_f32_16x16x32_bf16 v[38:41], v[166:169], v[138:141], v[38:41]
	ds_read_b128 v[214:217], v241 offset:256
	v_mfma_f32_16x16x32_bf16 v[42:45], v[170:173], v[138:141], v[42:45]
	ds_read_b128 v[218:221], v241 offset:2048
	global_load_lds_dwordx4 v226, s[54:55] offset:1024
	v_mfma_f32_16x16x32_bf16 v[46:49], v[174:177], v[138:141], v[46:49]
	ds_read_b128 v[222:225], v241 offset:2304
	v_mfma_f32_16x16x32_bf16 v[62:65], v[174:177], v[142:145], v[62:65]
	ds_read_b128 v[178:181], v240 offset:0
	v_mfma_f32_16x16x32_bf16 v[58:61], v[170:173], v[142:145], v[58:61]
	ds_read_b128 v[182:185], v240 offset:1024
	v_mfma_f32_16x16x32_bf16 v[54:57], v[166:169], v[142:145], v[54:57]
	ds_read_b128 v[186:189], v240 offset:2048
	v_mfma_f32_16x16x32_bf16 v[50:53], v[162:165], v[142:145], v[50:53]
	ds_read_b128 v[190:193], v240 offset:3072
	global_load_lds_dwordx4 v226, s[54:55] offset:2048
	v_mfma_f32_16x16x32_bf16 v[66:69], v[162:165], v[146:149], v[66:69]
	ds_read_b128 v[194:197], v240 offset:4096
	v_mfma_f32_16x16x32_bf16 v[70:73], v[166:169], v[146:149], v[70:73]
	ds_read_b128 v[198:201], v240 offset:5120
	v_mfma_f32_16x16x32_bf16 v[74:77], v[170:173], v[146:149], v[74:77]
	ds_read_b128 v[202:205], v240 offset:6144
	v_mfma_f32_16x16x32_bf16 v[78:81], v[174:177], v[146:149], v[78:81]
	ds_read_b128 v[206:209], v240 offset:7168
	v_mfma_f32_16x16x32_bf16 v[94:97], v[174:177], v[150:153], v[94:97]
	global_load_lds_dwordx4 v226, s[54:55] offset:3072
	v_mfma_f32_16x16x32_bf16 v[90:93], v[170:173], v[150:153], v[90:93]
	v_mfma_f32_16x16x32_bf16 v[86:89], v[166:169], v[150:153], v[86:89]
	v_mfma_f32_16x16x32_bf16 v[82:85], v[162:165], v[150:153], v[82:85]
	v_mfma_f32_16x16x32_bf16 v[98:101], v[162:165], v[154:157], v[98:101]
	s_add_i32 m0, s60, s63
	v_mfma_f32_16x16x32_bf16 v[102:105], v[166:169], v[154:157], v[102:105]
	global_load_lds_dwordx4 v230, s[56:57]
	v_mfma_f32_16x16x32_bf16 v[106:109], v[170:173], v[154:157], v[106:109]
	v_mfma_f32_16x16x32_bf16 v[110:113], v[174:177], v[154:157], v[110:113]
	v_mfma_f32_16x16x32_bf16 v[126:129], v[174:177], v[158:161], v[126:129]
	v_mfma_f32_16x16x32_bf16 v[122:125], v[170:173], v[158:161], v[122:125]
	v_mfma_f32_16x16x32_bf16 v[118:121], v[166:169], v[158:161], v[118:121]
	global_load_lds_dwordx4 v231, s[56:57] offset:1024
	v_mfma_f32_16x16x32_bf16 v[114:117], v[162:165], v[158:161], v[114:117]
	s_setprio 0
	s_add_i32 s60, s60, 0x6000
	s_cmp_eq_u32 s60, 0x12000
	s_cselect_b32 s60, 0, s60
	s_add_u32 s54, s54, s72
	s_addc_u32 s55, s55, 0
	s_add_u32 s56, s56, s73
	s_addc_u32 s57, s57, 0
	s_add_i32 s61, s61, 0x6000
	s_cmp_eq_u32 s61, 0x12000
	s_cselect_b32 s61, 0, s61
	s_waitcnt lgkmcnt(0)
	v_add_u32_e32 v240, s61, v238
	v_add_u32_e32 v241, s61, v239
	s_setprio 1
	v_mfma_f32_16x16x32_bf16 v[2:5], v[210:213], v[178:181], v[2:5]
	v_mfma_f32_16x16x32_bf16 v[6:9], v[214:217], v[178:181], v[6:9]
	v_mfma_f32_16x16x32_bf16 v[10:13], v[218:221], v[178:181], v[10:13]
	v_mfma_f32_16x16x32_bf16 v[14:17], v[222:225], v[178:181], v[14:17]
	s_waitcnt vmcnt(6)
	s_barrier
	v_mfma_f32_16x16x32_bf16 v[30:33], v[222:225], v[182:185], v[30:33]
	v_mfma_f32_16x16x32_bf16 v[26:29], v[218:221], v[182:185], v[26:29]
	v_mfma_f32_16x16x32_bf16 v[22:25], v[214:217], v[182:185], v[22:25]
	v_mfma_f32_16x16x32_bf16 v[18:21], v[210:213], v[182:185], v[18:21]
	v_mfma_f32_16x16x32_bf16 v[34:37], v[210:213], v[186:189], v[34:37]
	ds_read_b128 v[162:165], v241 offset:0
	v_mfma_f32_16x16x32_bf16 v[38:41], v[214:217], v[186:189], v[38:41]
	ds_read_b128 v[166:169], v241 offset:256
	v_mfma_f32_16x16x32_bf16 v[42:45], v[218:221], v[186:189], v[42:45]
	ds_read_b128 v[170:173], v241 offset:2048
	v_mfma_f32_16x16x32_bf16 v[46:49], v[222:225], v[186:189], v[46:49]
	ds_read_b128 v[174:177], v241 offset:2304
	v_mfma_f32_16x16x32_bf16 v[62:65], v[222:225], v[190:193], v[62:65]
	ds_read_b128 v[130:133], v240 offset:0
	v_mfma_f32_16x16x32_bf16 v[58:61], v[218:221], v[190:193], v[58:61]
	ds_read_b128 v[134:137], v240 offset:1024
	v_mfma_f32_16x16x32_bf16 v[54:57], v[214:217], v[190:193], v[54:57]
	ds_read_b128 v[138:141], v240 offset:2048
	v_mfma_f32_16x16x32_bf16 v[50:53], v[210:213], v[190:193], v[50:53]
	ds_read_b128 v[142:145], v240 offset:3072
	v_mfma_f32_16x16x32_bf16 v[66:69], v[210:213], v[194:197], v[66:69]
	ds_read_b128 v[146:149], v240 offset:4096
	v_mfma_f32_16x16x32_bf16 v[70:73], v[214:217], v[194:197], v[70:73]
	ds_read_b128 v[150:153], v240 offset:5120
	v_mfma_f32_16x16x32_bf16 v[74:77], v[218:221], v[194:197], v[74:77]
	ds_read_b128 v[154:157], v240 offset:6144
	v_mfma_f32_16x16x32_bf16 v[78:81], v[222:225], v[194:197], v[78:81]
	ds_read_b128 v[158:161], v240 offset:7168
	v_mfma_f32_16x16x32_bf16 v[94:97], v[222:225], v[198:201], v[94:97]
	v_mfma_f32_16x16x32_bf16 v[90:93], v[218:221], v[198:201], v[90:93]
	v_mfma_f32_16x16x32_bf16 v[86:89], v[214:217], v[198:201], v[86:89]
	v_mfma_f32_16x16x32_bf16 v[82:85], v[210:213], v[198:201], v[82:85]
	v_mfma_f32_16x16x32_bf16 v[98:101], v[210:213], v[202:205], v[98:101]
	v_mfma_f32_16x16x32_bf16 v[102:105], v[214:217], v[202:205], v[102:105]
	v_mfma_f32_16x16x32_bf16 v[106:109], v[218:221], v[202:205], v[106:109]
	v_mfma_f32_16x16x32_bf16 v[110:113], v[222:225], v[202:205], v[110:113]
	v_mfma_f32_16x16x32_bf16 v[126:129], v[222:225], v[206:209], v[126:129]
	v_mfma_f32_16x16x32_bf16 v[122:125], v[218:221], v[206:209], v[122:125]
	v_mfma_f32_16x16x32_bf16 v[118:121], v[214:217], v[206:209], v[118:121]
	v_mfma_f32_16x16x32_bf16 v[114:117], v[210:213], v[206:209], v[114:117]
	s_setprio 0
	s_add_i32 s61, s61, 0x6000
	s_cmp_eq_u32 s61, 0x12000
	s_cselect_b32 s61, 0, s61
	s_waitcnt lgkmcnt(0)
	v_add_u32_e32 v240, s61, v238
	v_add_u32_e32 v241, s61, v239
	s_setprio 1
	v_mfma_f32_16x16x32_bf16 v[2:5], v[162:165], v[130:133], v[2:5]
	v_mfma_f32_16x16x32_bf16 v[6:9], v[166:169], v[130:133], v[6:9]
	v_mfma_f32_16x16x32_bf16 v[10:13], v[170:173], v[130:133], v[10:13]
	v_mfma_f32_16x16x32_bf16 v[14:17], v[174:177], v[130:133], v[14:17]
	s_waitcnt vmcnt(0)
	s_barrier
	v_mfma_f32_16x16x32_bf16 v[30:33], v[174:177], v[134:137], v[30:33]
	v_mfma_f32_16x16x32_bf16 v[26:29], v[170:173], v[134:137], v[26:29]
	v_mfma_f32_16x16x32_bf16 v[22:25], v[166:169], v[134:137], v[22:25]
	v_mfma_f32_16x16x32_bf16 v[18:21], v[162:165], v[134:137], v[18:21]
	v_mfma_f32_16x16x32_bf16 v[34:37], v[162:165], v[138:141], v[34:37]
	ds_read_b128 v[210:213], v241 offset:0
	v_mfma_f32_16x16x32_bf16 v[38:41], v[166:169], v[138:141], v[38:41]
	ds_read_b128 v[214:217], v241 offset:256
	v_mfma_f32_16x16x32_bf16 v[42:45], v[170:173], v[138:141], v[42:45]
	ds_read_b128 v[218:221], v241 offset:2048
	v_mfma_f32_16x16x32_bf16 v[46:49], v[174:177], v[138:141], v[46:49]
	ds_read_b128 v[222:225], v241 offset:2304
	v_mfma_f32_16x16x32_bf16 v[62:65], v[174:177], v[142:145], v[62:65]
	ds_read_b128 v[178:181], v240 offset:0
	v_mfma_f32_16x16x32_bf16 v[58:61], v[170:173], v[142:145], v[58:61]
	ds_read_b128 v[182:185], v240 offset:1024
	v_mfma_f32_16x16x32_bf16 v[54:57], v[166:169], v[142:145], v[54:57]
	ds_read_b128 v[186:189], v240 offset:2048
	v_mfma_f32_16x16x32_bf16 v[50:53], v[162:165], v[142:145], v[50:53]
	ds_read_b128 v[190:193], v240 offset:3072
	v_mfma_f32_16x16x32_bf16 v[66:69], v[162:165], v[146:149], v[66:69]
	ds_read_b128 v[194:197], v240 offset:4096
	v_mfma_f32_16x16x32_bf16 v[70:73], v[166:169], v[146:149], v[70:73]
	ds_read_b128 v[198:201], v240 offset:5120
	v_mfma_f32_16x16x32_bf16 v[74:77], v[170:173], v[146:149], v[74:77]
	ds_read_b128 v[202:205], v240 offset:6144
	v_mfma_f32_16x16x32_bf16 v[78:81], v[174:177], v[146:149], v[78:81]
	ds_read_b128 v[206:209], v240 offset:7168
	v_mfma_f32_16x16x32_bf16 v[94:97], v[174:177], v[150:153], v[94:97]
	v_mfma_f32_16x16x32_bf16 v[90:93], v[170:173], v[150:153], v[90:93]
	v_mfma_f32_16x16x32_bf16 v[86:89], v[166:169], v[150:153], v[86:89]
	v_mfma_f32_16x16x32_bf16 v[82:85], v[162:165], v[150:153], v[82:85]
	v_mfma_f32_16x16x32_bf16 v[98:101], v[162:165], v[154:157], v[98:101]
	v_mfma_f32_16x16x32_bf16 v[102:105], v[166:169], v[154:157], v[102:105]
	v_mfma_f32_16x16x32_bf16 v[106:109], v[170:173], v[154:157], v[106:109]
	v_mfma_f32_16x16x32_bf16 v[110:113], v[174:177], v[154:157], v[110:113]
	v_mfma_f32_16x16x32_bf16 v[126:129], v[174:177], v[158:161], v[126:129]
	v_mfma_f32_16x16x32_bf16 v[122:125], v[170:173], v[158:161], v[122:125]
	v_mfma_f32_16x16x32_bf16 v[118:121], v[166:169], v[158:161], v[118:121]
	v_mfma_f32_16x16x32_bf16 v[114:117], v[162:165], v[158:161], v[114:117]
	s_setprio 0
	s_add_i32 s61, s61, 0x6000
	s_cmp_eq_u32 s61, 0x12000
	s_cselect_b32 s61, 0, s61
	s_waitcnt lgkmcnt(0)
	s_setprio 1
	v_mfma_f32_16x16x32_bf16 v[2:5], v[210:213], v[178:181], v[2:5]
	v_mfma_f32_16x16x32_bf16 v[6:9], v[214:217], v[178:181], v[6:9]
	v_mfma_f32_16x16x32_bf16 v[10:13], v[218:221], v[178:181], v[10:13]
	v_mfma_f32_16x16x32_bf16 v[14:17], v[222:225], v[178:181], v[14:17]
	s_barrier
	v_mfma_f32_16x16x32_bf16 v[30:33], v[222:225], v[182:185], v[30:33]
	v_mfma_f32_16x16x32_bf16 v[26:29], v[218:221], v[182:185], v[26:29]
	v_mfma_f32_16x16x32_bf16 v[22:25], v[214:217], v[182:185], v[22:25]
	v_mfma_f32_16x16x32_bf16 v[18:21], v[210:213], v[182:185], v[18:21]
	v_mfma_f32_16x16x32_bf16 v[34:37], v[210:213], v[186:189], v[34:37]
	v_mfma_f32_16x16x32_bf16 v[38:41], v[214:217], v[186:189], v[38:41]
	v_mfma_f32_16x16x32_bf16 v[42:45], v[218:221], v[186:189], v[42:45]
	v_mfma_f32_16x16x32_bf16 v[46:49], v[222:225], v[186:189], v[46:49]
	v_mfma_f32_16x16x32_bf16 v[62:65], v[222:225], v[190:193], v[62:65]
	v_mfma_f32_16x16x32_bf16 v[58:61], v[218:221], v[190:193], v[58:61]
	v_mfma_f32_16x16x32_bf16 v[54:57], v[214:217], v[190:193], v[54:57]
	v_mfma_f32_16x16x32_bf16 v[50:53], v[210:213], v[190:193], v[50:53]
	v_mfma_f32_16x16x32_bf16 v[66:69], v[210:213], v[194:197], v[66:69]
	v_mfma_f32_16x16x32_bf16 v[70:73], v[214:217], v[194:197], v[70:73]
	v_mfma_f32_16x16x32_bf16 v[74:77], v[218:221], v[194:197], v[74:77]
	v_mfma_f32_16x16x32_bf16 v[78:81], v[222:225], v[194:197], v[78:81]
	v_mfma_f32_16x16x32_bf16 v[94:97], v[222:225], v[198:201], v[94:97]
	v_mfma_f32_16x16x32_bf16 v[90:93], v[218:221], v[198:201], v[90:93]
	v_mfma_f32_16x16x32_bf16 v[86:89], v[214:217], v[198:201], v[86:89]
	v_mfma_f32_16x16x32_bf16 v[82:85], v[210:213], v[198:201], v[82:85]
	v_mfma_f32_16x16x32_bf16 v[98:101], v[210:213], v[202:205], v[98:101]
	v_mfma_f32_16x16x32_bf16 v[102:105], v[214:217], v[202:205], v[102:105]
	v_mfma_f32_16x16x32_bf16 v[106:109], v[218:221], v[202:205], v[106:109]
	v_mfma_f32_16x16x32_bf16 v[110:113], v[222:225], v[202:205], v[110:113]
	v_mfma_f32_16x16x32_bf16 v[126:129], v[222:225], v[206:209], v[126:129]
	v_mfma_f32_16x16x32_bf16 v[122:125], v[218:221], v[206:209], v[122:125]
	v_mfma_f32_16x16x32_bf16 v[118:121], v[214:217], v[206:209], v[118:121]
	v_mfma_f32_16x16x32_bf16 v[114:117], v[210:213], v[206:209], v[114:117]
	s_setprio 0
